# GEMM DMA pieces split 5+3 over the post-barrier segment and the next k-slab
# speedup vs baseline: 1.1346x; 1.0052x over previous
.LBB0_22:
	s_add_i32 s2, s7, s8
	s_cmpk_gt_i32 s2, 0x1ff
	s_mov_b64 s[0:1], -1
	s_cbranch_scc1 .LBB0_21
	s_ashr_i32 s0, s2, 31
	s_lshr_b32 s0, s0, 27
	s_add_i32 s0, s2, s0
	s_and_b32 s1, s0, 0xffffffe0
	s_sub_i32 s1, s2, s1
	s_ashr_i32 s2, s1, 31
	s_lshr_b32 s2, s2, 29
	s_add_i32 s2, s1, s2
	s_and_b32 s3, s2, 0xfffff8
	s_sub_i32 s1, s1, s3
	s_lshl_b32 s0, s0, 6
	s_and_b32 s0, s0, 0xfffff800
	s_lshl_b32 s1, s1, 8
	s_add_i32 s0, s1, s0
	s_ashr_i32 s1, s0, 31
	s_lshl_b64 s[4:5], s[0:1], 12
	s_lshl_b32 s1, s2, 5
	s_and_b32 s2, s1, 0xffffff00
	s_ashr_i32 s3, s2, 31
	s_lshl_b64 s[10:11], s[2:3], 12
	s_add_u32 s12, s64, s4
	v_mov_b32_e32 v0, v138
	s_addc_u32 s13, s65, s5
	s_barrier
	v_readlane_b32 s14, v251, 22
	v_lshl_add_u64 v[2:3], v[0:1], 1, s[12:13]
	v_add_u32_e32 v0, 32, v139
	v_readlane_b32 s15, v251, 23
	v_readfirstlane_b32 s1, v0
	s_mov_b32 m0, s1
	v_mov_b32_e32 v0, v140
	global_load_lds_dwordx4 v[2:3], off
	s_add_u32 s14, s14, s10
	v_lshl_add_u64 v[2:3], v[0:1], 1, s[12:13]
	v_add_u32_e32 v0, 32, v141
	s_addc_u32 s15, s15, s11
	v_readfirstlane_b32 s1, v0
	s_mov_b32 m0, s1
	v_mov_b32_e32 v0, v142
	global_load_lds_dwordx4 v[2:3], off
	v_readlane_b32 s3, v254, 3
	v_lshl_add_u64 v[2:3], v[0:1], 1, s[12:13]
	v_add_u32_e32 v0, 32, v143
	s_mov_b32 s27, s51
	v_readfirstlane_b32 s1, v0
	s_mov_b32 m0, s1
	v_mov_b32_e32 v0, v144
	global_load_lds_dwordx4 v[2:3], off
	s_nop 0
	v_lshl_add_u64 v[2:3], v[0:1], 1, s[12:13]
	v_add_u32_e32 v0, 32, v145
	s_nop 0
	v_readfirstlane_b32 s1, v0
	s_mov_b32 m0, s1
	v_mov_b32_e32 v0, v138
	global_load_lds_dwordx4 v[2:3], off
	s_nop 0
	v_lshl_add_u64 v[2:3], v[0:1], 1, s[14:15]
	v_add_u32_e32 v0, s3, v139
	s_nop 0
	v_readfirstlane_b32 s1, v0
	s_mov_b32 m0, s1
	v_mov_b32_e32 v0, v140
	global_load_lds_dwordx4 v[2:3], off
	s_nop 0
	v_lshl_add_u64 v[2:3], v[0:1], 1, s[14:15]
	v_add_u32_e32 v0, s3, v141
	s_nop 0
	v_readfirstlane_b32 s1, v0
	s_mov_b32 m0, s1
	v_mov_b32_e32 v0, v142
	global_load_lds_dwordx4 v[2:3], off
	s_nop 0
	v_lshl_add_u64 v[2:3], v[0:1], 1, s[14:15]
	v_add_u32_e32 v0, s3, v143
	s_nop 0
	v_readfirstlane_b32 s1, v0
	s_mov_b32 m0, s1
	v_mov_b32_e32 v0, v144
	global_load_lds_dwordx4 v[2:3], off
	s_nop 0
	v_lshl_add_u64 v[2:3], v[0:1], 1, s[14:15]
	v_add_u32_e32 v0, s3, v145
	v_readlane_b32 s3, v253, 26
	v_readfirstlane_b32 s1, v0
	s_mov_b32 m0, s1
	v_readlane_b32 s1, v253, 25
	global_load_lds_dwordx4 v[2:3], off
	s_add_u32 s1, s1, s4
	s_waitcnt vmcnt(0)
	s_addc_u32 s3, s3, s5
	v_readlane_b32 s4, v253, 27
	s_add_u32 s9, s4, s10
	v_readlane_b32 s4, v253, 28
	v_mov_b32_e32 v2, 0
	s_addc_u32 s10, s4, s11
	s_mov_b64 s[4:5], 0
	s_mov_b32 s11, 0
	v_mov_b32_e32 v3, v2
	v_mov_b32_e32 v4, v2
	v_mov_b32_e32 v5, v2
	v_mov_b32_e32 v6, v2
	v_mov_b32_e32 v7, v2
	v_mov_b32_e32 v8, v2
	v_mov_b32_e32 v9, v2
	v_mov_b32_e32 v10, v2
	v_mov_b32_e32 v11, v2
	v_mov_b32_e32 v12, v2
	v_mov_b32_e32 v13, v2
	s_waitcnt vmcnt(0)
	v_mov_b32_e32 v14, v2
	v_mov_b32_e32 v15, v2
	v_mov_b32_e32 v16, v2
	v_mov_b32_e32 v17, v2
	v_mov_b32_e32 v18, v2
	v_mov_b32_e32 v19, v2
	v_mov_b32_e32 v20, v2
	v_mov_b32_e32 v21, v2
	v_mov_b32_e32 v22, v2
	v_mov_b32_e32 v23, v2
	v_mov_b32_e32 v24, v2
	v_mov_b32_e32 v25, v2
	v_mov_b32_e32 v26, v2
	v_mov_b32_e32 v27, v2
	v_mov_b32_e32 v28, v2
	v_mov_b32_e32 v29, v2
	v_mov_b32_e32 v30, v2
	v_mov_b32_e32 v31, v2
	v_mov_b32_e32 v32, v2
	v_mov_b32_e32 v33, v2
	v_mov_b32_e32 v34, v2
	v_mov_b32_e32 v35, v2
	v_mov_b32_e32 v36, v2
	v_mov_b32_e32 v37, v2
	v_mov_b32_e32 v38, v2
	v_mov_b32_e32 v39, v2
	v_mov_b32_e32 v40, v2
	v_mov_b32_e32 v41, v2
	v_mov_b32_e32 v42, v2
	v_mov_b32_e32 v43, v2
	v_mov_b32_e32 v44, v2
	v_mov_b32_e32 v45, v2
	v_mov_b32_e32 v46, v2
	v_mov_b32_e32 v47, v2
	v_mov_b32_e32 v48, v2
	v_mov_b32_e32 v49, v2
	v_mov_b32_e32 v50, v2
	v_mov_b32_e32 v51, v2
	v_mov_b32_e32 v52, v2
	v_mov_b32_e32 v53, v2
	v_mov_b32_e32 v54, v2
	v_mov_b32_e32 v55, v2
	v_mov_b32_e32 v56, v2
	v_mov_b32_e32 v57, v2
	v_mov_b32_e32 v58, v2
	v_mov_b32_e32 v59, v2
	v_mov_b32_e32 v60, v2
	v_mov_b32_e32 v61, v2
	v_mov_b32_e32 v62, v2
	v_mov_b32_e32 v63, v2
	v_mov_b32_e32 v64, v2
	v_mov_b32_e32 v65, v2
	v_mov_b32_e32 v66, v2
	v_mov_b32_e32 v67, v2
	v_mov_b32_e32 v68, v2
	v_mov_b32_e32 v69, v2
	v_mov_b32_e32 v70, v2
	v_mov_b32_e32 v71, v2
	v_mov_b32_e32 v72, v2
	v_mov_b32_e32 v73, v2
	v_mov_b32_e32 v74, v2
	v_mov_b32_e32 v75, v2
	v_mov_b32_e32 v76, v2
	v_mov_b32_e32 v77, v2
	v_mov_b32_e32 v78, v2
	v_mov_b32_e32 v79, v2
	v_mov_b32_e32 v80, v2
	v_mov_b32_e32 v81, v2
	v_mov_b32_e32 v82, v2
	v_mov_b32_e32 v83, v2
	v_mov_b32_e32 v84, v2
	v_mov_b32_e32 v85, v2
	v_mov_b32_e32 v86, v2
	v_mov_b32_e32 v87, v2
	v_mov_b32_e32 v88, v2
	v_mov_b32_e32 v89, v2
	v_mov_b32_e32 v90, v2
	v_mov_b32_e32 v91, v2
	v_mov_b32_e32 v92, v2
	v_mov_b32_e32 v93, v2
	v_mov_b32_e32 v94, v2
	v_mov_b32_e32 v95, v2
	v_mov_b32_e32 v96, v2
	v_mov_b32_e32 v97, v2
	v_mov_b32_e32 v98, v2
	v_mov_b32_e32 v99, v2
	v_mov_b32_e32 v100, v2
	v_mov_b32_e32 v101, v2
	v_mov_b32_e32 v102, v2
	v_mov_b32_e32 v103, v2
	v_mov_b32_e32 v104, v2
	v_mov_b32_e32 v105, v2
	v_mov_b32_e32 v106, v2
	v_mov_b32_e32 v107, v2
	v_mov_b32_e32 v108, v2
	v_mov_b32_e32 v109, v2
	v_mov_b32_e32 v110, v2
	v_mov_b32_e32 v111, v2
	v_mov_b32_e32 v112, v2
	v_mov_b32_e32 v113, v2
	v_mov_b32_e32 v114, v2
	v_mov_b32_e32 v115, v2
	v_mov_b32_e32 v116, v2
	v_mov_b32_e32 v117, v2
	v_mov_b32_e32 v118, v2
	v_mov_b32_e32 v119, v2
	v_mov_b32_e32 v120, v2
	v_mov_b32_e32 v121, v2
	v_mov_b32_e32 v122, v2
	v_mov_b32_e32 v123, v2
	v_mov_b32_e32 v124, v2
	v_mov_b32_e32 v125, v2
	v_mov_b32_e32 v126, v2
	v_mov_b32_e32 v127, v2
	v_mov_b32_e32 v128, v2
	v_mov_b32_e32 v129, v2
	s_waitcnt vmcnt(0) lgkmcnt(0)
	s_barrier
	v_lshlrev_b32_e32 v155, 1, v138
	v_readfirstlane_b32 s14, v139
	v_add_u32_e32 v177, v146, v148
	v_add_u32_e32 v207, v147, v148
	v_add_u32_e32 v204, v146, v152
	v_add_u32_e32 v208, v147, v152
	v_add_u32_e32 v205, v146, v153
	v_add_u32_e32 v209, v147, v153
	v_add_u32_e32 v206, v146, v154
	v_add_u32_e32 v210, v147, v154
	s_mov_b32 s11, 15
	s_add_u32 m0, s14, 0x8020
	s_add_u32 s12, s1, s4
	s_addc_u32 s13, s3, s5
	global_load_lds_dwordx4 v155, s[12:13]
	s_add_u32 m0, s14, 0xa020
	s_add_u32 s12, s12, 0x40000
	s_addc_u32 s13, s13, 0
	global_load_lds_dwordx4 v155, s[12:13]
	s_add_u32 m0, s14, 0xc020
	s_add_u32 s12, s12, 0x40000
	s_addc_u32 s13, s13, 0
	global_load_lds_dwordx4 v155, s[12:13]
	s_add_u32 m0, s14, 0xe020
	s_add_u32 s12, s12, 0x40000
	s_addc_u32 s13, s13, 0
	global_load_lds_dwordx4 v155, s[12:13]
	s_add_u32 m0, s14, 0x18020
	s_add_u32 s12, s9, s4
	s_addc_u32 s13, s10, s5
	global_load_lds_dwordx4 v155, s[12:13]
	ds_read_b128 v[130:133], v177 offset:0
	ds_read_b128 v[164:167], v207 offset:0
	ds_read_b128 v[168:171], v207 offset:4096
	ds_read_b128 v[134:137], v177 offset:4096
	ds_read_b128 v[156:159], v177 offset:8192
	ds_read_b128 v[160:163], v177 offset:12288
.Lg24_loop:
	s_waitcnt lgkmcnt(4)
	v_mfma_f32_32x32x16_bf16 v[114:129], v[130:133], v[164:167], v[114:129]
	ds_read_b128 v[172:175], v204 offset:0
	s_waitcnt lgkmcnt(4)
	v_mfma_f32_32x32x16_bf16 v[98:113], v[130:133], v[168:171], v[98:113]
	ds_read_b128 v[192:195], v208 offset:0
	s_add_u32 m0, s14, 0x1a020
	s_add_u32 s12, s12, 0x40000
	s_addc_u32 s13, s13, 0
	global_load_lds_dwordx4 v155, s[12:13]
	s_waitcnt lgkmcnt(4)
	v_mfma_f32_32x32x16_bf16 v[82:97], v[134:137], v[164:167], v[82:97]
	ds_read_b128 v[200:203], v208 offset:4096
	v_mfma_f32_32x32x16_bf16 v[66:81], v[134:137], v[168:171], v[66:81]
	ds_read_b128 v[180:183], v204 offset:4096
	s_add_u32 m0, s14, 0x1c020
	s_add_u32 s12, s12, 0x40000
	s_addc_u32 s13, s13, 0
	global_load_lds_dwordx4 v155, s[12:13]
	s_waitcnt lgkmcnt(5)
	v_mfma_f32_32x32x16_bf16 v[50:65], v[156:159], v[164:167], v[50:65]
	ds_read_b128 v[184:187], v204 offset:8192
	v_mfma_f32_32x32x16_bf16 v[34:49], v[156:159], v[168:171], v[34:49]
	ds_read_b128 v[188:191], v204 offset:12288
	s_add_u32 m0, s14, 0x1e020
	s_add_u32 s12, s12, 0x40000
	s_addc_u32 s13, s13, 0
	global_load_lds_dwordx4 v155, s[12:13]
	s_add_u32 s4, s4, 0x80
	s_addc_u32 s5, s5, 0
	s_waitcnt lgkmcnt(6)
	v_mfma_f32_32x32x16_bf16 v[18:33], v[160:163], v[164:167], v[18:33]
	v_mfma_f32_32x32x16_bf16 v[2:17], v[160:163], v[168:171], v[2:17]
	s_waitcnt lgkmcnt(4)
	v_mfma_f32_32x32x16_bf16 v[114:129], v[172:175], v[192:195], v[114:129]
	ds_read_b128 v[130:133], v205 offset:0
	s_waitcnt lgkmcnt(4)
	v_mfma_f32_32x32x16_bf16 v[98:113], v[172:175], v[200:203], v[98:113]
	ds_read_b128 v[164:167], v209 offset:0
	s_waitcnt lgkmcnt(4)
	v_mfma_f32_32x32x16_bf16 v[82:97], v[180:183], v[192:195], v[82:97]
	ds_read_b128 v[168:171], v209 offset:4096
	v_mfma_f32_32x32x16_bf16 v[66:81], v[180:183], v[200:203], v[66:81]
	ds_read_b128 v[134:137], v205 offset:4096
	s_waitcnt lgkmcnt(5)
	v_mfma_f32_32x32x16_bf16 v[50:65], v[184:187], v[192:195], v[50:65]
	ds_read_b128 v[156:159], v205 offset:8192
	v_mfma_f32_32x32x16_bf16 v[34:49], v[184:187], v[200:203], v[34:49]
	ds_read_b128 v[160:163], v205 offset:12288
	s_waitcnt lgkmcnt(6)
	v_mfma_f32_32x32x16_bf16 v[18:33], v[188:191], v[192:195], v[18:33]
	v_mfma_f32_32x32x16_bf16 v[2:17], v[188:191], v[200:203], v[2:17]
	s_waitcnt lgkmcnt(4)
	v_mfma_f32_32x32x16_bf16 v[114:129], v[130:133], v[164:167], v[114:129]
	ds_read_b128 v[172:175], v206 offset:0
	ds_read_b128 v[192:195], v210 offset:0
	s_waitcnt lgkmcnt(5)
	v_mfma_f32_32x32x16_bf16 v[98:113], v[130:133], v[168:171], v[98:113]
	ds_read_b128 v[200:203], v210 offset:4096
	ds_read_b128 v[180:183], v206 offset:4096
	s_waitcnt lgkmcnt(6)
	v_mfma_f32_32x32x16_bf16 v[82:97], v[134:137], v[164:167], v[82:97]
	ds_read_b128 v[184:187], v206 offset:8192
	ds_read_b128 v[188:191], v206 offset:12288
	v_mfma_f32_32x32x16_bf16 v[66:81], v[134:137], v[168:171], v[66:81]
	s_waitcnt lgkmcnt(7)
	v_mfma_f32_32x32x16_bf16 v[50:65], v[156:159], v[164:167], v[50:65]
	v_mfma_f32_32x32x16_bf16 v[34:49], v[156:159], v[168:171], v[34:49]
	s_waitcnt lgkmcnt(6)
	v_mfma_f32_32x32x16_bf16 v[18:33], v[160:163], v[164:167], v[18:33]
	v_mfma_f32_32x32x16_bf16 v[2:17], v[160:163], v[168:171], v[2:17]
	s_waitcnt vmcnt(0) lgkmcnt(0)
	s_barrier
	v_mfma_f32_32x32x16_bf16 v[114:129], v[172:175], v[192:195], v[114:129]
	ds_read_b128 v[130:133], v177 offset:32768
	s_add_u32 m0, s14, 0x20
	s_add_u32 s12, s1, s4
	s_addc_u32 s13, s3, s5
	global_load_lds_dwordx4 v155, s[12:13]
	v_mfma_f32_32x32x16_bf16 v[98:113], v[172:175], v[200:203], v[98:113]
	ds_read_b128 v[164:167], v207 offset:32768
	s_add_u32 m0, s14, 0x2020
	s_add_u32 s12, s12, 0x40000
	s_addc_u32 s13, s13, 0
	global_load_lds_dwordx4 v155, s[12:13]
	v_mfma_f32_32x32x16_bf16 v[82:97], v[180:183], v[192:195], v[82:97]
	ds_read_b128 v[168:171], v207 offset:36864
	s_add_u32 m0, s14, 0x4020
	s_add_u32 s12, s12, 0x40000
	s_addc_u32 s13, s13, 0
	global_load_lds_dwordx4 v155, s[12:13]
	v_mfma_f32_32x32x16_bf16 v[66:81], v[180:183], v[200:203], v[66:81]
	ds_read_b128 v[134:137], v177 offset:36864
	s_add_u32 m0, s14, 0x6020
	s_add_u32 s12, s12, 0x40000
	s_addc_u32 s13, s13, 0
	global_load_lds_dwordx4 v155, s[12:13]
	v_mfma_f32_32x32x16_bf16 v[50:65], v[184:187], v[192:195], v[50:65]
	ds_read_b128 v[156:159], v177 offset:40960
	s_add_u32 m0, s14, 0x10020
	s_add_u32 s12, s9, s4
	s_addc_u32 s13, s10, s5
	global_load_lds_dwordx4 v155, s[12:13]
	v_mfma_f32_32x32x16_bf16 v[34:49], v[184:187], v[200:203], v[34:49]
	ds_read_b128 v[160:163], v177 offset:45056
	v_mfma_f32_32x32x16_bf16 v[18:33], v[188:191], v[192:195], v[18:33]
	v_mfma_f32_32x32x16_bf16 v[2:17], v[188:191], v[200:203], v[2:17]
	s_waitcnt lgkmcnt(4)
	v_mfma_f32_32x32x16_bf16 v[114:129], v[130:133], v[164:167], v[114:129]
	ds_read_b128 v[172:175], v204 offset:32768
	s_waitcnt lgkmcnt(4)
	v_mfma_f32_32x32x16_bf16 v[98:113], v[130:133], v[168:171], v[98:113]
	ds_read_b128 v[192:195], v208 offset:32768
	s_add_u32 m0, s14, 0x12020
	s_add_u32 s12, s12, 0x40000
	s_addc_u32 s13, s13, 0
	global_load_lds_dwordx4 v155, s[12:13]
	s_waitcnt lgkmcnt(4)
	v_mfma_f32_32x32x16_bf16 v[82:97], v[134:137], v[164:167], v[82:97]
	ds_read_b128 v[200:203], v208 offset:36864
	v_mfma_f32_32x32x16_bf16 v[66:81], v[134:137], v[168:171], v[66:81]
	ds_read_b128 v[180:183], v204 offset:36864
	s_add_u32 m0, s14, 0x14020
	s_add_u32 s12, s12, 0x40000
	s_addc_u32 s13, s13, 0
	global_load_lds_dwordx4 v155, s[12:13]
	s_waitcnt lgkmcnt(5)
	v_mfma_f32_32x32x16_bf16 v[50:65], v[156:159], v[164:167], v[50:65]
	ds_read_b128 v[184:187], v204 offset:40960
	v_mfma_f32_32x32x16_bf16 v[34:49], v[156:159], v[168:171], v[34:49]
	ds_read_b128 v[188:191], v204 offset:45056
	s_add_u32 m0, s14, 0x16020
	s_add_u32 s12, s12, 0x40000
	s_addc_u32 s13, s13, 0
	global_load_lds_dwordx4 v155, s[12:13]
	s_add_u32 s4, s4, 0x80
	s_addc_u32 s5, s5, 0
	s_waitcnt lgkmcnt(6)
	v_mfma_f32_32x32x16_bf16 v[18:33], v[160:163], v[164:167], v[18:33]
	v_mfma_f32_32x32x16_bf16 v[2:17], v[160:163], v[168:171], v[2:17]
	s_waitcnt lgkmcnt(4)
	v_mfma_f32_32x32x16_bf16 v[114:129], v[172:175], v[192:195], v[114:129]
	ds_read_b128 v[130:133], v205 offset:32768
	s_waitcnt lgkmcnt(4)
	v_mfma_f32_32x32x16_bf16 v[98:113], v[172:175], v[200:203], v[98:113]
	ds_read_b128 v[164:167], v209 offset:32768
	s_waitcnt lgkmcnt(4)
	v_mfma_f32_32x32x16_bf16 v[82:97], v[180:183], v[192:195], v[82:97]
	ds_read_b128 v[168:171], v209 offset:36864
	v_mfma_f32_32x32x16_bf16 v[66:81], v[180:183], v[200:203], v[66:81]
	ds_read_b128 v[134:137], v205 offset:36864
	s_waitcnt lgkmcnt(5)
	v_mfma_f32_32x32x16_bf16 v[50:65], v[184:187], v[192:195], v[50:65]
	ds_read_b128 v[156:159], v205 offset:40960
	v_mfma_f32_32x32x16_bf16 v[34:49], v[184:187], v[200:203], v[34:49]
	ds_read_b128 v[160:163], v205 offset:45056
	s_waitcnt lgkmcnt(6)
	v_mfma_f32_32x32x16_bf16 v[18:33], v[188:191], v[192:195], v[18:33]
	v_mfma_f32_32x32x16_bf16 v[2:17], v[188:191], v[200:203], v[2:17]
	s_waitcnt lgkmcnt(4)
	v_mfma_f32_32x32x16_bf16 v[114:129], v[130:133], v[164:167], v[114:129]
	ds_read_b128 v[172:175], v206 offset:32768
	ds_read_b128 v[192:195], v210 offset:32768
	s_waitcnt lgkmcnt(5)
	v_mfma_f32_32x32x16_bf16 v[98:113], v[130:133], v[168:171], v[98:113]
	ds_read_b128 v[200:203], v210 offset:36864
	ds_read_b128 v[180:183], v206 offset:36864
	s_waitcnt lgkmcnt(6)
	v_mfma_f32_32x32x16_bf16 v[82:97], v[134:137], v[164:167], v[82:97]
	ds_read_b128 v[184:187], v206 offset:40960
	ds_read_b128 v[188:191], v206 offset:45056
	v_mfma_f32_32x32x16_bf16 v[66:81], v[134:137], v[168:171], v[66:81]
	s_waitcnt lgkmcnt(7)
	v_mfma_f32_32x32x16_bf16 v[50:65], v[156:159], v[164:167], v[50:65]
	v_mfma_f32_32x32x16_bf16 v[34:49], v[156:159], v[168:171], v[34:49]
	s_waitcnt lgkmcnt(6)
	v_mfma_f32_32x32x16_bf16 v[18:33], v[160:163], v[164:167], v[18:33]
	v_mfma_f32_32x32x16_bf16 v[2:17], v[160:163], v[168:171], v[2:17]
	s_waitcnt vmcnt(0) lgkmcnt(0)
	s_barrier
	v_mfma_f32_32x32x16_bf16 v[114:129], v[172:175], v[192:195], v[114:129]
	ds_read_b128 v[130:133], v177 offset:0
	s_add_u32 m0, s14, 0x8020
	s_add_u32 s12, s1, s4
	s_addc_u32 s13, s3, s5
	global_load_lds_dwordx4 v155, s[12:13]
	v_mfma_f32_32x32x16_bf16 v[98:113], v[172:175], v[200:203], v[98:113]
	ds_read_b128 v[164:167], v207 offset:0
	s_add_u32 m0, s14, 0xa020
	s_add_u32 s12, s12, 0x40000
	s_addc_u32 s13, s13, 0
	global_load_lds_dwordx4 v155, s[12:13]
	v_mfma_f32_32x32x16_bf16 v[82:97], v[180:183], v[192:195], v[82:97]
	ds_read_b128 v[168:171], v207 offset:4096
	s_add_u32 m0, s14, 0xc020
	s_add_u32 s12, s12, 0x40000
	s_addc_u32 s13, s13, 0
	global_load_lds_dwordx4 v155, s[12:13]
	v_mfma_f32_32x32x16_bf16 v[66:81], v[180:183], v[200:203], v[66:81]
	ds_read_b128 v[134:137], v177 offset:4096
	s_add_u32 m0, s14, 0xe020
	s_add_u32 s12, s12, 0x40000
	s_addc_u32 s13, s13, 0
	global_load_lds_dwordx4 v155, s[12:13]
	v_mfma_f32_32x32x16_bf16 v[50:65], v[184:187], v[192:195], v[50:65]
	ds_read_b128 v[156:159], v177 offset:8192
	s_add_u32 m0, s14, 0x18020
	s_add_u32 s12, s9, s4
	s_addc_u32 s13, s10, s5
	global_load_lds_dwordx4 v155, s[12:13]
	v_mfma_f32_32x32x16_bf16 v[34:49], v[184:187], v[200:203], v[34:49]
	ds_read_b128 v[160:163], v177 offset:12288
	v_mfma_f32_32x32x16_bf16 v[18:33], v[188:191], v[192:195], v[18:33]
	v_mfma_f32_32x32x16_bf16 v[2:17], v[188:191], v[200:203], v[2:17]
	s_sub_u32 s11, s11, 1
	s_cmp_lg_u32 s11, 0
	s_cbranch_scc1 .Lg24_loop
	s_waitcnt lgkmcnt(4)
	v_mfma_f32_32x32x16_bf16 v[114:129], v[130:133], v[164:167], v[114:129]
	ds_read_b128 v[172:175], v204 offset:0
	s_waitcnt lgkmcnt(4)
	v_mfma_f32_32x32x16_bf16 v[98:113], v[130:133], v[168:171], v[98:113]
	ds_read_b128 v[192:195], v208 offset:0
	s_add_u32 m0, s14, 0x1a020
	s_add_u32 s12, s12, 0x40000
	s_addc_u32 s13, s13, 0
	global_load_lds_dwordx4 v155, s[12:13]
	s_waitcnt lgkmcnt(4)
	v_mfma_f32_32x32x16_bf16 v[82:97], v[134:137], v[164:167], v[82:97]
	ds_read_b128 v[200:203], v208 offset:4096
	v_mfma_f32_32x32x16_bf16 v[66:81], v[134:137], v[168:171], v[66:81]
	ds_read_b128 v[180:183], v204 offset:4096
	s_add_u32 m0, s14, 0x1c020
	s_add_u32 s12, s12, 0x40000
	s_addc_u32 s13, s13, 0
	global_load_lds_dwordx4 v155, s[12:13]
	s_waitcnt lgkmcnt(5)
	v_mfma_f32_32x32x16_bf16 v[50:65], v[156:159], v[164:167], v[50:65]
	ds_read_b128 v[184:187], v204 offset:8192
	v_mfma_f32_32x32x16_bf16 v[34:49], v[156:159], v[168:171], v[34:49]
	ds_read_b128 v[188:191], v204 offset:12288
	s_add_u32 m0, s14, 0x1e020
	s_add_u32 s12, s12, 0x40000
	s_addc_u32 s13, s13, 0
	global_load_lds_dwordx4 v155, s[12:13]
	s_add_u32 s4, s4, 0x80
	s_addc_u32 s5, s5, 0
	s_waitcnt lgkmcnt(6)
	v_mfma_f32_32x32x16_bf16 v[18:33], v[160:163], v[164:167], v[18:33]
	v_mfma_f32_32x32x16_bf16 v[2:17], v[160:163], v[168:171], v[2:17]
	s_waitcnt lgkmcnt(4)
	v_mfma_f32_32x32x16_bf16 v[114:129], v[172:175], v[192:195], v[114:129]
	ds_read_b128 v[130:133], v205 offset:0
	s_waitcnt lgkmcnt(4)
	v_mfma_f32_32x32x16_bf16 v[98:113], v[172:175], v[200:203], v[98:113]
	ds_read_b128 v[164:167], v209 offset:0
	s_waitcnt lgkmcnt(4)
	v_mfma_f32_32x32x16_bf16 v[82:97], v[180:183], v[192:195], v[82:97]
	ds_read_b128 v[168:171], v209 offset:4096
	v_mfma_f32_32x32x16_bf16 v[66:81], v[180:183], v[200:203], v[66:81]
	ds_read_b128 v[134:137], v205 offset:4096
	s_waitcnt lgkmcnt(5)
	v_mfma_f32_32x32x16_bf16 v[50:65], v[184:187], v[192:195], v[50:65]
	ds_read_b128 v[156:159], v205 offset:8192
	v_mfma_f32_32x32x16_bf16 v[34:49], v[184:187], v[200:203], v[34:49]
	ds_read_b128 v[160:163], v205 offset:12288
	s_waitcnt lgkmcnt(6)
	v_mfma_f32_32x32x16_bf16 v[18:33], v[188:191], v[192:195], v[18:33]
	v_mfma_f32_32x32x16_bf16 v[2:17], v[188:191], v[200:203], v[2:17]
	s_waitcnt lgkmcnt(4)
	v_mfma_f32_32x32x16_bf16 v[114:129], v[130:133], v[164:167], v[114:129]
	ds_read_b128 v[172:175], v206 offset:0
	ds_read_b128 v[192:195], v210 offset:0
	s_waitcnt lgkmcnt(5)
	v_mfma_f32_32x32x16_bf16 v[98:113], v[130:133], v[168:171], v[98:113]
	ds_read_b128 v[200:203], v210 offset:4096
	ds_read_b128 v[180:183], v206 offset:4096
	s_waitcnt lgkmcnt(6)
	v_mfma_f32_32x32x16_bf16 v[82:97], v[134:137], v[164:167], v[82:97]
	ds_read_b128 v[184:187], v206 offset:8192
	ds_read_b128 v[188:191], v206 offset:12288
	v_mfma_f32_32x32x16_bf16 v[66:81], v[134:137], v[168:171], v[66:81]
	s_waitcnt lgkmcnt(7)
	v_mfma_f32_32x32x16_bf16 v[50:65], v[156:159], v[164:167], v[50:65]
	v_mfma_f32_32x32x16_bf16 v[34:49], v[156:159], v[168:171], v[34:49]
	s_waitcnt lgkmcnt(6)
	v_mfma_f32_32x32x16_bf16 v[18:33], v[160:163], v[164:167], v[18:33]
	v_mfma_f32_32x32x16_bf16 v[2:17], v[160:163], v[168:171], v[2:17]
	s_waitcnt vmcnt(0) lgkmcnt(0)
	s_barrier
	v_mfma_f32_32x32x16_bf16 v[114:129], v[172:175], v[192:195], v[114:129]
	ds_read_b128 v[130:133], v177 offset:32768
	v_mfma_f32_32x32x16_bf16 v[98:113], v[172:175], v[200:203], v[98:113]
	ds_read_b128 v[164:167], v207 offset:32768
	v_mfma_f32_32x32x16_bf16 v[82:97], v[180:183], v[192:195], v[82:97]
	ds_read_b128 v[168:171], v207 offset:36864
	v_mfma_f32_32x32x16_bf16 v[66:81], v[180:183], v[200:203], v[66:81]
	ds_read_b128 v[134:137], v177 offset:36864
	v_mfma_f32_32x32x16_bf16 v[50:65], v[184:187], v[192:195], v[50:65]
	ds_read_b128 v[156:159], v177 offset:40960
	v_mfma_f32_32x32x16_bf16 v[34:49], v[184:187], v[200:203], v[34:49]
	ds_read_b128 v[160:163], v177 offset:45056
	v_mfma_f32_32x32x16_bf16 v[18:33], v[188:191], v[192:195], v[18:33]
	v_mfma_f32_32x32x16_bf16 v[2:17], v[188:191], v[200:203], v[2:17]
	s_waitcnt lgkmcnt(4)
	v_mfma_f32_32x32x16_bf16 v[114:129], v[130:133], v[164:167], v[114:129]
	ds_read_b128 v[172:175], v204 offset:32768
	s_waitcnt lgkmcnt(4)
	v_mfma_f32_32x32x16_bf16 v[98:113], v[130:133], v[168:171], v[98:113]
	ds_read_b128 v[192:195], v208 offset:32768
	s_waitcnt lgkmcnt(4)
	v_mfma_f32_32x32x16_bf16 v[82:97], v[134:137], v[164:167], v[82:97]
	ds_read_b128 v[200:203], v208 offset:36864
	v_mfma_f32_32x32x16_bf16 v[66:81], v[134:137], v[168:171], v[66:81]
	ds_read_b128 v[180:183], v204 offset:36864
	s_waitcnt lgkmcnt(5)
	v_mfma_f32_32x32x16_bf16 v[50:65], v[156:159], v[164:167], v[50:65]
	ds_read_b128 v[184:187], v204 offset:40960
	v_mfma_f32_32x32x16_bf16 v[34:49], v[156:159], v[168:171], v[34:49]
	ds_read_b128 v[188:191], v204 offset:45056
	s_waitcnt lgkmcnt(6)
	v_mfma_f32_32x32x16_bf16 v[18:33], v[160:163], v[164:167], v[18:33]
	v_mfma_f32_32x32x16_bf16 v[2:17], v[160:163], v[168:171], v[2:17]
	s_waitcnt lgkmcnt(4)
	v_mfma_f32_32x32x16_bf16 v[114:129], v[172:175], v[192:195], v[114:129]
	ds_read_b128 v[130:133], v205 offset:32768
	s_waitcnt lgkmcnt(4)
	v_mfma_f32_32x32x16_bf16 v[98:113], v[172:175], v[200:203], v[98:113]
	ds_read_b128 v[164:167], v209 offset:32768
	s_waitcnt lgkmcnt(4)
	v_mfma_f32_32x32x16_bf16 v[82:97], v[180:183], v[192:195], v[82:97]
	ds_read_b128 v[168:171], v209 offset:36864
	v_mfma_f32_32x32x16_bf16 v[66:81], v[180:183], v[200:203], v[66:81]
	ds_read_b128 v[134:137], v205 offset:36864
	s_waitcnt lgkmcnt(5)
	v_mfma_f32_32x32x16_bf16 v[50:65], v[184:187], v[192:195], v[50:65]
	ds_read_b128 v[156:159], v205 offset:40960
	v_mfma_f32_32x32x16_bf16 v[34:49], v[184:187], v[200:203], v[34:49]
	ds_read_b128 v[160:163], v205 offset:45056
	s_waitcnt lgkmcnt(6)
	v_mfma_f32_32x32x16_bf16 v[18:33], v[188:191], v[192:195], v[18:33]
	v_mfma_f32_32x32x16_bf16 v[2:17], v[188:191], v[200:203], v[2:17]
	s_waitcnt lgkmcnt(4)
	v_mfma_f32_32x32x16_bf16 v[114:129], v[130:133], v[164:167], v[114:129]
	ds_read_b128 v[172:175], v206 offset:32768
	ds_read_b128 v[192:195], v210 offset:32768
	s_waitcnt lgkmcnt(5)
	v_mfma_f32_32x32x16_bf16 v[98:113], v[130:133], v[168:171], v[98:113]
	ds_read_b128 v[200:203], v210 offset:36864
	ds_read_b128 v[180:183], v206 offset:36864
	s_waitcnt lgkmcnt(6)
	v_mfma_f32_32x32x16_bf16 v[82:97], v[134:137], v[164:167], v[82:97]
	ds_read_b128 v[184:187], v206 offset:40960
	ds_read_b128 v[188:191], v206 offset:45056
	v_mfma_f32_32x32x16_bf16 v[66:81], v[134:137], v[168:171], v[66:81]
	s_waitcnt lgkmcnt(7)
	v_mfma_f32_32x32x16_bf16 v[50:65], v[156:159], v[164:167], v[50:65]
	v_mfma_f32_32x32x16_bf16 v[34:49], v[156:159], v[168:171], v[34:49]
	s_waitcnt lgkmcnt(6)
	v_mfma_f32_32x32x16_bf16 v[18:33], v[160:163], v[164:167], v[18:33]
	v_mfma_f32_32x32x16_bf16 v[2:17], v[160:163], v[168:171], v[2:17]
	s_waitcnt vmcnt(0) lgkmcnt(0)
	s_barrier
	v_mfma_f32_32x32x16_bf16 v[114:129], v[172:175], v[192:195], v[114:129]
	v_mfma_f32_32x32x16_bf16 v[98:113], v[172:175], v[200:203], v[98:113]
	v_mfma_f32_32x32x16_bf16 v[82:97], v[180:183], v[192:195], v[82:97]
	v_mfma_f32_32x32x16_bf16 v[66:81], v[180:183], v[200:203], v[66:81]
	v_mfma_f32_32x32x16_bf16 v[50:65], v[184:187], v[192:195], v[50:65]
	v_mfma_f32_32x32x16_bf16 v[34:49], v[184:187], v[200:203], v[34:49]
	v_mfma_f32_32x32x16_bf16 v[18:33], v[188:191], v[192:195], v[18:33]
	v_mfma_f32_32x32x16_bf16 v[2:17], v[188:191], v[200:203], v[2:17]
	v_add_u32_e32 v130, s0, v149
	v_ashrrev_i32_e32 v131, 31, v130
	v_lshrrev_b32_e32 v155, 18, v131
	v_add_u32_e32 v0, v130, v155
	v_ashrrev_i32_e32 v0, 14, v0
	v_mul_i32_i24_e32 v133, 0x4000, v0
	v_sub_u32_e32 v133, v130, v133
	v_add_u32_e32 v156, 0x100, v133
	v_mul_hi_i32_i24_e32 v137, 0x4100, v0
	v_mul_i32_i24_e32 v136, 0x4100, v0
	v_ashrrev_i32_e32 v157, 31, v156
	v_lshl_add_u64 v[136:137], v[136:137], 0, v[156:157]
	v_mov_b32_e32 v156, v179
	s_waitcnt vmcnt(0)
	s_barrier
	v_mul_i32_i24_e32 v134, 0xc00, v0
	v_readlane_b32 s40, v251, 2
	v_and_b32_e32 v0, 31, v156
	v_bfe_u32 v133, v156, 5, 1
	v_mul_u32_u24_e32 v133, 0x240, v133
	v_lshlrev_b32_e32 v0, 2, v0
	v_add3_u32 v0, v151, v133, v0
	ds_write2_b32 v0, v114, v115 offset1:36
	ds_write2_b32 v0, v116, v117 offset0:72 offset1:108
	v_add_u32_e32 v114, 0x400, v0
	v_or_b32_e32 v132, s2, v150
	ds_write2_b32 v114, v118, v119 offset0:32 offset1:68
	ds_write2_b32 v114, v120, v121 offset0:104 offset1:140
	v_add_u32_e32 v114, 0x800, v0
	v_add_u32_e32 v0, 0xc00, v0
	v_readlane_b32 s41, v251, 3
	v_readlane_b32 s42, v251, 4
	v_readlane_b32 s43, v251, 5
	v_readlane_b32 s44, v251, 6
	v_readlane_b32 s45, v251, 7
	v_readlane_b32 s46, v251, 8
	v_readlane_b32 s47, v251, 9
	v_readlane_b32 s48, v251, 10
	v_readlane_b32 s49, v251, 11
	v_readlane_b32 s50, v251, 12
	v_readlane_b32 s51, v251, 13
	v_readlane_b32 s0, v251, 26
	v_ashrrev_i32_e32 v135, 31, v134
	v_lshlrev_b64 v[136:137], 11, v[136:137]
	ds_write2_b32 v114, v122, v123 offset0:64 offset1:100
	ds_write2_b32 v114, v124, v125 offset0:136 offset1:172
	ds_write2_b32 v0, v126, v127 offset0:96 offset1:132
	ds_write2_b32 v0, v128, v129 offset0:168 offset1:204
	v_readlane_b32 s54, v251, 16
	v_readlane_b32 s55, v251, 17
	v_ashrrev_i32_e32 v133, 31, v132
	v_readlane_b32 s1, v251, 27
	v_readlane_b32 s36, v253, 47
	v_lshlrev_b32_e32 v0, 2, v156
	v_readlane_b32 s52, v251, 14
	v_readlane_b32 s53, v251, 15
	v_lshl_add_u64 v[114:115], v[134:135], 2, s[54:55]
	s_mov_b64 s[2:3], 0x1b0b000
	v_lshl_add_u64 v[118:119], s[0:1], 0, v[136:137]
	v_lshlrev_b64 v[116:117], 1, v[132:133]
	v_lshlrev_b64 v[122:123], 12, v[130:131]
	v_readlane_b32 s37, v253, 48
	v_and_b32_e32 v128, 28, v0
	v_lshl_add_u64 v[120:121], v[114:115], 0, s[2:3]
	v_lshlrev_b64 v[114:115], 2, v[132:133]
	v_lshl_add_u64 v[118:119], v[118:119], 0, v[116:117]
	v_lshl_add_u64 v[124:125], s[36:37], 0, v[122:123]
	v_lshl_add_u64 v[122:123], s[52:53], 0, v[122:123]
	v_lshlrev_b32_e32 v0, 2, v128
	v_lshlrev_b32_e32 v128, 1, v128
	v_mov_b32_e32 v129, v1
	v_bfe_u32 v133, v156, 3, 3
	v_lshl_add_u64 v[126:127], v[120:121], 0, v[114:115]
	v_lshl_add_u64 v[124:125], v[124:125], 0, v[114:115]
	v_lshl_add_u64 v[122:123], v[122:123], 0, v[114:115]
	v_lshl_add_u64 v[134:135], v[118:119], 0, v[128:129]
	v_mul_u32_u24_e32 v131, 0x90, v133
	v_lshlrev_b32_e32 v156, 11, v133
	v_mov_b32_e32 v157, v1
	s_waitcnt lgkmcnt(0)
	v_lshl_add_u64 v[126:127], v[126:127], 0, v[0:1]
	v_lshl_add_u64 v[136:137], v[124:125], 0, v[0:1]
	v_lshl_add_u64 v[128:129], v[122:123], 0, v[0:1]
	v_add3_u32 v131, v151, v0, v131
	v_lshlrev_b32_e32 v0, 12, v133
	v_lshl_add_u64 v[156:157], v[134:135], 0, v[156:157]
	v_lshl_add_u64 v[164:165], v[136:137], 0, v[0:1]
	global_load_dwordx2 v[168:169], v[156:157], off
	ds_read_b128 v[156:159], v131
	global_load_dwordx4 v[160:163], v[126:127], off
	s_nop 0
	global_load_dwordx4 v[164:167], v[164:165], off
	v_lshl_add_u64 v[170:171], v[128:129], 0, v[0:1]
	v_readlane_b32 s38, v253, 49
	v_readlane_b32 s39, v253, 50
	v_readlane_b32 s42, v253, 53
	v_readlane_b32 s43, v253, 54
	v_readlane_b32 s44, v253, 55
	v_readlane_b32 s45, v253, 56
	v_readlane_b32 s46, v253, 57
	v_readlane_b32 s47, v253, 58
	v_readlane_b32 s48, v253, 59
	v_readlane_b32 s49, v253, 60
	v_readlane_b32 s51, v253, 62
	v_readlane_b32 s40, v253, 51
	v_readlane_b32 s41, v253, 52
	v_readlane_b32 s50, v253, 61
	s_waitcnt vmcnt(2)
	v_and_b32_e32 v173, 0xffff0000, v168
	v_lshlrev_b32_e32 v172, 16, v168
	s_waitcnt vmcnt(0)
	v_pk_add_f32 v[164:165], v[164:165], v[172:173]
	s_waitcnt lgkmcnt(0)
	v_pk_fma_f32 v[156:157], v[156:157], v[160:161], v[164:165]
	v_and_b32_e32 v161, 0xffff0000, v169
	v_lshlrev_b32_e32 v160, 16, v169
	v_pk_add_f32 v[160:161], v[166:167], v[160:161]
	s_nop 0
	v_pk_fma_f32 v[158:159], v[158:159], v[162:163], v[160:161]
	global_store_dwordx4 v[170:171], v[156:159], off
	s_nop 1
	v_or_b32_e32 v156, 8, v133
	v_lshlrev_b32_e32 v0, 12, v156
	v_lshlrev_b32_e32 v156, 11, v156
	v_mov_b32_e32 v157, v1
	v_lshl_add_u64 v[156:157], v[134:135], 0, v[156:157]
	v_lshl_add_u64 v[164:165], v[136:137], 0, v[0:1]
	global_load_dwordx2 v[168:169], v[156:157], off
	ds_read_b128 v[156:159], v131 offset:1152
	global_load_dwordx4 v[160:163], v[126:127], off
	s_nop 0
	global_load_dwordx4 v[164:167], v[164:165], off
	v_lshl_add_u64 v[170:171], v[128:129], 0, v[0:1]
	v_or_b32_e32 v0, 16, v133
	s_waitcnt vmcnt(2)
	v_and_b32_e32 v173, 0xffff0000, v168
	v_lshlrev_b32_e32 v172, 16, v168
	s_waitcnt vmcnt(0)
	v_pk_add_f32 v[164:165], v[164:165], v[172:173]
	s_waitcnt lgkmcnt(0)
	v_pk_fma_f32 v[156:157], v[156:157], v[160:161], v[164:165]
	v_and_b32_e32 v161, 0xffff0000, v169
	v_lshlrev_b32_e32 v160, 16, v169
	v_pk_add_f32 v[160:161], v[166:167], v[160:161]
	s_nop 0
	v_pk_fma_f32 v[158:159], v[158:159], v[162:163], v[160:161]
	global_store_dwordx4 v[170:171], v[156:159], off
	s_nop 1
	v_lshlrev_b32_e32 v158, 11, v0
	v_mov_b32_e32 v159, v1
	v_lshlrev_b32_e32 v156, 12, v0
	v_mov_b32_e32 v157, v1
	v_lshl_add_u64 v[158:159], v[134:135], 0, v[158:159]
	v_lshl_add_u64 v[164:165], v[136:137], 0, v[156:157]
	global_load_dwordx2 v[168:169], v[158:159], off
	v_lshl_add_u64 v[170:171], v[128:129], 0, v[156:157]
	ds_read_b128 v[156:159], v131 offset:2304
	global_load_dwordx4 v[160:163], v[126:127], off
	s_nop 0
	global_load_dwordx4 v[164:167], v[164:165], off
	v_or_b32_e32 v0, 24, v133
	s_waitcnt vmcnt(2)
	v_and_b32_e32 v173, 0xffff0000, v168
	v_lshlrev_b32_e32 v172, 16, v168
	s_waitcnt vmcnt(0)
	v_pk_add_f32 v[164:165], v[164:165], v[172:173]
	s_waitcnt lgkmcnt(0)
	v_pk_fma_f32 v[156:157], v[156:157], v[160:161], v[164:165]
	v_and_b32_e32 v161, 0xffff0000, v169
	v_lshlrev_b32_e32 v160, 16, v169
	v_pk_add_f32 v[160:161], v[166:167], v[160:161]
	s_nop 0
	v_pk_fma_f32 v[158:159], v[158:159], v[162:163], v[160:161]
	global_store_dwordx4 v[170:171], v[156:159], off
	s_nop 1
	v_lshlrev_b32_e32 v156, 12, v0
	v_mov_b32_e32 v157, v1
	v_lshl_add_u64 v[158:159], v[136:137], 0, v[156:157]
	v_lshlrev_b32_e32 v136, 11, v0
	v_mov_b32_e32 v137, v1
	v_lshl_add_u64 v[134:135], v[134:135], 0, v[136:137]
	global_load_dwordx2 v[160:161], v[134:135], off
	v_lshl_add_u64 v[162:163], v[128:129], 0, v[156:157]
	ds_read_b128 v[134:137], v131 offset:3456
	global_load_dwordx4 v[126:129], v[126:127], off
	s_nop 0
	global_load_dwordx4 v[156:159], v[158:159], off
	s_waitcnt vmcnt(2)
	v_and_b32_e32 v165, 0xffff0000, v160
	v_lshlrev_b32_e32 v164, 16, v160
	s_waitcnt vmcnt(0)
	v_pk_add_f32 v[156:157], v[156:157], v[164:165]
	s_waitcnt lgkmcnt(0)
	v_pk_fma_f32 v[126:127], v[134:135], v[126:127], v[156:157]
	v_and_b32_e32 v135, 0xffff0000, v161
	v_lshlrev_b32_e32 v134, 16, v161
	v_pk_add_f32 v[134:135], v[158:159], v[134:135]
	s_nop 0
	v_pk_fma_f32 v[128:129], v[136:137], v[128:129], v[134:135]
	global_store_dwordx4 v[162:163], v[126:129], off
	v_mov_b32_e32 v0, v179
	s_nop 0
	v_or_b32_e32 v126, 32, v132
	v_and_b32_e32 v127, 31, v0
	v_bfe_u32 v128, v0, 5, 1
	v_mul_u32_u24_e32 v128, 0x240, v128
	v_lshlrev_b32_e32 v127, 2, v127
	v_add3_u32 v127, v151, v128, v127
	ds_write2_b32 v127, v98, v99 offset1:36
	ds_write2_b32 v127, v100, v101 offset0:72 offset1:108
	v_add_u32_e32 v98, 0x400, v127
	ds_write2_b32 v98, v102, v103 offset0:32 offset1:68
	ds_write2_b32 v98, v104, v105 offset0:104 offset1:140
	v_add_u32_e32 v98, 0x800, v127
	ds_write2_b32 v98, v106, v107 offset0:64 offset1:100
	ds_write2_b32 v98, v108, v109 offset0:136 offset1:172
	v_add_u32_e32 v98, 0xc00, v127
	ds_write2_b32 v98, v110, v111 offset0:96 offset1:132
	ds_write2_b32 v98, v112, v113 offset0:168 offset1:204
	v_lshlrev_b32_e32 v98, 2, v0
	v_and_b32_e32 v102, 28, v98
	v_lshlrev_b32_e32 v108, 2, v102
	v_lshlrev_b32_e32 v102, 1, v102
	v_mov_b32_e32 v103, v1
	v_bfe_u32 v131, v0, 3, 3
	v_ashrrev_i32_e32 v127, 31, v126
	v_mov_b32_e32 v109, v1
	v_lshl_add_u64 v[104:105], v[118:119], 0, v[102:103]
	v_lshlrev_b32_e32 v110, 11, v131
	v_mov_b32_e32 v111, v1
	s_waitcnt lgkmcnt(0)
	v_lshl_add_u64 v[100:101], v[120:121], 0, v[108:109]
	v_lshlrev_b64 v[98:99], 2, v[126:127]
	v_mul_u32_u24_e32 v0, 0x90, v131
	v_lshl_add_u64 v[110:111], v[104:105], 0, v[110:111]
	v_lshl_add_u64 v[100:101], v[100:101], 0, v[98:99]
	v_lshl_add_u64 v[106:107], v[124:125], 0, v[108:109]
	v_lshl_add_u64 v[102:103], v[122:123], 0, v[108:109]
	v_add3_u32 v0, v151, v108, v0
	v_lshlrev_b32_e32 v108, 12, v131
	global_load_dwordx2 v[126:127], v[110:111], off offset:64
	v_lshl_add_u64 v[112:113], v[106:107], 0, v[108:109]
	v_lshl_add_u64 v[128:129], v[102:103], 0, v[108:109]
	ds_read_b128 v[108:111], v0
	global_load_dwordx4 v[118:121], v[100:101], off
	global_load_dwordx4 v[122:125], v[112:113], off offset:128
	s_waitcnt vmcnt(2)
	v_and_b32_e32 v113, 0xffff0000, v126
	v_lshlrev_b32_e32 v112, 16, v126
	s_waitcnt vmcnt(0)
	v_pk_add_f32 v[112:113], v[122:123], v[112:113]
	s_waitcnt lgkmcnt(0)
	v_pk_fma_f32 v[108:109], v[108:109], v[118:119], v[112:113]
	v_and_b32_e32 v113, 0xffff0000, v127
	v_lshlrev_b32_e32 v112, 16, v127
	v_pk_add_f32 v[112:113], v[124:125], v[112:113]
	s_nop 0
	v_pk_fma_f32 v[110:111], v[110:111], v[120:121], v[112:113]
	global_store_dwordx4 v[128:129], v[108:111], off offset:128
	s_nop 1
	v_or_b32_e32 v110, 8, v131
	v_lshlrev_b32_e32 v108, 12, v110
	v_lshlrev_b32_e32 v110, 11, v110
	v_mov_b32_e32 v111, v1
	v_lshl_add_u64 v[110:111], v[104:105], 0, v[110:111]
	v_mov_b32_e32 v109, v1
	global_load_dwordx2 v[126:127], v[110:111], off offset:64
	v_lshl_add_u64 v[112:113], v[106:107], 0, v[108:109]
	v_lshl_add_u64 v[128:129], v[102:103], 0, v[108:109]
	ds_read_b128 v[108:111], v0 offset:1152
	global_load_dwordx4 v[118:121], v[100:101], off
	global_load_dwordx4 v[122:125], v[112:113], off offset:128
	s_waitcnt vmcnt(2)
	v_and_b32_e32 v113, 0xffff0000, v126
	v_lshlrev_b32_e32 v112, 16, v126
	s_waitcnt vmcnt(0)
	v_pk_add_f32 v[112:113], v[122:123], v[112:113]
	s_waitcnt lgkmcnt(0)
	v_pk_fma_f32 v[108:109], v[108:109], v[118:119], v[112:113]
	v_and_b32_e32 v113, 0xffff0000, v127
	v_lshlrev_b32_e32 v112, 16, v127
	v_pk_add_f32 v[112:113], v[124:125], v[112:113]
	s_nop 0
	v_pk_fma_f32 v[110:111], v[110:111], v[120:121], v[112:113]
	global_store_dwordx4 v[128:129], v[108:111], off offset:128
	s_nop 1
	v_or_b32_e32 v110, 16, v131
	v_lshlrev_b32_e32 v108, 12, v110
	v_lshlrev_b32_e32 v110, 11, v110
	v_mov_b32_e32 v111, v1
	v_lshl_add_u64 v[110:111], v[104:105], 0, v[110:111]
	v_mov_b32_e32 v109, v1
	global_load_dwordx2 v[126:127], v[110:111], off offset:64
	v_lshl_add_u64 v[112:113], v[106:107], 0, v[108:109]
	v_lshl_add_u64 v[128:129], v[102:103], 0, v[108:109]
	ds_read_b128 v[108:111], v0 offset:2304
	global_load_dwordx4 v[118:121], v[100:101], off
	global_load_dwordx4 v[122:125], v[112:113], off offset:128
	s_waitcnt vmcnt(2)
	v_and_b32_e32 v113, 0xffff0000, v126
	v_lshlrev_b32_e32 v112, 16, v126
	s_waitcnt vmcnt(0)
	v_pk_add_f32 v[112:113], v[122:123], v[112:113]
	s_waitcnt lgkmcnt(0)
	v_pk_fma_f32 v[108:109], v[108:109], v[118:119], v[112:113]
	v_and_b32_e32 v113, 0xffff0000, v127
	v_lshlrev_b32_e32 v112, 16, v127
	v_pk_add_f32 v[112:113], v[124:125], v[112:113]
	s_nop 0
	v_pk_fma_f32 v[110:111], v[110:111], v[120:121], v[112:113]
	v_or_b32_e32 v112, 24, v131
	global_store_dwordx4 v[128:129], v[108:111], off offset:128
	s_nop 1
	v_lshlrev_b32_e32 v108, 12, v112
	v_mov_b32_e32 v109, v1
	v_lshl_add_u64 v[110:111], v[106:107], 0, v[108:109]
	v_lshlrev_b32_e32 v106, 11, v112
	v_mov_b32_e32 v107, v1
	v_lshl_add_u64 v[104:105], v[104:105], 0, v[106:107]
	global_load_dwordx2 v[118:119], v[104:105], off offset:64
	v_lshl_add_u64 v[120:121], v[102:103], 0, v[108:109]
	ds_read_b128 v[102:105], v0 offset:3456
	global_load_dwordx4 v[106:109], v[100:101], off
	s_nop 0
	global_load_dwordx4 v[110:113], v[110:111], off offset:128
	s_waitcnt vmcnt(2)
	v_and_b32_e32 v101, 0xffff0000, v118
	v_lshlrev_b32_e32 v100, 16, v118
	s_waitcnt vmcnt(0)
	v_pk_add_f32 v[100:101], v[110:111], v[100:101]
	s_waitcnt lgkmcnt(0)
	v_pk_fma_f32 v[100:101], v[102:103], v[106:107], v[100:101]
	v_and_b32_e32 v103, 0xffff0000, v119
	v_lshlrev_b32_e32 v102, 16, v119
	v_pk_add_f32 v[102:103], v[112:113], v[102:103]
	s_nop 0
	v_pk_fma_f32 v[102:103], v[104:105], v[108:109], v[102:103]
	global_store_dwordx4 v[120:121], v[100:103], off offset:128
	s_nop 1
	v_or_b32_e32 v100, 32, v130
	v_add_u32_e32 v0, v100, v155
	v_ashrrev_i32_e32 v0, 14, v0
	v_mul_i32_i24_e32 v101, 0x4000, v0
	v_sub_u32_e32 v101, v100, v101
	v_add_u32_e32 v106, 0x100, v101
	v_mul_i32_i24_e32 v102, 0xc00, v0
	v_mul_hi_i32_i24_e32 v105, 0x4100, v0
	v_mul_i32_i24_e32 v104, 0x4100, v0
	v_ashrrev_i32_e32 v107, 31, v106
	v_mov_b32_e32 v0, v179
	v_lshl_add_u64 v[104:105], v[104:105], 0, v[106:107]
	v_ashrrev_i32_e32 v103, 31, v102
	v_and_b32_e32 v106, 31, v0
	v_bfe_u32 v107, v0, 5, 1
	v_mul_u32_u24_e32 v107, 0x240, v107
	v_lshlrev_b32_e32 v106, 2, v106
	v_add3_u32 v106, v151, v107, v106
	ds_write2_b32 v106, v82, v83 offset1:36
	ds_write2_b32 v106, v84, v85 offset0:72 offset1:108
	v_add_u32_e32 v82, 0x400, v106
	ds_write2_b32 v82, v86, v87 offset0:32 offset1:68
	ds_write2_b32 v82, v88, v89 offset0:104 offset1:140
	v_add_u32_e32 v82, 0x800, v106
	ds_write2_b32 v82, v90, v91 offset0:64 offset1:100
	ds_write2_b32 v82, v92, v93 offset0:136 offset1:172
	v_add_u32_e32 v82, 0xc00, v106
	v_lshlrev_b64 v[104:105], 11, v[104:105]
	v_ashrrev_i32_e32 v101, 31, v100
	ds_write2_b32 v82, v94, v95 offset0:96 offset1:132
	ds_write2_b32 v82, v96, v97 offset0:168 offset1:204
	v_lshl_add_u64 v[82:83], v[102:103], 2, s[54:55]
	v_lshlrev_b32_e32 v92, 2, v0
	v_lshl_add_u64 v[86:87], v[82:83], 0, s[2:3]
	v_lshl_add_u64 v[82:83], s[0:1], 0, v[104:105]
	v_lshlrev_b64 v[84:85], 12, v[100:101]
	v_and_b32_e32 v92, 28, v92
	v_lshl_add_u64 v[82:83], v[82:83], 0, v[116:117]
	v_lshl_add_u64 v[88:89], s[36:37], 0, v[84:85]
	v_lshl_add_u64 v[84:85], s[52:53], 0, v[84:85]
	v_lshlrev_b32_e32 v100, 2, v92
	v_lshlrev_b32_e32 v92, 1, v92
	v_mov_b32_e32 v93, v1
	v_bfe_u32 v122, v0, 3, 3
	v_lshl_add_u64 v[90:91], v[86:87], 0, v[114:115]
	v_lshl_add_u64 v[88:89], v[88:89], 0, v[114:115]
	v_lshl_add_u64 v[84:85], v[84:85], 0, v[114:115]
	v_mov_b32_e32 v101, v1
	v_lshl_add_u64 v[94:95], v[82:83], 0, v[92:93]
	v_mul_u32_u24_e32 v0, 0x90, v122
	v_lshlrev_b32_e32 v102, 11, v122
	v_mov_b32_e32 v103, v1
	s_waitcnt lgkmcnt(0)
	v_lshl_add_u64 v[90:91], v[90:91], 0, v[100:101]
	v_lshl_add_u64 v[96:97], v[88:89], 0, v[100:101]
	v_lshl_add_u64 v[92:93], v[84:85], 0, v[100:101]
	v_add3_u32 v0, v151, v100, v0
	v_lshlrev_b32_e32 v100, 12, v122
	v_lshl_add_u64 v[102:103], v[94:95], 0, v[102:103]
	v_lshl_add_u64 v[108:109], v[96:97], 0, v[100:101]
	global_load_dwordx2 v[112:113], v[102:103], off
	v_lshl_add_u64 v[118:119], v[92:93], 0, v[100:101]
	ds_read_b128 v[100:103], v0
	global_load_dwordx4 v[104:107], v[90:91], off
	s_nop 0
	global_load_dwordx4 v[108:111], v[108:109], off
	s_waitcnt vmcnt(2)
	v_and_b32_e32 v121, 0xffff0000, v112
	v_lshlrev_b32_e32 v120, 16, v112
	s_waitcnt vmcnt(0)
	v_pk_add_f32 v[108:109], v[108:109], v[120:121]
	s_waitcnt lgkmcnt(0)
	v_pk_fma_f32 v[100:101], v[100:101], v[104:105], v[108:109]
	v_and_b32_e32 v105, 0xffff0000, v113
	v_lshlrev_b32_e32 v104, 16, v113
	v_pk_add_f32 v[104:105], v[110:111], v[104:105]
	s_nop 0
	v_pk_fma_f32 v[102:103], v[102:103], v[106:107], v[104:105]
	global_store_dwordx4 v[118:119], v[100:103], off
	s_nop 1
	v_or_b32_e32 v102, 8, v122
	v_lshlrev_b32_e32 v100, 12, v102
	v_lshlrev_b32_e32 v102, 11, v102
	v_mov_b32_e32 v103, v1
	v_mov_b32_e32 v101, v1
	v_lshl_add_u64 v[102:103], v[94:95], 0, v[102:103]
	v_lshl_add_u64 v[108:109], v[96:97], 0, v[100:101]
	global_load_dwordx2 v[112:113], v[102:103], off
	v_lshl_add_u64 v[118:119], v[92:93], 0, v[100:101]
	ds_read_b128 v[100:103], v0 offset:1152
	global_load_dwordx4 v[104:107], v[90:91], off
	s_nop 0
	global_load_dwordx4 v[108:111], v[108:109], off
	s_waitcnt vmcnt(2)
	v_and_b32_e32 v121, 0xffff0000, v112
	v_lshlrev_b32_e32 v120, 16, v112
	s_waitcnt vmcnt(0)
	v_pk_add_f32 v[108:109], v[108:109], v[120:121]
	s_waitcnt lgkmcnt(0)
	v_pk_fma_f32 v[100:101], v[100:101], v[104:105], v[108:109]
	v_and_b32_e32 v105, 0xffff0000, v113
	v_lshlrev_b32_e32 v104, 16, v113
	v_pk_add_f32 v[104:105], v[110:111], v[104:105]
	s_nop 0
	v_pk_fma_f32 v[102:103], v[102:103], v[106:107], v[104:105]
	global_store_dwordx4 v[118:119], v[100:103], off
	s_nop 1
	v_or_b32_e32 v102, 16, v122
	v_lshlrev_b32_e32 v100, 12, v102
	v_lshlrev_b32_e32 v102, 11, v102
	v_mov_b32_e32 v103, v1
	v_mov_b32_e32 v101, v1
	v_lshl_add_u64 v[102:103], v[94:95], 0, v[102:103]
	v_lshl_add_u64 v[108:109], v[96:97], 0, v[100:101]
	global_load_dwordx2 v[112:113], v[102:103], off
	v_lshl_add_u64 v[118:119], v[92:93], 0, v[100:101]
	ds_read_b128 v[100:103], v0 offset:2304
	global_load_dwordx4 v[104:107], v[90:91], off
	s_nop 0
	global_load_dwordx4 v[108:111], v[108:109], off
	s_waitcnt vmcnt(2)
	v_and_b32_e32 v121, 0xffff0000, v112
	v_lshlrev_b32_e32 v120, 16, v112
	s_waitcnt vmcnt(0)
	v_pk_add_f32 v[108:109], v[108:109], v[120:121]
	s_waitcnt lgkmcnt(0)
	v_pk_fma_f32 v[100:101], v[100:101], v[104:105], v[108:109]
	v_and_b32_e32 v105, 0xffff0000, v113
	v_lshlrev_b32_e32 v104, 16, v113
	v_pk_add_f32 v[104:105], v[110:111], v[104:105]
	s_nop 0
	v_pk_fma_f32 v[102:103], v[102:103], v[106:107], v[104:105]
	global_store_dwordx4 v[118:119], v[100:103], off
	s_nop 1
	v_or_b32_e32 v102, 24, v122
	v_lshlrev_b32_e32 v100, 12, v102
	v_lshlrev_b32_e32 v102, 11, v102
	v_mov_b32_e32 v103, v1
	v_lshl_add_u64 v[94:95], v[94:95], 0, v[102:103]
	v_mov_b32_e32 v101, v1
	global_load_dwordx2 v[108:109], v[94:95], off
	v_lshl_add_u64 v[96:97], v[96:97], 0, v[100:101]
	v_lshl_add_u64 v[110:111], v[92:93], 0, v[100:101]
	ds_read_b128 v[92:95], v0 offset:3456
	global_load_dwordx4 v[100:103], v[90:91], off
	global_load_dwordx4 v[104:107], v[96:97], off
	s_waitcnt vmcnt(2)
	v_and_b32_e32 v91, 0xffff0000, v108
	v_lshlrev_b32_e32 v90, 16, v108
	s_waitcnt vmcnt(0)
	v_pk_add_f32 v[90:91], v[104:105], v[90:91]
	s_waitcnt lgkmcnt(0)
	v_pk_fma_f32 v[90:91], v[92:93], v[100:101], v[90:91]
	v_and_b32_e32 v93, 0xffff0000, v109
	v_lshlrev_b32_e32 v92, 16, v109
	v_pk_add_f32 v[92:93], v[106:107], v[92:93]
	s_nop 0
	v_pk_fma_f32 v[92:93], v[94:95], v[102:103], v[92:93]
	global_store_dwordx4 v[110:111], v[90:93], off
	v_mov_b32_e32 v0, v179
	s_nop 0
	v_and_b32_e32 v90, 31, v0
	v_bfe_u32 v91, v0, 5, 1
	v_mul_u32_u24_e32 v91, 0x240, v91
	v_lshlrev_b32_e32 v90, 2, v90
	v_add3_u32 v90, v151, v91, v90
	ds_write2_b32 v90, v66, v67 offset1:36
	ds_write2_b32 v90, v68, v69 offset0:72 offset1:108
	v_add_u32_e32 v66, 0x400, v90
	ds_write2_b32 v66, v70, v71 offset0:32 offset1:68
	ds_write2_b32 v66, v72, v73 offset0:104 offset1:140
	v_add_u32_e32 v66, 0x800, v90
	ds_write2_b32 v66, v74, v75 offset0:64 offset1:100
	ds_write2_b32 v66, v76, v77 offset0:136 offset1:172
	v_add_u32_e32 v66, 0xc00, v90
	ds_write2_b32 v66, v78, v79 offset0:96 offset1:132
	ds_write2_b32 v66, v80, v81 offset0:168 offset1:204
	v_lshlrev_b32_e32 v66, 2, v0
	v_and_b32_e32 v68, 28, v66
	v_lshlrev_b32_e32 v74, 2, v68
	v_lshlrev_b32_e32 v68, 1, v68
	v_mov_b32_e32 v69, v1
	v_bfe_u32 v92, v0, 3, 3
	v_mov_b32_e32 v75, v1
	v_lshl_add_u64 v[70:71], v[82:83], 0, v[68:69]
	v_mul_u32_u24_e32 v0, 0x90, v92
	v_lshlrev_b32_e32 v76, 11, v92
	v_mov_b32_e32 v77, v1
	s_waitcnt lgkmcnt(0)
	v_lshl_add_u64 v[66:67], v[86:87], 0, v[74:75]
	v_lshl_add_u64 v[72:73], v[88:89], 0, v[74:75]
	v_lshl_add_u64 v[68:69], v[84:85], 0, v[74:75]
	v_add3_u32 v0, v151, v74, v0
	v_lshlrev_b32_e32 v74, 12, v92
	v_lshl_add_u64 v[76:77], v[70:71], 0, v[76:77]
	v_lshl_add_u64 v[66:67], v[66:67], 0, v[98:99]
	v_lshl_add_u64 v[82:83], v[72:73], 0, v[74:75]
	global_load_dwordx2 v[86:87], v[76:77], off offset:64
	v_lshl_add_u64 v[88:89], v[68:69], 0, v[74:75]
	ds_read_b128 v[74:77], v0
	global_load_dwordx4 v[78:81], v[66:67], off
	s_nop 0
	global_load_dwordx4 v[82:85], v[82:83], off offset:128
	s_waitcnt vmcnt(2)
	v_and_b32_e32 v91, 0xffff0000, v86
	v_lshlrev_b32_e32 v90, 16, v86
	s_waitcnt vmcnt(0)
	v_pk_add_f32 v[82:83], v[82:83], v[90:91]
	s_waitcnt lgkmcnt(0)
	v_pk_fma_f32 v[74:75], v[74:75], v[78:79], v[82:83]
	v_and_b32_e32 v79, 0xffff0000, v87
	v_lshlrev_b32_e32 v78, 16, v87
	v_pk_add_f32 v[78:79], v[84:85], v[78:79]
	s_nop 0
	v_pk_fma_f32 v[76:77], v[76:77], v[80:81], v[78:79]
	global_store_dwordx4 v[88:89], v[74:77], off offset:128
	s_nop 1
	v_or_b32_e32 v76, 8, v92
	v_lshlrev_b32_e32 v74, 12, v76
	v_lshlrev_b32_e32 v76, 11, v76
	v_mov_b32_e32 v77, v1
	v_mov_b32_e32 v75, v1
	v_lshl_add_u64 v[76:77], v[70:71], 0, v[76:77]
	v_lshl_add_u64 v[82:83], v[72:73], 0, v[74:75]
	global_load_dwordx2 v[86:87], v[76:77], off offset:64
	v_lshl_add_u64 v[88:89], v[68:69], 0, v[74:75]
	ds_read_b128 v[74:77], v0 offset:1152
	global_load_dwordx4 v[78:81], v[66:67], off
	s_nop 0
	global_load_dwordx4 v[82:85], v[82:83], off offset:128
	s_waitcnt vmcnt(2)
	v_and_b32_e32 v91, 0xffff0000, v86
	v_lshlrev_b32_e32 v90, 16, v86
	s_waitcnt vmcnt(0)
	v_pk_add_f32 v[82:83], v[82:83], v[90:91]
	s_waitcnt lgkmcnt(0)
	v_pk_fma_f32 v[74:75], v[74:75], v[78:79], v[82:83]
	v_and_b32_e32 v79, 0xffff0000, v87
	v_lshlrev_b32_e32 v78, 16, v87
	v_pk_add_f32 v[78:79], v[84:85], v[78:79]
	s_nop 0
	v_pk_fma_f32 v[76:77], v[76:77], v[80:81], v[78:79]
	global_store_dwordx4 v[88:89], v[74:77], off offset:128
	s_nop 1
	v_or_b32_e32 v76, 16, v92
	v_lshlrev_b32_e32 v74, 12, v76
	v_lshlrev_b32_e32 v76, 11, v76
	v_mov_b32_e32 v77, v1
	v_mov_b32_e32 v75, v1
	v_lshl_add_u64 v[76:77], v[70:71], 0, v[76:77]
	v_lshl_add_u64 v[82:83], v[72:73], 0, v[74:75]
	global_load_dwordx2 v[86:87], v[76:77], off offset:64
	v_lshl_add_u64 v[88:89], v[68:69], 0, v[74:75]
	ds_read_b128 v[74:77], v0 offset:2304
	global_load_dwordx4 v[78:81], v[66:67], off
	s_nop 0
	global_load_dwordx4 v[82:85], v[82:83], off offset:128
	s_waitcnt vmcnt(2)
	v_and_b32_e32 v91, 0xffff0000, v86
	v_lshlrev_b32_e32 v90, 16, v86
	s_waitcnt vmcnt(0)
	v_pk_add_f32 v[82:83], v[82:83], v[90:91]
	s_waitcnt lgkmcnt(0)
	v_pk_fma_f32 v[74:75], v[74:75], v[78:79], v[82:83]
	v_and_b32_e32 v79, 0xffff0000, v87
	v_lshlrev_b32_e32 v78, 16, v87
	v_pk_add_f32 v[78:79], v[84:85], v[78:79]
	s_nop 0
	v_pk_fma_f32 v[76:77], v[76:77], v[80:81], v[78:79]
	v_or_b32_e32 v78, 24, v92
	global_store_dwordx4 v[88:89], v[74:77], off offset:128
	s_nop 1
	v_lshlrev_b32_e32 v74, 12, v78
	v_mov_b32_e32 v75, v1
	v_lshl_add_u64 v[76:77], v[72:73], 0, v[74:75]
	v_lshlrev_b32_e32 v72, 11, v78
	v_mov_b32_e32 v73, v1
	v_lshl_add_u64 v[70:71], v[70:71], 0, v[72:73]
	global_load_dwordx2 v[80:81], v[70:71], off offset:64
	v_lshl_add_u64 v[82:83], v[68:69], 0, v[74:75]
	ds_read_b128 v[68:71], v0 offset:3456
	global_load_dwordx4 v[72:75], v[66:67], off
	s_nop 0
	global_load_dwordx4 v[76:79], v[76:77], off offset:128
	s_waitcnt vmcnt(2)
	v_and_b32_e32 v67, 0xffff0000, v80
	v_lshlrev_b32_e32 v66, 16, v80
	s_waitcnt vmcnt(0)
	v_pk_add_f32 v[66:67], v[76:77], v[66:67]
	s_waitcnt lgkmcnt(0)
	v_pk_fma_f32 v[66:67], v[68:69], v[72:73], v[66:67]
	v_and_b32_e32 v69, 0xffff0000, v81
	v_lshlrev_b32_e32 v68, 16, v81
	v_pk_add_f32 v[68:69], v[78:79], v[68:69]
	s_nop 0
	v_pk_fma_f32 v[68:69], v[70:71], v[74:75], v[68:69]
	global_store_dwordx4 v[82:83], v[66:69], off offset:128
	s_nop 1
	v_or_b32_e32 v66, 64, v130
	v_add_u32_e32 v0, v66, v155
	v_ashrrev_i32_e32 v0, 14, v0
	v_mul_i32_i24_e32 v67, 0x4000, v0
	v_sub_u32_e32 v67, v66, v67
	v_add_u32_e32 v72, 0x100, v67
	v_mul_i32_i24_e32 v68, 0xc00, v0
	v_mul_hi_i32_i24_e32 v71, 0x4100, v0
	v_mul_i32_i24_e32 v70, 0x4100, v0
	v_ashrrev_i32_e32 v73, 31, v72
	v_mov_b32_e32 v0, v179
	v_lshl_add_u64 v[70:71], v[70:71], 0, v[72:73]
	v_ashrrev_i32_e32 v69, 31, v68
	v_and_b32_e32 v72, 31, v0
	v_bfe_u32 v73, v0, 5, 1
	v_mul_u32_u24_e32 v73, 0x240, v73
	v_lshlrev_b32_e32 v72, 2, v72
	v_add3_u32 v72, v151, v73, v72
	ds_write2_b32 v72, v50, v51 offset1:36
	ds_write2_b32 v72, v52, v53 offset0:72 offset1:108
	v_add_u32_e32 v50, 0x400, v72
	ds_write2_b32 v50, v54, v55 offset0:32 offset1:68
	ds_write2_b32 v50, v56, v57 offset0:104 offset1:140
	v_add_u32_e32 v50, 0x800, v72
	ds_write2_b32 v50, v58, v59 offset0:64 offset1:100
	ds_write2_b32 v50, v60, v61 offset0:136 offset1:172
	v_add_u32_e32 v50, 0xc00, v72
	v_lshlrev_b64 v[70:71], 11, v[70:71]
	v_ashrrev_i32_e32 v67, 31, v66
	ds_write2_b32 v50, v62, v63 offset0:96 offset1:132
	ds_write2_b32 v50, v64, v65 offset0:168 offset1:204
	v_lshl_add_u64 v[50:51], v[68:69], 2, s[54:55]
	v_lshlrev_b32_e32 v60, 2, v0
	v_lshl_add_u64 v[54:55], v[50:51], 0, s[2:3]
	v_lshl_add_u64 v[50:51], s[0:1], 0, v[70:71]
	v_lshlrev_b64 v[52:53], 12, v[66:67]
	v_and_b32_e32 v60, 28, v60
	v_lshl_add_u64 v[50:51], v[50:51], 0, v[116:117]
	v_lshl_add_u64 v[56:57], s[36:37], 0, v[52:53]
	v_lshl_add_u64 v[52:53], s[52:53], 0, v[52:53]
	v_lshlrev_b32_e32 v66, 2, v60
	v_lshlrev_b32_e32 v60, 1, v60
	v_mov_b32_e32 v61, v1
	v_bfe_u32 v84, v0, 3, 3
	v_lshl_add_u64 v[58:59], v[54:55], 0, v[114:115]
	v_lshl_add_u64 v[56:57], v[56:57], 0, v[114:115]
	v_lshl_add_u64 v[52:53], v[52:53], 0, v[114:115]
	v_mov_b32_e32 v67, v1
	v_lshl_add_u64 v[62:63], v[50:51], 0, v[60:61]
	v_mul_u32_u24_e32 v0, 0x90, v84
	v_lshlrev_b32_e32 v68, 11, v84
	v_mov_b32_e32 v69, v1
	s_waitcnt lgkmcnt(0)
	v_lshl_add_u64 v[58:59], v[58:59], 0, v[66:67]
	v_lshl_add_u64 v[64:65], v[56:57], 0, v[66:67]
	v_lshl_add_u64 v[60:61], v[52:53], 0, v[66:67]
	v_add3_u32 v0, v151, v66, v0
	v_lshlrev_b32_e32 v66, 12, v84
	v_lshl_add_u64 v[68:69], v[62:63], 0, v[68:69]
	v_lshl_add_u64 v[74:75], v[64:65], 0, v[66:67]
	global_load_dwordx2 v[78:79], v[68:69], off
	v_lshl_add_u64 v[80:81], v[60:61], 0, v[66:67]
	ds_read_b128 v[66:69], v0
	global_load_dwordx4 v[70:73], v[58:59], off
	s_nop 0
	global_load_dwordx4 v[74:77], v[74:75], off
	s_waitcnt vmcnt(2)
	v_and_b32_e32 v83, 0xffff0000, v78
	v_lshlrev_b32_e32 v82, 16, v78
	s_waitcnt vmcnt(0)
	v_pk_add_f32 v[74:75], v[74:75], v[82:83]
	s_waitcnt lgkmcnt(0)
	v_pk_fma_f32 v[66:67], v[66:67], v[70:71], v[74:75]
	v_and_b32_e32 v71, 0xffff0000, v79
	v_lshlrev_b32_e32 v70, 16, v79
	v_pk_add_f32 v[70:71], v[76:77], v[70:71]
	s_nop 0
	v_pk_fma_f32 v[68:69], v[68:69], v[72:73], v[70:71]
	global_store_dwordx4 v[80:81], v[66:69], off
	s_nop 1
	v_or_b32_e32 v68, 8, v84
	v_lshlrev_b32_e32 v66, 12, v68
	v_lshlrev_b32_e32 v68, 11, v68
	v_mov_b32_e32 v69, v1
	v_mov_b32_e32 v67, v1
	v_lshl_add_u64 v[68:69], v[62:63], 0, v[68:69]
	v_lshl_add_u64 v[74:75], v[64:65], 0, v[66:67]
	global_load_dwordx2 v[78:79], v[68:69], off
	v_lshl_add_u64 v[80:81], v[60:61], 0, v[66:67]
	ds_read_b128 v[66:69], v0 offset:1152
	global_load_dwordx4 v[70:73], v[58:59], off
	s_nop 0
	global_load_dwordx4 v[74:77], v[74:75], off
	s_waitcnt vmcnt(2)
	v_and_b32_e32 v83, 0xffff0000, v78
	v_lshlrev_b32_e32 v82, 16, v78
	s_waitcnt vmcnt(0)
	v_pk_add_f32 v[74:75], v[74:75], v[82:83]
	s_waitcnt lgkmcnt(0)
	v_pk_fma_f32 v[66:67], v[66:67], v[70:71], v[74:75]
	v_and_b32_e32 v71, 0xffff0000, v79
	v_lshlrev_b32_e32 v70, 16, v79
	v_pk_add_f32 v[70:71], v[76:77], v[70:71]
	s_nop 0
	v_pk_fma_f32 v[68:69], v[68:69], v[72:73], v[70:71]
	global_store_dwordx4 v[80:81], v[66:69], off
	s_nop 1
	v_or_b32_e32 v68, 16, v84
	v_lshlrev_b32_e32 v66, 12, v68
	v_lshlrev_b32_e32 v68, 11, v68
	v_mov_b32_e32 v69, v1
	v_mov_b32_e32 v67, v1
	v_lshl_add_u64 v[68:69], v[62:63], 0, v[68:69]
	v_lshl_add_u64 v[74:75], v[64:65], 0, v[66:67]
	global_load_dwordx2 v[78:79], v[68:69], off
	v_lshl_add_u64 v[80:81], v[60:61], 0, v[66:67]
	ds_read_b128 v[66:69], v0 offset:2304
	global_load_dwordx4 v[70:73], v[58:59], off
	s_nop 0
	global_load_dwordx4 v[74:77], v[74:75], off
	s_waitcnt vmcnt(2)
	v_and_b32_e32 v83, 0xffff0000, v78
	v_lshlrev_b32_e32 v82, 16, v78
	s_waitcnt vmcnt(0)
	v_pk_add_f32 v[74:75], v[74:75], v[82:83]
	s_waitcnt lgkmcnt(0)
	v_pk_fma_f32 v[66:67], v[66:67], v[70:71], v[74:75]
	v_and_b32_e32 v71, 0xffff0000, v79
	v_lshlrev_b32_e32 v70, 16, v79
	v_pk_add_f32 v[70:71], v[76:77], v[70:71]
	s_nop 0
	v_pk_fma_f32 v[68:69], v[68:69], v[72:73], v[70:71]
	v_or_b32_e32 v70, 24, v84
	global_store_dwordx4 v[80:81], v[66:69], off
	s_nop 1
	v_lshlrev_b32_e32 v66, 12, v70
	v_mov_b32_e32 v67, v1
	v_lshl_add_u64 v[68:69], v[64:65], 0, v[66:67]
	v_lshlrev_b32_e32 v64, 11, v70
	v_mov_b32_e32 v65, v1
	v_lshl_add_u64 v[62:63], v[62:63], 0, v[64:65]
	global_load_dwordx2 v[72:73], v[62:63], off
	v_lshl_add_u64 v[74:75], v[60:61], 0, v[66:67]
	ds_read_b128 v[60:63], v0 offset:3456
	global_load_dwordx4 v[64:67], v[58:59], off
	s_nop 0
	global_load_dwordx4 v[68:71], v[68:69], off
	s_waitcnt vmcnt(2)
	v_and_b32_e32 v59, 0xffff0000, v72
	v_lshlrev_b32_e32 v58, 16, v72
	s_waitcnt vmcnt(0)
	v_pk_add_f32 v[58:59], v[68:69], v[58:59]
	s_waitcnt lgkmcnt(0)
	v_pk_fma_f32 v[58:59], v[60:61], v[64:65], v[58:59]
	v_and_b32_e32 v61, 0xffff0000, v73
	v_lshlrev_b32_e32 v60, 16, v73
	v_pk_add_f32 v[60:61], v[70:71], v[60:61]
	s_nop 0
	v_pk_fma_f32 v[60:61], v[62:63], v[66:67], v[60:61]
	global_store_dwordx4 v[74:75], v[58:61], off
	v_mov_b32_e32 v0, v179
	s_nop 0
	v_and_b32_e32 v58, 31, v0
	v_bfe_u32 v59, v0, 5, 1
	v_mul_u32_u24_e32 v59, 0x240, v59
	v_lshlrev_b32_e32 v58, 2, v58
	v_add3_u32 v58, v151, v59, v58
	ds_write2_b32 v58, v34, v35 offset1:36
	ds_write2_b32 v58, v36, v37 offset0:72 offset1:108
	v_add_u32_e32 v34, 0x400, v58
	ds_write2_b32 v34, v38, v39 offset0:32 offset1:68
	ds_write2_b32 v34, v40, v41 offset0:104 offset1:140
	v_add_u32_e32 v34, 0x800, v58
	ds_write2_b32 v34, v42, v43 offset0:64 offset1:100
	ds_write2_b32 v34, v44, v45 offset0:136 offset1:172
	v_add_u32_e32 v34, 0xc00, v58
	ds_write2_b32 v34, v46, v47 offset0:96 offset1:132
	ds_write2_b32 v34, v48, v49 offset0:168 offset1:204
	v_lshlrev_b32_e32 v34, 2, v0
	v_and_b32_e32 v36, 28, v34
	v_lshlrev_b32_e32 v42, 2, v36
	v_lshlrev_b32_e32 v36, 1, v36
	v_mov_b32_e32 v37, v1
	v_bfe_u32 v60, v0, 3, 3
	v_mov_b32_e32 v43, v1
	v_lshl_add_u64 v[38:39], v[50:51], 0, v[36:37]
	v_mul_u32_u24_e32 v0, 0x90, v60
	v_lshlrev_b32_e32 v44, 11, v60
	v_mov_b32_e32 v45, v1
	s_waitcnt lgkmcnt(0)
	v_lshl_add_u64 v[34:35], v[54:55], 0, v[42:43]
	v_lshl_add_u64 v[40:41], v[56:57], 0, v[42:43]
	v_lshl_add_u64 v[36:37], v[52:53], 0, v[42:43]
	v_add3_u32 v0, v151, v42, v0
	v_lshlrev_b32_e32 v42, 12, v60
	v_lshl_add_u64 v[44:45], v[38:39], 0, v[44:45]
	v_lshl_add_u64 v[34:35], v[34:35], 0, v[98:99]
	v_lshl_add_u64 v[50:51], v[40:41], 0, v[42:43]
	global_load_dwordx2 v[54:55], v[44:45], off offset:64
	v_lshl_add_u64 v[56:57], v[36:37], 0, v[42:43]
	ds_read_b128 v[42:45], v0
	global_load_dwordx4 v[46:49], v[34:35], off
	s_nop 0
	global_load_dwordx4 v[50:53], v[50:51], off offset:128
	s_waitcnt vmcnt(2)
	v_and_b32_e32 v59, 0xffff0000, v54
	v_lshlrev_b32_e32 v58, 16, v54
	s_waitcnt vmcnt(0)
	v_pk_add_f32 v[50:51], v[50:51], v[58:59]
	s_waitcnt lgkmcnt(0)
	v_pk_fma_f32 v[42:43], v[42:43], v[46:47], v[50:51]
	v_and_b32_e32 v47, 0xffff0000, v55
	v_lshlrev_b32_e32 v46, 16, v55
	v_pk_add_f32 v[46:47], v[52:53], v[46:47]
	s_nop 0
	v_pk_fma_f32 v[44:45], v[44:45], v[48:49], v[46:47]
	global_store_dwordx4 v[56:57], v[42:45], off offset:128
	s_nop 1
	v_or_b32_e32 v44, 8, v60
	v_lshlrev_b32_e32 v42, 12, v44
	v_lshlrev_b32_e32 v44, 11, v44
	v_mov_b32_e32 v45, v1
	v_mov_b32_e32 v43, v1
	v_lshl_add_u64 v[44:45], v[38:39], 0, v[44:45]
	v_lshl_add_u64 v[50:51], v[40:41], 0, v[42:43]
	global_load_dwordx2 v[54:55], v[44:45], off offset:64
	v_lshl_add_u64 v[56:57], v[36:37], 0, v[42:43]
	ds_read_b128 v[42:45], v0 offset:1152
	global_load_dwordx4 v[46:49], v[34:35], off
	s_nop 0
	global_load_dwordx4 v[50:53], v[50:51], off offset:128
	s_waitcnt vmcnt(2)
	v_and_b32_e32 v59, 0xffff0000, v54
	v_lshlrev_b32_e32 v58, 16, v54
	s_waitcnt vmcnt(0)
	v_pk_add_f32 v[50:51], v[50:51], v[58:59]
	s_waitcnt lgkmcnt(0)
	v_pk_fma_f32 v[42:43], v[42:43], v[46:47], v[50:51]
	v_and_b32_e32 v47, 0xffff0000, v55
	v_lshlrev_b32_e32 v46, 16, v55
	v_pk_add_f32 v[46:47], v[52:53], v[46:47]
	s_nop 0
	v_pk_fma_f32 v[44:45], v[44:45], v[48:49], v[46:47]
	global_store_dwordx4 v[56:57], v[42:45], off offset:128
	s_nop 1
	v_or_b32_e32 v44, 16, v60
	v_lshlrev_b32_e32 v42, 12, v44
	v_lshlrev_b32_e32 v44, 11, v44
	v_mov_b32_e32 v45, v1
	v_mov_b32_e32 v43, v1
	v_lshl_add_u64 v[44:45], v[38:39], 0, v[44:45]
	v_lshl_add_u64 v[50:51], v[40:41], 0, v[42:43]
	global_load_dwordx2 v[54:55], v[44:45], off offset:64
	v_lshl_add_u64 v[56:57], v[36:37], 0, v[42:43]
	ds_read_b128 v[42:45], v0 offset:2304
	global_load_dwordx4 v[46:49], v[34:35], off
	s_nop 0
	global_load_dwordx4 v[50:53], v[50:51], off offset:128
	s_waitcnt vmcnt(2)
	v_and_b32_e32 v59, 0xffff0000, v54
	v_lshlrev_b32_e32 v58, 16, v54
	s_waitcnt vmcnt(0)
	v_pk_add_f32 v[50:51], v[50:51], v[58:59]
	s_waitcnt lgkmcnt(0)
	v_pk_fma_f32 v[42:43], v[42:43], v[46:47], v[50:51]
	v_and_b32_e32 v47, 0xffff0000, v55
	v_lshlrev_b32_e32 v46, 16, v55
	v_pk_add_f32 v[46:47], v[52:53], v[46:47]
	s_nop 0
	v_pk_fma_f32 v[44:45], v[44:45], v[48:49], v[46:47]
	v_or_b32_e32 v46, 24, v60
	global_store_dwordx4 v[56:57], v[42:45], off offset:128
	s_nop 1
	v_lshlrev_b32_e32 v42, 12, v46
	v_mov_b32_e32 v43, v1
	v_lshl_add_u64 v[44:45], v[40:41], 0, v[42:43]
	v_lshlrev_b32_e32 v40, 11, v46
	v_mov_b32_e32 v41, v1
	v_lshl_add_u64 v[38:39], v[38:39], 0, v[40:41]
	global_load_dwordx2 v[48:49], v[38:39], off offset:64
	v_lshl_add_u64 v[50:51], v[36:37], 0, v[42:43]
	ds_read_b128 v[36:39], v0 offset:3456
	global_load_dwordx4 v[40:43], v[34:35], off
	s_nop 0
	global_load_dwordx4 v[44:47], v[44:45], off offset:128
	s_waitcnt vmcnt(2)
	v_and_b32_e32 v35, 0xffff0000, v48
	v_lshlrev_b32_e32 v34, 16, v48
	s_waitcnt vmcnt(0)
	v_pk_add_f32 v[34:35], v[44:45], v[34:35]
	s_waitcnt lgkmcnt(0)
	v_pk_fma_f32 v[34:35], v[36:37], v[40:41], v[34:35]
	v_and_b32_e32 v37, 0xffff0000, v49
	v_lshlrev_b32_e32 v36, 16, v49
	v_pk_add_f32 v[36:37], v[46:47], v[36:37]
	s_nop 0
	v_pk_fma_f32 v[36:37], v[38:39], v[42:43], v[36:37]
	global_store_dwordx4 v[50:51], v[34:37], off offset:128
	s_nop 1
	v_or_b32_e32 v34, 0x60, v130
	v_add_u32_e32 v0, v34, v155
	v_ashrrev_i32_e32 v0, 14, v0
	v_mul_i32_i24_e32 v35, 0x4000, v0
	v_sub_u32_e32 v35, v34, v35
	v_add_u32_e32 v40, 0x100, v35
	v_mul_i32_i24_e32 v36, 0xc00, v0
	v_mul_hi_i32_i24_e32 v39, 0x4100, v0
	v_mul_i32_i24_e32 v38, 0x4100, v0
	v_ashrrev_i32_e32 v41, 31, v40
	v_mov_b32_e32 v0, v179
	v_lshl_add_u64 v[38:39], v[38:39], 0, v[40:41]
	v_ashrrev_i32_e32 v37, 31, v36
	v_and_b32_e32 v40, 31, v0
	v_bfe_u32 v41, v0, 5, 1
	v_mul_u32_u24_e32 v41, 0x240, v41
	v_lshlrev_b32_e32 v40, 2, v40
	v_add3_u32 v40, v151, v41, v40
	ds_write2_b32 v40, v18, v19 offset1:36
	ds_write2_b32 v40, v20, v21 offset0:72 offset1:108
	v_add_u32_e32 v18, 0x400, v40
	ds_write2_b32 v18, v22, v23 offset0:32 offset1:68
	ds_write2_b32 v18, v24, v25 offset0:104 offset1:140
	v_add_u32_e32 v18, 0x800, v40
	ds_write2_b32 v18, v26, v27 offset0:64 offset1:100
	ds_write2_b32 v18, v28, v29 offset0:136 offset1:172
	v_add_u32_e32 v18, 0xc00, v40
	v_lshlrev_b64 v[38:39], 11, v[38:39]
	v_ashrrev_i32_e32 v35, 31, v34
	ds_write2_b32 v18, v30, v31 offset0:96 offset1:132
	ds_write2_b32 v18, v32, v33 offset0:168 offset1:204
	v_lshl_add_u64 v[18:19], v[36:37], 2, s[54:55]
	v_lshlrev_b32_e32 v28, 2, v0
	v_lshl_add_u64 v[20:21], v[18:19], 0, s[2:3]
	v_lshl_add_u64 v[18:19], s[0:1], 0, v[38:39]
	v_lshlrev_b64 v[22:23], 12, v[34:35]
	v_and_b32_e32 v28, 28, v28
	v_lshl_add_u64 v[18:19], v[18:19], 0, v[116:117]
	v_lshl_add_u64 v[24:25], s[36:37], 0, v[22:23]
	v_lshl_add_u64 v[22:23], s[52:53], 0, v[22:23]
	v_lshlrev_b32_e32 v34, 2, v28
	v_lshlrev_b32_e32 v28, 1, v28
	v_mov_b32_e32 v29, v1
	v_bfe_u32 v52, v0, 3, 3
	v_lshl_add_u64 v[26:27], v[20:21], 0, v[114:115]
	v_lshl_add_u64 v[24:25], v[24:25], 0, v[114:115]
	v_lshl_add_u64 v[22:23], v[22:23], 0, v[114:115]
	v_mov_b32_e32 v35, v1
	v_lshl_add_u64 v[30:31], v[18:19], 0, v[28:29]
	v_mul_u32_u24_e32 v0, 0x90, v52
	v_lshlrev_b32_e32 v36, 11, v52
	v_mov_b32_e32 v37, v1
	s_waitcnt lgkmcnt(0)
	v_lshl_add_u64 v[26:27], v[26:27], 0, v[34:35]
	v_lshl_add_u64 v[32:33], v[24:25], 0, v[34:35]
	v_lshl_add_u64 v[28:29], v[22:23], 0, v[34:35]
	v_add3_u32 v0, v151, v34, v0
	v_lshlrev_b32_e32 v34, 12, v52
	v_lshl_add_u64 v[36:37], v[30:31], 0, v[36:37]
	v_lshl_add_u64 v[42:43], v[32:33], 0, v[34:35]
	global_load_dwordx2 v[46:47], v[36:37], off
	v_lshl_add_u64 v[48:49], v[28:29], 0, v[34:35]
	ds_read_b128 v[34:37], v0
	global_load_dwordx4 v[38:41], v[26:27], off
	s_nop 0
	global_load_dwordx4 v[42:45], v[42:43], off
	s_waitcnt vmcnt(2)
	v_and_b32_e32 v51, 0xffff0000, v46
	v_lshlrev_b32_e32 v50, 16, v46
	s_waitcnt vmcnt(0)
	v_pk_add_f32 v[42:43], v[42:43], v[50:51]
	s_waitcnt lgkmcnt(0)
	v_pk_fma_f32 v[34:35], v[34:35], v[38:39], v[42:43]
	v_and_b32_e32 v39, 0xffff0000, v47
	v_lshlrev_b32_e32 v38, 16, v47
	v_pk_add_f32 v[38:39], v[44:45], v[38:39]
	s_nop 0
	v_pk_fma_f32 v[36:37], v[36:37], v[40:41], v[38:39]
	global_store_dwordx4 v[48:49], v[34:37], off
	s_nop 1
	v_or_b32_e32 v36, 8, v52
	v_lshlrev_b32_e32 v34, 12, v36
	v_lshlrev_b32_e32 v36, 11, v36
	v_mov_b32_e32 v37, v1
	v_mov_b32_e32 v35, v1
	v_lshl_add_u64 v[36:37], v[30:31], 0, v[36:37]
	v_lshl_add_u64 v[42:43], v[32:33], 0, v[34:35]
	global_load_dwordx2 v[46:47], v[36:37], off
	v_lshl_add_u64 v[48:49], v[28:29], 0, v[34:35]
	ds_read_b128 v[34:37], v0 offset:1152
	global_load_dwordx4 v[38:41], v[26:27], off
	s_nop 0
	global_load_dwordx4 v[42:45], v[42:43], off
	s_waitcnt vmcnt(2)
	v_and_b32_e32 v51, 0xffff0000, v46
	v_lshlrev_b32_e32 v50, 16, v46
	s_waitcnt vmcnt(0)
	v_pk_add_f32 v[42:43], v[42:43], v[50:51]
	s_waitcnt lgkmcnt(0)
	v_pk_fma_f32 v[34:35], v[34:35], v[38:39], v[42:43]
	v_and_b32_e32 v39, 0xffff0000, v47
	v_lshlrev_b32_e32 v38, 16, v47
	v_pk_add_f32 v[38:39], v[44:45], v[38:39]
	s_nop 0
	v_pk_fma_f32 v[36:37], v[36:37], v[40:41], v[38:39]
	global_store_dwordx4 v[48:49], v[34:37], off
	s_nop 1
	v_or_b32_e32 v36, 16, v52
	v_lshlrev_b32_e32 v34, 12, v36
	v_lshlrev_b32_e32 v36, 11, v36
	v_mov_b32_e32 v37, v1
	v_mov_b32_e32 v35, v1
	v_lshl_add_u64 v[36:37], v[30:31], 0, v[36:37]
	v_lshl_add_u64 v[42:43], v[32:33], 0, v[34:35]
	global_load_dwordx2 v[46:47], v[36:37], off
	v_lshl_add_u64 v[48:49], v[28:29], 0, v[34:35]
	ds_read_b128 v[34:37], v0 offset:2304
	global_load_dwordx4 v[38:41], v[26:27], off
	s_nop 0
	global_load_dwordx4 v[42:45], v[42:43], off
	s_waitcnt vmcnt(2)
	v_and_b32_e32 v51, 0xffff0000, v46
	v_lshlrev_b32_e32 v50, 16, v46
	s_waitcnt vmcnt(0)
	v_pk_add_f32 v[42:43], v[42:43], v[50:51]
	s_waitcnt lgkmcnt(0)
	v_pk_fma_f32 v[34:35], v[34:35], v[38:39], v[42:43]
	v_and_b32_e32 v39, 0xffff0000, v47
	v_lshlrev_b32_e32 v38, 16, v47
	v_pk_add_f32 v[38:39], v[44:45], v[38:39]
	s_nop 0
	v_pk_fma_f32 v[36:37], v[36:37], v[40:41], v[38:39]
	v_or_b32_e32 v38, 24, v52
	global_store_dwordx4 v[48:49], v[34:37], off
	s_nop 1
	v_lshlrev_b32_e32 v34, 12, v38
	v_mov_b32_e32 v35, v1
	v_lshl_add_u64 v[36:37], v[32:33], 0, v[34:35]
	v_lshlrev_b32_e32 v32, 11, v38
	v_mov_b32_e32 v33, v1
	v_lshl_add_u64 v[30:31], v[30:31], 0, v[32:33]
	global_load_dwordx2 v[40:41], v[30:31], off
	v_lshl_add_u64 v[42:43], v[28:29], 0, v[34:35]
	ds_read_b128 v[28:31], v0 offset:3456
	global_load_dwordx4 v[32:35], v[26:27], off
	s_nop 0
	global_load_dwordx4 v[36:39], v[36:37], off
	s_waitcnt vmcnt(2)
	v_and_b32_e32 v27, 0xffff0000, v40
	v_lshlrev_b32_e32 v26, 16, v40
	s_waitcnt vmcnt(0)
	v_pk_add_f32 v[26:27], v[36:37], v[26:27]
	s_waitcnt lgkmcnt(0)
	v_pk_fma_f32 v[26:27], v[28:29], v[32:33], v[26:27]
	v_and_b32_e32 v29, 0xffff0000, v41
	v_lshlrev_b32_e32 v28, 16, v41
	v_pk_add_f32 v[28:29], v[38:39], v[28:29]
	s_nop 0
	v_pk_fma_f32 v[28:29], v[30:31], v[34:35], v[28:29]
	global_store_dwordx4 v[42:43], v[26:29], off
	v_mov_b32_e32 v0, v179
	s_nop 0
	v_and_b32_e32 v26, 31, v0
	v_bfe_u32 v27, v0, 5, 1
	v_mul_u32_u24_e32 v27, 0x240, v27
	v_lshlrev_b32_e32 v26, 2, v26
	v_add3_u32 v26, v151, v27, v26
	ds_write2_b32 v26, v2, v3 offset1:36
	ds_write2_b32 v26, v4, v5 offset0:72 offset1:108
	v_add_u32_e32 v2, 0x400, v26
	ds_write2_b32 v2, v6, v7 offset0:32 offset1:68
	ds_write2_b32 v2, v8, v9 offset0:104 offset1:140
	v_add_u32_e32 v2, 0x800, v26
	ds_write2_b32 v2, v10, v11 offset0:64 offset1:100
	ds_write2_b32 v2, v12, v13 offset0:136 offset1:172
	v_add_u32_e32 v2, 0xc00, v26
	ds_write2_b32 v2, v14, v15 offset0:96 offset1:132
	ds_write2_b32 v2, v16, v17 offset0:168 offset1:204
	v_lshlrev_b32_e32 v2, 2, v0
	v_and_b32_e32 v4, 28, v2
	v_lshlrev_b32_e32 v10, 2, v4
	v_lshlrev_b32_e32 v4, 1, v4
	v_mov_b32_e32 v5, v1
	v_bfe_u32 v28, v0, 3, 3
	v_mov_b32_e32 v11, v1
	v_lshl_add_u64 v[6:7], v[18:19], 0, v[4:5]
	v_mul_u32_u24_e32 v0, 0x90, v28
	v_lshlrev_b32_e32 v12, 11, v28
	v_mov_b32_e32 v13, v1
	s_waitcnt lgkmcnt(0)
	v_lshl_add_u64 v[2:3], v[20:21], 0, v[10:11]
	v_lshl_add_u64 v[8:9], v[24:25], 0, v[10:11]
	v_lshl_add_u64 v[4:5], v[22:23], 0, v[10:11]
	v_add3_u32 v0, v151, v10, v0
	v_lshlrev_b32_e32 v10, 12, v28
	v_lshl_add_u64 v[12:13], v[6:7], 0, v[12:13]
	v_lshl_add_u64 v[2:3], v[2:3], 0, v[98:99]
	v_lshl_add_u64 v[18:19], v[8:9], 0, v[10:11]
	global_load_dwordx2 v[22:23], v[12:13], off offset:64
	v_lshl_add_u64 v[24:25], v[4:5], 0, v[10:11]
	ds_read_b128 v[10:13], v0
	global_load_dwordx4 v[14:17], v[2:3], off
	s_nop 0
	global_load_dwordx4 v[18:21], v[18:19], off offset:128
	s_waitcnt vmcnt(2)
	v_and_b32_e32 v27, 0xffff0000, v22
	v_lshlrev_b32_e32 v26, 16, v22
	s_waitcnt vmcnt(0)
	v_pk_add_f32 v[18:19], v[18:19], v[26:27]
	s_waitcnt lgkmcnt(0)
	v_pk_fma_f32 v[10:11], v[10:11], v[14:15], v[18:19]
	v_and_b32_e32 v15, 0xffff0000, v23
	v_lshlrev_b32_e32 v14, 16, v23
	v_pk_add_f32 v[14:15], v[20:21], v[14:15]
	s_nop 0
	v_pk_fma_f32 v[12:13], v[12:13], v[16:17], v[14:15]
	global_store_dwordx4 v[24:25], v[10:13], off offset:128
	s_nop 1
	v_or_b32_e32 v12, 8, v28
	v_lshlrev_b32_e32 v10, 12, v12
	v_lshlrev_b32_e32 v12, 11, v12
	v_mov_b32_e32 v13, v1
	v_mov_b32_e32 v11, v1
	v_lshl_add_u64 v[12:13], v[6:7], 0, v[12:13]
	v_lshl_add_u64 v[18:19], v[8:9], 0, v[10:11]
	global_load_dwordx2 v[22:23], v[12:13], off offset:64
	v_lshl_add_u64 v[24:25], v[4:5], 0, v[10:11]
	ds_read_b128 v[10:13], v0 offset:1152
	global_load_dwordx4 v[14:17], v[2:3], off
	s_nop 0
	global_load_dwordx4 v[18:21], v[18:19], off offset:128
	s_waitcnt vmcnt(2)
	v_and_b32_e32 v27, 0xffff0000, v22
	v_lshlrev_b32_e32 v26, 16, v22
	s_waitcnt vmcnt(0)
	v_pk_add_f32 v[18:19], v[18:19], v[26:27]
	s_waitcnt lgkmcnt(0)
	v_pk_fma_f32 v[10:11], v[10:11], v[14:15], v[18:19]
	v_and_b32_e32 v15, 0xffff0000, v23
	v_lshlrev_b32_e32 v14, 16, v23
	v_pk_add_f32 v[14:15], v[20:21], v[14:15]
	s_nop 0
	v_pk_fma_f32 v[12:13], v[12:13], v[16:17], v[14:15]
	global_store_dwordx4 v[24:25], v[10:13], off offset:128
	s_nop 1
	v_or_b32_e32 v12, 16, v28
	v_lshlrev_b32_e32 v10, 12, v12
	v_lshlrev_b32_e32 v12, 11, v12
	v_mov_b32_e32 v13, v1
	v_mov_b32_e32 v11, v1
	v_lshl_add_u64 v[12:13], v[6:7], 0, v[12:13]
	v_lshl_add_u64 v[18:19], v[8:9], 0, v[10:11]
	global_load_dwordx2 v[22:23], v[12:13], off offset:64
	v_lshl_add_u64 v[24:25], v[4:5], 0, v[10:11]
	ds_read_b128 v[10:13], v0 offset:2304
	global_load_dwordx4 v[14:17], v[2:3], off
	s_nop 0
	global_load_dwordx4 v[18:21], v[18:19], off offset:128
	s_waitcnt vmcnt(2)
	v_and_b32_e32 v27, 0xffff0000, v22
	v_lshlrev_b32_e32 v26, 16, v22
	s_waitcnt vmcnt(0)
	v_pk_add_f32 v[18:19], v[18:19], v[26:27]
	s_waitcnt lgkmcnt(0)
	v_pk_fma_f32 v[10:11], v[10:11], v[14:15], v[18:19]
	v_and_b32_e32 v15, 0xffff0000, v23
	v_lshlrev_b32_e32 v14, 16, v23
	v_pk_add_f32 v[14:15], v[20:21], v[14:15]
	s_nop 0
	v_pk_fma_f32 v[12:13], v[12:13], v[16:17], v[14:15]
	v_or_b32_e32 v14, 24, v28
	global_store_dwordx4 v[24:25], v[10:13], off offset:128
	s_nop 1
	v_lshlrev_b32_e32 v10, 12, v14
	v_mov_b32_e32 v11, v1
	v_lshl_add_u64 v[12:13], v[8:9], 0, v[10:11]
	v_lshlrev_b32_e32 v8, 11, v14
	v_mov_b32_e32 v9, v1
	v_lshl_add_u64 v[6:7], v[6:7], 0, v[8:9]
	global_load_dwordx2 v[16:17], v[6:7], off offset:64
	v_lshl_add_u64 v[18:19], v[4:5], 0, v[10:11]
	ds_read_b128 v[4:7], v0 offset:3456
	global_load_dwordx4 v[8:11], v[2:3], off
	s_nop 0
	global_load_dwordx4 v[12:15], v[12:13], off offset:128
	s_waitcnt vmcnt(2)
	v_and_b32_e32 v3, 0xffff0000, v16
	v_lshlrev_b32_e32 v2, 16, v16
	s_waitcnt vmcnt(0)
	v_pk_add_f32 v[2:3], v[12:13], v[2:3]
	s_waitcnt lgkmcnt(0)
	v_pk_fma_f32 v[2:3], v[4:5], v[8:9], v[2:3]
	v_and_b32_e32 v5, 0xffff0000, v17
	v_lshlrev_b32_e32 v4, 16, v17
	v_pk_add_f32 v[4:5], v[14:15], v[4:5]
	s_nop 0
	v_pk_fma_f32 v[4:5], v[6:7], v[10:11], v[4:5]
	global_store_dwordx4 v[18:19], v[2:5], off offset:128
	s_add_i32 s7, s7, s6
	s_cmpk_gt_i32 s7, 0x1ff
	v_readlane_b32 s64, v254, 55
	v_readlane_b32 s38, v254, 57
	v_readlane_b32 s42, v254, 59
	s_cselect_b64 s[0:1], -1, 0
	v_readlane_b32 s65, v254, 56
	v_readlane_b32 s39, v254, 58
	v_readlane_b32 s43, v254, 60
	s_mov_b32 s51, s27
	s_movk_i32 s37, 0x1000
	s_movk_i32 s36, 0x1ff
	s_mov_b32 s47, 0x7f800000
	s_mov_b32 s49, 0x20000
	s_mov_b32 s46, 0x4081e0d3
	s_mov_b32 s48, 0xc09de9e6
	s_mov_b64 s[44:45], 0x800
	s_branch .LBB0_21

.LBB0_293:
	s_add_i32 s2, s11, s12
	s_cmpk_gt_i32 s2, 0xcb1
	s_mov_b64 s[0:1], -1
	s_cbranch_scc1 .LBB0_292
	s_mul_hi_i32 s0, s2, 0x51eb851f
	s_lshr_b32 s1, s0, 31
	s_ashr_i32 s0, s0, 6
	s_add_i32 s0, s0, s1
	s_lshl_b32 s1, s0, 3
	s_sub_i32 s3, 0x82, s1
	s_min_u32 s3, s3, 8
	v_cvt_f32_ubyte0_e32 v0, s3
	v_rcp_iflag_f32_e32 v0, v0
	s_sub_i32 s5, 0, s3
	s_mulk_i32 s0, 0xff38
	s_add_i32 s0, s0, s2
	v_mul_f32_e32 v0, 0x4f7ffffe, v0
	v_cvt_u32_f32_e32 v0, v0
	s_abs_i32 s4, s0
	s_ashr_i32 s2, s0, 31
	v_readlane_b32 s16, v251, 2
	v_readfirstlane_b32 s7, v0
	s_mul_i32 s5, s5, s7
	s_mul_hi_u32 s5, s7, s5
	s_add_i32 s7, s7, s5
	s_mul_hi_u32 s5, s4, s7
	s_mul_i32 s7, s5, s3
	s_sub_i32 s4, s4, s7
	s_add_i32 s7, s5, 1
	s_sub_i32 s8, s4, s3
	s_cmp_ge_u32 s4, s3
	s_cselect_b32 s5, s7, s5
	s_cselect_b32 s4, s8, s4
	s_add_i32 s7, s5, 1
	s_cmp_ge_u32 s4, s3
	s_cselect_b32 s4, s7, s5
	s_xor_b32 s4, s4, s2
	s_sub_i32 s4, s4, s2
	s_mul_i32 s2, s4, s3
	s_sub_i32 s0, s0, s2
	s_add_i32 s0, s0, s1
	s_lshl_b32 s0, s0, 8
	s_lshl_b32 s4, s4, 8
	s_ashr_i32 s1, s0, 31
	s_ashr_i32 s5, s4, 31
	s_lshl_b64 s[2:3], s[0:1], 11
	s_lshl_b64 s[8:9], s[4:5], 11
	v_readlane_b32 s28, v251, 14
	v_readlane_b32 s29, v251, 15
	s_add_u32 s14, s28, s2
	v_mov_b32_e32 v0, v142
	s_addc_u32 s15, s29, s3
	s_waitcnt vmcnt(63) expcnt(7) lgkmcnt(15)
	s_barrier
	v_readlane_b32 s17, v251, 3
	v_lshl_add_u64 v[2:3], v[0:1], 1, s[14:15]
	v_add_u32_e32 v0, 32, v143
	v_readlane_b32 s16, v251, 42
	v_readfirstlane_b32 s1, v0
	s_mov_b32 m0, s1
	v_mov_b32_e32 v0, v144
	global_load_lds_dwordx4 v[2:3], off
	v_readlane_b32 s17, v251, 43
	v_lshl_add_u64 v[2:3], v[0:1], 1, s[14:15]
	v_add_u32_e32 v0, 32, v145
	s_add_u32 s16, s16, s8
	v_readfirstlane_b32 s1, v0
	s_mov_b32 m0, s1
	v_mov_b32_e32 v0, v146
	global_load_lds_dwordx4 v[2:3], off
	s_addc_u32 s17, s17, s9
	v_lshl_add_u64 v[2:3], v[0:1], 1, s[14:15]
	v_add_u32_e32 v0, 32, v147
	v_readlane_b32 s5, v254, 3
	v_readfirstlane_b32 s1, v0
	s_mov_b32 m0, s1
	v_mov_b32_e32 v0, v148
	global_load_lds_dwordx4 v[2:3], off
	s_mov_b32 s6, 0
	v_lshl_add_u64 v[2:3], v[0:1], 1, s[14:15]
	v_add_u32_e32 v0, 32, v149
	v_readlane_b32 s18, v251, 4
	v_readfirstlane_b32 s1, v0
	s_mov_b32 m0, s1
	v_mov_b32_e32 v0, v142
	global_load_lds_dwordx4 v[2:3], off
	v_readlane_b32 s19, v251, 5
	v_lshl_add_u64 v[2:3], v[0:1], 1, s[16:17]
	v_add_u32_e32 v0, s5, v143
	v_readlane_b32 s20, v251, 6
	v_readfirstlane_b32 s1, v0
	s_mov_b32 m0, s1
	v_mov_b32_e32 v0, v144
	global_load_lds_dwordx4 v[2:3], off
	v_readlane_b32 s21, v251, 7
	v_lshl_add_u64 v[2:3], v[0:1], 1, s[16:17]
	v_add_u32_e32 v0, s5, v145
	v_readlane_b32 s22, v251, 8
	v_readfirstlane_b32 s1, v0
	s_mov_b32 m0, s1
	v_mov_b32_e32 v0, v146
	global_load_lds_dwordx4 v[2:3], off
	v_readlane_b32 s23, v251, 9
	v_lshl_add_u64 v[2:3], v[0:1], 1, s[16:17]
	v_add_u32_e32 v0, s5, v147
	v_readlane_b32 s24, v251, 10
	v_readfirstlane_b32 s1, v0
	s_mov_b32 m0, s1
	v_mov_b32_e32 v0, v148
	global_load_lds_dwordx4 v[2:3], off
	v_readlane_b32 s25, v251, 11
	v_lshl_add_u64 v[2:3], v[0:1], 1, s[16:17]
	v_add_u32_e32 v0, s5, v149
	v_readlane_b32 s26, v251, 12
	v_readfirstlane_b32 s1, v0
	s_mov_b32 m0, s1
	v_readlane_b32 s1, v253, 29
	global_load_lds_dwordx4 v[2:3], off
	s_add_u32 s1, s1, s2
	v_readlane_b32 s2, v253, 30
	s_waitcnt vmcnt(0)
	s_addc_u32 s5, s2, s3
	v_readlane_b32 s2, v253, 31
	s_add_u32 s7, s2, s8
	v_readlane_b32 s2, v253, 32
	v_mov_b32_e32 v2, 0
	s_addc_u32 s8, s2, s9
	s_mov_b64 s[2:3], 0
	v_mov_b32_e32 v3, v2
	v_mov_b32_e32 v4, v2
	v_mov_b32_e32 v5, v2
	v_mov_b32_e32 v6, v2
	v_mov_b32_e32 v7, v2
	v_mov_b32_e32 v8, v2
	v_mov_b32_e32 v9, v2
	v_mov_b32_e32 v10, v2
	v_mov_b32_e32 v11, v2
	v_mov_b32_e32 v12, v2
	v_mov_b32_e32 v13, v2
	s_waitcnt vmcnt(0)
	v_mov_b32_e32 v14, v2
	v_mov_b32_e32 v15, v2
	v_mov_b32_e32 v16, v2
	v_mov_b32_e32 v17, v2
	v_mov_b32_e32 v18, v2
	v_mov_b32_e32 v19, v2
	v_mov_b32_e32 v20, v2
	v_mov_b32_e32 v21, v2
	v_mov_b32_e32 v22, v2
	v_mov_b32_e32 v23, v2
	v_mov_b32_e32 v24, v2
	v_mov_b32_e32 v25, v2
	v_mov_b32_e32 v26, v2
	v_mov_b32_e32 v27, v2
	v_mov_b32_e32 v28, v2
	v_mov_b32_e32 v29, v2
	v_mov_b32_e32 v30, v2
	v_mov_b32_e32 v31, v2
	v_mov_b32_e32 v32, v2
	v_mov_b32_e32 v33, v2
	v_mov_b32_e32 v34, v2
	v_mov_b32_e32 v35, v2
	v_mov_b32_e32 v36, v2
	v_mov_b32_e32 v37, v2
	v_mov_b32_e32 v38, v2
	v_mov_b32_e32 v39, v2
	v_mov_b32_e32 v40, v2
	v_mov_b32_e32 v41, v2
	v_mov_b32_e32 v42, v2
	v_mov_b32_e32 v43, v2
	v_mov_b32_e32 v44, v2
	v_mov_b32_e32 v45, v2
	v_mov_b32_e32 v46, v2
	v_mov_b32_e32 v47, v2
	v_mov_b32_e32 v48, v2
	v_mov_b32_e32 v49, v2
	v_mov_b32_e32 v50, v2
	v_mov_b32_e32 v51, v2
	v_mov_b32_e32 v52, v2
	v_mov_b32_e32 v53, v2
	v_mov_b32_e32 v54, v2
	v_mov_b32_e32 v55, v2
	v_mov_b32_e32 v56, v2
	v_mov_b32_e32 v57, v2
	v_mov_b32_e32 v58, v2
	v_mov_b32_e32 v59, v2
	v_mov_b32_e32 v60, v2
	v_mov_b32_e32 v61, v2
	v_mov_b32_e32 v62, v2
	v_mov_b32_e32 v63, v2
	v_mov_b32_e32 v64, v2
	v_mov_b32_e32 v65, v2
	v_mov_b32_e32 v66, v2
	v_mov_b32_e32 v67, v2
	v_mov_b32_e32 v68, v2
	v_mov_b32_e32 v69, v2
	v_mov_b32_e32 v70, v2
	v_mov_b32_e32 v71, v2
	v_mov_b32_e32 v72, v2
	v_mov_b32_e32 v73, v2
	v_mov_b32_e32 v74, v2
	v_mov_b32_e32 v75, v2
	v_mov_b32_e32 v76, v2
	v_mov_b32_e32 v77, v2
	v_mov_b32_e32 v78, v2
	v_mov_b32_e32 v79, v2
	v_mov_b32_e32 v80, v2
	v_mov_b32_e32 v81, v2
	v_mov_b32_e32 v82, v2
	v_mov_b32_e32 v83, v2
	v_mov_b32_e32 v84, v2
	v_mov_b32_e32 v85, v2
	v_mov_b32_e32 v86, v2
	v_mov_b32_e32 v87, v2
	v_mov_b32_e32 v88, v2
	v_mov_b32_e32 v89, v2
	v_mov_b32_e32 v90, v2
	v_mov_b32_e32 v91, v2
	v_mov_b32_e32 v92, v2
	v_mov_b32_e32 v93, v2
	v_mov_b32_e32 v94, v2
	v_mov_b32_e32 v95, v2
	v_mov_b32_e32 v96, v2
	v_mov_b32_e32 v97, v2
	v_mov_b32_e32 v98, v2
	v_mov_b32_e32 v99, v2
	v_mov_b32_e32 v100, v2
	v_mov_b32_e32 v101, v2
	v_mov_b32_e32 v102, v2
	v_mov_b32_e32 v103, v2
	v_mov_b32_e32 v104, v2
	v_mov_b32_e32 v105, v2
	v_mov_b32_e32 v106, v2
	v_mov_b32_e32 v107, v2
	v_mov_b32_e32 v108, v2
	v_mov_b32_e32 v109, v2
	v_mov_b32_e32 v110, v2
	v_mov_b32_e32 v111, v2
	v_mov_b32_e32 v112, v2
	v_mov_b32_e32 v113, v2
	v_mov_b32_e32 v114, v2
	v_mov_b32_e32 v115, v2
	v_mov_b32_e32 v116, v2
	v_mov_b32_e32 v117, v2
	v_mov_b32_e32 v118, v2
	v_mov_b32_e32 v119, v2
	v_mov_b32_e32 v120, v2
	v_mov_b32_e32 v121, v2
	v_mov_b32_e32 v122, v2
	v_mov_b32_e32 v123, v2
	v_mov_b32_e32 v124, v2
	v_mov_b32_e32 v125, v2
	v_mov_b32_e32 v126, v2
	v_mov_b32_e32 v127, v2
	v_mov_b32_e32 v128, v2
	v_mov_b32_e32 v129, v2
	v_readlane_b32 s27, v251, 13
	v_readlane_b32 s30, v251, 16
	v_readlane_b32 s31, v251, 17
	s_waitcnt lgkmcnt(0)
	s_barrier
	v_lshlrev_b32_e32 v159, 1, v142
	v_readfirstlane_b32 s9, v143
	v_add_u32_e32 v177, v150, v152
	v_add_u32_e32 v207, v151, v152
	v_add_u32_e32 v204, v150, v156
	v_add_u32_e32 v208, v151, v156
	v_add_u32_e32 v205, v150, v157
	v_add_u32_e32 v209, v151, v157
	v_add_u32_e32 v206, v150, v158
	v_add_u32_e32 v210, v151, v158
	s_mov_b32 s6, 7
	s_add_u32 m0, s9, 0x8020
	s_add_u32 s14, s1, s2
	s_addc_u32 s15, s5, s3
	global_load_lds_dwordx4 v159, s[14:15]
	s_add_u32 m0, s9, 0xa020
	s_add_u32 s14, s14, 0x20000
	s_addc_u32 s15, s15, 0
	global_load_lds_dwordx4 v159, s[14:15]
	s_add_u32 m0, s9, 0xc020
	s_add_u32 s14, s14, 0x20000
	s_addc_u32 s15, s15, 0
	global_load_lds_dwordx4 v159, s[14:15]
	s_add_u32 m0, s9, 0xe020
	s_add_u32 s14, s14, 0x20000
	s_addc_u32 s15, s15, 0
	global_load_lds_dwordx4 v159, s[14:15]
	s_add_u32 m0, s9, 0x18020
	s_add_u32 s14, s7, s2
	s_addc_u32 s15, s8, s3
	global_load_lds_dwordx4 v159, s[14:15]
	ds_read_b128 v[130:133], v177 offset:0
	ds_read_b128 v[164:167], v207 offset:0
	ds_read_b128 v[168:171], v207 offset:4096
	ds_read_b128 v[134:137], v177 offset:4096
	ds_read_b128 v[138:141], v177 offset:8192
	ds_read_b128 v[160:163], v177 offset:12288
.Lg295_loop:
	s_waitcnt lgkmcnt(4)
	v_mfma_f32_32x32x16_bf16 v[114:129], v[130:133], v[164:167], v[114:129]
	ds_read_b128 v[172:175], v204 offset:0
	s_waitcnt lgkmcnt(4)
	v_mfma_f32_32x32x16_bf16 v[98:113], v[130:133], v[168:171], v[98:113]
	ds_read_b128 v[192:195], v208 offset:0
	s_add_u32 m0, s9, 0x1a020
	s_add_u32 s14, s14, 0x20000
	s_addc_u32 s15, s15, 0
	global_load_lds_dwordx4 v159, s[14:15]
	s_waitcnt lgkmcnt(4)
	v_mfma_f32_32x32x16_bf16 v[82:97], v[134:137], v[164:167], v[82:97]
	ds_read_b128 v[200:203], v208 offset:4096
	v_mfma_f32_32x32x16_bf16 v[66:81], v[134:137], v[168:171], v[66:81]
	ds_read_b128 v[180:183], v204 offset:4096
	s_add_u32 m0, s9, 0x1c020
	s_add_u32 s14, s14, 0x20000
	s_addc_u32 s15, s15, 0
	global_load_lds_dwordx4 v159, s[14:15]
	s_waitcnt lgkmcnt(5)
	v_mfma_f32_32x32x16_bf16 v[50:65], v[138:141], v[164:167], v[50:65]
	ds_read_b128 v[184:187], v204 offset:8192
	v_mfma_f32_32x32x16_bf16 v[34:49], v[138:141], v[168:171], v[34:49]
	ds_read_b128 v[188:191], v204 offset:12288
	s_add_u32 m0, s9, 0x1e020
	s_add_u32 s14, s14, 0x20000
	s_addc_u32 s15, s15, 0
	global_load_lds_dwordx4 v159, s[14:15]
	s_add_u32 s2, s2, 0x80
	s_addc_u32 s3, s3, 0
	s_waitcnt lgkmcnt(6)
	v_mfma_f32_32x32x16_bf16 v[18:33], v[160:163], v[164:167], v[18:33]
	v_mfma_f32_32x32x16_bf16 v[2:17], v[160:163], v[168:171], v[2:17]
	s_waitcnt lgkmcnt(4)
	v_mfma_f32_32x32x16_bf16 v[114:129], v[172:175], v[192:195], v[114:129]
	ds_read_b128 v[130:133], v205 offset:0
	s_waitcnt lgkmcnt(4)
	v_mfma_f32_32x32x16_bf16 v[98:113], v[172:175], v[200:203], v[98:113]
	ds_read_b128 v[164:167], v209 offset:0
	s_waitcnt lgkmcnt(4)
	v_mfma_f32_32x32x16_bf16 v[82:97], v[180:183], v[192:195], v[82:97]
	ds_read_b128 v[168:171], v209 offset:4096
	v_mfma_f32_32x32x16_bf16 v[66:81], v[180:183], v[200:203], v[66:81]
	ds_read_b128 v[134:137], v205 offset:4096
	s_waitcnt lgkmcnt(5)
	v_mfma_f32_32x32x16_bf16 v[50:65], v[184:187], v[192:195], v[50:65]
	ds_read_b128 v[138:141], v205 offset:8192
	v_mfma_f32_32x32x16_bf16 v[34:49], v[184:187], v[200:203], v[34:49]
	ds_read_b128 v[160:163], v205 offset:12288
	s_waitcnt lgkmcnt(6)
	v_mfma_f32_32x32x16_bf16 v[18:33], v[188:191], v[192:195], v[18:33]
	v_mfma_f32_32x32x16_bf16 v[2:17], v[188:191], v[200:203], v[2:17]
	s_waitcnt lgkmcnt(4)
	v_mfma_f32_32x32x16_bf16 v[114:129], v[130:133], v[164:167], v[114:129]
	ds_read_b128 v[172:175], v206 offset:0
	ds_read_b128 v[192:195], v210 offset:0
	s_waitcnt lgkmcnt(5)
	v_mfma_f32_32x32x16_bf16 v[98:113], v[130:133], v[168:171], v[98:113]
	ds_read_b128 v[200:203], v210 offset:4096
	ds_read_b128 v[180:183], v206 offset:4096
	s_waitcnt lgkmcnt(6)
	v_mfma_f32_32x32x16_bf16 v[82:97], v[134:137], v[164:167], v[82:97]
	ds_read_b128 v[184:187], v206 offset:8192
	ds_read_b128 v[188:191], v206 offset:12288
	v_mfma_f32_32x32x16_bf16 v[66:81], v[134:137], v[168:171], v[66:81]
	s_waitcnt lgkmcnt(7)
	v_mfma_f32_32x32x16_bf16 v[50:65], v[138:141], v[164:167], v[50:65]
	v_mfma_f32_32x32x16_bf16 v[34:49], v[138:141], v[168:171], v[34:49]
	s_waitcnt lgkmcnt(6)
	v_mfma_f32_32x32x16_bf16 v[18:33], v[160:163], v[164:167], v[18:33]
	v_mfma_f32_32x32x16_bf16 v[2:17], v[160:163], v[168:171], v[2:17]
	s_waitcnt vmcnt(0) lgkmcnt(0)
	s_barrier
	v_mfma_f32_32x32x16_bf16 v[114:129], v[172:175], v[192:195], v[114:129]
	ds_read_b128 v[130:133], v177 offset:32768
	s_add_u32 m0, s9, 0x20
	s_add_u32 s14, s1, s2
	s_addc_u32 s15, s5, s3
	global_load_lds_dwordx4 v159, s[14:15]
	v_mfma_f32_32x32x16_bf16 v[98:113], v[172:175], v[200:203], v[98:113]
	ds_read_b128 v[164:167], v207 offset:32768
	s_add_u32 m0, s9, 0x2020
	s_add_u32 s14, s14, 0x20000
	s_addc_u32 s15, s15, 0
	global_load_lds_dwordx4 v159, s[14:15]
	v_mfma_f32_32x32x16_bf16 v[82:97], v[180:183], v[192:195], v[82:97]
	ds_read_b128 v[168:171], v207 offset:36864
	s_add_u32 m0, s9, 0x4020
	s_add_u32 s14, s14, 0x20000
	s_addc_u32 s15, s15, 0
	global_load_lds_dwordx4 v159, s[14:15]
	v_mfma_f32_32x32x16_bf16 v[66:81], v[180:183], v[200:203], v[66:81]
	ds_read_b128 v[134:137], v177 offset:36864
	s_add_u32 m0, s9, 0x6020
	s_add_u32 s14, s14, 0x20000
	s_addc_u32 s15, s15, 0
	global_load_lds_dwordx4 v159, s[14:15]
	v_mfma_f32_32x32x16_bf16 v[50:65], v[184:187], v[192:195], v[50:65]
	ds_read_b128 v[138:141], v177 offset:40960
	s_add_u32 m0, s9, 0x10020
	s_add_u32 s14, s7, s2
	s_addc_u32 s15, s8, s3
	global_load_lds_dwordx4 v159, s[14:15]
	v_mfma_f32_32x32x16_bf16 v[34:49], v[184:187], v[200:203], v[34:49]
	ds_read_b128 v[160:163], v177 offset:45056
	v_mfma_f32_32x32x16_bf16 v[18:33], v[188:191], v[192:195], v[18:33]
	v_mfma_f32_32x32x16_bf16 v[2:17], v[188:191], v[200:203], v[2:17]
	s_waitcnt lgkmcnt(4)
	v_mfma_f32_32x32x16_bf16 v[114:129], v[130:133], v[164:167], v[114:129]
	ds_read_b128 v[172:175], v204 offset:32768
	s_waitcnt lgkmcnt(4)
	v_mfma_f32_32x32x16_bf16 v[98:113], v[130:133], v[168:171], v[98:113]
	ds_read_b128 v[192:195], v208 offset:32768
	s_add_u32 m0, s9, 0x12020
	s_add_u32 s14, s14, 0x20000
	s_addc_u32 s15, s15, 0
	global_load_lds_dwordx4 v159, s[14:15]
	s_waitcnt lgkmcnt(4)
	v_mfma_f32_32x32x16_bf16 v[82:97], v[134:137], v[164:167], v[82:97]
	ds_read_b128 v[200:203], v208 offset:36864
	v_mfma_f32_32x32x16_bf16 v[66:81], v[134:137], v[168:171], v[66:81]
	ds_read_b128 v[180:183], v204 offset:36864
	s_add_u32 m0, s9, 0x14020
	s_add_u32 s14, s14, 0x20000
	s_addc_u32 s15, s15, 0
	global_load_lds_dwordx4 v159, s[14:15]
	s_waitcnt lgkmcnt(5)
	v_mfma_f32_32x32x16_bf16 v[50:65], v[138:141], v[164:167], v[50:65]
	ds_read_b128 v[184:187], v204 offset:40960
	v_mfma_f32_32x32x16_bf16 v[34:49], v[138:141], v[168:171], v[34:49]
	ds_read_b128 v[188:191], v204 offset:45056
	s_add_u32 m0, s9, 0x16020
	s_add_u32 s14, s14, 0x20000
	s_addc_u32 s15, s15, 0
	global_load_lds_dwordx4 v159, s[14:15]
	s_add_u32 s2, s2, 0x80
	s_addc_u32 s3, s3, 0
	s_waitcnt lgkmcnt(6)
	v_mfma_f32_32x32x16_bf16 v[18:33], v[160:163], v[164:167], v[18:33]
	v_mfma_f32_32x32x16_bf16 v[2:17], v[160:163], v[168:171], v[2:17]
	s_waitcnt lgkmcnt(4)
	v_mfma_f32_32x32x16_bf16 v[114:129], v[172:175], v[192:195], v[114:129]
	ds_read_b128 v[130:133], v205 offset:32768
	s_waitcnt lgkmcnt(4)
	v_mfma_f32_32x32x16_bf16 v[98:113], v[172:175], v[200:203], v[98:113]
	ds_read_b128 v[164:167], v209 offset:32768
	s_waitcnt lgkmcnt(4)
	v_mfma_f32_32x32x16_bf16 v[82:97], v[180:183], v[192:195], v[82:97]
	ds_read_b128 v[168:171], v209 offset:36864
	v_mfma_f32_32x32x16_bf16 v[66:81], v[180:183], v[200:203], v[66:81]
	ds_read_b128 v[134:137], v205 offset:36864
	s_waitcnt lgkmcnt(5)
	v_mfma_f32_32x32x16_bf16 v[50:65], v[184:187], v[192:195], v[50:65]
	ds_read_b128 v[138:141], v205 offset:40960
	v_mfma_f32_32x32x16_bf16 v[34:49], v[184:187], v[200:203], v[34:49]
	ds_read_b128 v[160:163], v205 offset:45056
	s_waitcnt lgkmcnt(6)
	v_mfma_f32_32x32x16_bf16 v[18:33], v[188:191], v[192:195], v[18:33]
	v_mfma_f32_32x32x16_bf16 v[2:17], v[188:191], v[200:203], v[2:17]
	s_waitcnt lgkmcnt(4)
	v_mfma_f32_32x32x16_bf16 v[114:129], v[130:133], v[164:167], v[114:129]
	ds_read_b128 v[172:175], v206 offset:32768
	ds_read_b128 v[192:195], v210 offset:32768
	s_waitcnt lgkmcnt(5)
	v_mfma_f32_32x32x16_bf16 v[98:113], v[130:133], v[168:171], v[98:113]
	ds_read_b128 v[200:203], v210 offset:36864
	ds_read_b128 v[180:183], v206 offset:36864
	s_waitcnt lgkmcnt(6)
	v_mfma_f32_32x32x16_bf16 v[82:97], v[134:137], v[164:167], v[82:97]
	ds_read_b128 v[184:187], v206 offset:40960
	ds_read_b128 v[188:191], v206 offset:45056
	v_mfma_f32_32x32x16_bf16 v[66:81], v[134:137], v[168:171], v[66:81]
	s_waitcnt lgkmcnt(7)
	v_mfma_f32_32x32x16_bf16 v[50:65], v[138:141], v[164:167], v[50:65]
	v_mfma_f32_32x32x16_bf16 v[34:49], v[138:141], v[168:171], v[34:49]
	s_waitcnt lgkmcnt(6)
	v_mfma_f32_32x32x16_bf16 v[18:33], v[160:163], v[164:167], v[18:33]
	v_mfma_f32_32x32x16_bf16 v[2:17], v[160:163], v[168:171], v[2:17]
	s_waitcnt vmcnt(0) lgkmcnt(0)
	s_barrier
	v_mfma_f32_32x32x16_bf16 v[114:129], v[172:175], v[192:195], v[114:129]
	ds_read_b128 v[130:133], v177 offset:0
	s_add_u32 m0, s9, 0x8020
	s_add_u32 s14, s1, s2
	s_addc_u32 s15, s5, s3
	global_load_lds_dwordx4 v159, s[14:15]
	v_mfma_f32_32x32x16_bf16 v[98:113], v[172:175], v[200:203], v[98:113]
	ds_read_b128 v[164:167], v207 offset:0
	s_add_u32 m0, s9, 0xa020
	s_add_u32 s14, s14, 0x20000
	s_addc_u32 s15, s15, 0
	global_load_lds_dwordx4 v159, s[14:15]
	v_mfma_f32_32x32x16_bf16 v[82:97], v[180:183], v[192:195], v[82:97]
	ds_read_b128 v[168:171], v207 offset:4096
	s_add_u32 m0, s9, 0xc020
	s_add_u32 s14, s14, 0x20000
	s_addc_u32 s15, s15, 0
	global_load_lds_dwordx4 v159, s[14:15]
	v_mfma_f32_32x32x16_bf16 v[66:81], v[180:183], v[200:203], v[66:81]
	ds_read_b128 v[134:137], v177 offset:4096
	s_add_u32 m0, s9, 0xe020
	s_add_u32 s14, s14, 0x20000
	s_addc_u32 s15, s15, 0
	global_load_lds_dwordx4 v159, s[14:15]
	v_mfma_f32_32x32x16_bf16 v[50:65], v[184:187], v[192:195], v[50:65]
	ds_read_b128 v[138:141], v177 offset:8192
	s_add_u32 m0, s9, 0x18020
	s_add_u32 s14, s7, s2
	s_addc_u32 s15, s8, s3
	global_load_lds_dwordx4 v159, s[14:15]
	v_mfma_f32_32x32x16_bf16 v[34:49], v[184:187], v[200:203], v[34:49]
	ds_read_b128 v[160:163], v177 offset:12288
	v_mfma_f32_32x32x16_bf16 v[18:33], v[188:191], v[192:195], v[18:33]
	v_mfma_f32_32x32x16_bf16 v[2:17], v[188:191], v[200:203], v[2:17]
	s_sub_u32 s6, s6, 1
	s_cmp_lg_u32 s6, 0
	s_cbranch_scc1 .Lg295_loop
	s_waitcnt lgkmcnt(4)
	v_mfma_f32_32x32x16_bf16 v[114:129], v[130:133], v[164:167], v[114:129]
	ds_read_b128 v[172:175], v204 offset:0
	s_waitcnt lgkmcnt(4)
	v_mfma_f32_32x32x16_bf16 v[98:113], v[130:133], v[168:171], v[98:113]
	ds_read_b128 v[192:195], v208 offset:0
	s_add_u32 m0, s9, 0x1a020
	s_add_u32 s14, s14, 0x20000
	s_addc_u32 s15, s15, 0
	global_load_lds_dwordx4 v159, s[14:15]
	s_waitcnt lgkmcnt(4)
	v_mfma_f32_32x32x16_bf16 v[82:97], v[134:137], v[164:167], v[82:97]
	ds_read_b128 v[200:203], v208 offset:4096
	v_mfma_f32_32x32x16_bf16 v[66:81], v[134:137], v[168:171], v[66:81]
	ds_read_b128 v[180:183], v204 offset:4096
	s_add_u32 m0, s9, 0x1c020
	s_add_u32 s14, s14, 0x20000
	s_addc_u32 s15, s15, 0
	global_load_lds_dwordx4 v159, s[14:15]
	s_waitcnt lgkmcnt(5)
	v_mfma_f32_32x32x16_bf16 v[50:65], v[138:141], v[164:167], v[50:65]
	ds_read_b128 v[184:187], v204 offset:8192
	v_mfma_f32_32x32x16_bf16 v[34:49], v[138:141], v[168:171], v[34:49]
	ds_read_b128 v[188:191], v204 offset:12288
	s_add_u32 m0, s9, 0x1e020
	s_add_u32 s14, s14, 0x20000
	s_addc_u32 s15, s15, 0
	global_load_lds_dwordx4 v159, s[14:15]
	s_add_u32 s2, s2, 0x80
	s_addc_u32 s3, s3, 0
	s_waitcnt lgkmcnt(6)
	v_mfma_f32_32x32x16_bf16 v[18:33], v[160:163], v[164:167], v[18:33]
	v_mfma_f32_32x32x16_bf16 v[2:17], v[160:163], v[168:171], v[2:17]
	s_waitcnt lgkmcnt(4)
	v_mfma_f32_32x32x16_bf16 v[114:129], v[172:175], v[192:195], v[114:129]
	ds_read_b128 v[130:133], v205 offset:0
	s_waitcnt lgkmcnt(4)
	v_mfma_f32_32x32x16_bf16 v[98:113], v[172:175], v[200:203], v[98:113]
	ds_read_b128 v[164:167], v209 offset:0
	s_waitcnt lgkmcnt(4)
	v_mfma_f32_32x32x16_bf16 v[82:97], v[180:183], v[192:195], v[82:97]
	ds_read_b128 v[168:171], v209 offset:4096
	v_mfma_f32_32x32x16_bf16 v[66:81], v[180:183], v[200:203], v[66:81]
	ds_read_b128 v[134:137], v205 offset:4096
	s_waitcnt lgkmcnt(5)
	v_mfma_f32_32x32x16_bf16 v[50:65], v[184:187], v[192:195], v[50:65]
	ds_read_b128 v[138:141], v205 offset:8192
	v_mfma_f32_32x32x16_bf16 v[34:49], v[184:187], v[200:203], v[34:49]
	ds_read_b128 v[160:163], v205 offset:12288
	s_waitcnt lgkmcnt(6)
	v_mfma_f32_32x32x16_bf16 v[18:33], v[188:191], v[192:195], v[18:33]
	v_mfma_f32_32x32x16_bf16 v[2:17], v[188:191], v[200:203], v[2:17]
	s_waitcnt lgkmcnt(4)
	v_mfma_f32_32x32x16_bf16 v[114:129], v[130:133], v[164:167], v[114:129]
	ds_read_b128 v[172:175], v206 offset:0
	ds_read_b128 v[192:195], v210 offset:0
	s_waitcnt lgkmcnt(5)
	v_mfma_f32_32x32x16_bf16 v[98:113], v[130:133], v[168:171], v[98:113]
	ds_read_b128 v[200:203], v210 offset:4096
	ds_read_b128 v[180:183], v206 offset:4096
	s_waitcnt lgkmcnt(6)
	v_mfma_f32_32x32x16_bf16 v[82:97], v[134:137], v[164:167], v[82:97]
	ds_read_b128 v[184:187], v206 offset:8192
	ds_read_b128 v[188:191], v206 offset:12288
	v_mfma_f32_32x32x16_bf16 v[66:81], v[134:137], v[168:171], v[66:81]
	s_waitcnt lgkmcnt(7)
	v_mfma_f32_32x32x16_bf16 v[50:65], v[138:141], v[164:167], v[50:65]
	v_mfma_f32_32x32x16_bf16 v[34:49], v[138:141], v[168:171], v[34:49]
	s_waitcnt lgkmcnt(6)
	v_mfma_f32_32x32x16_bf16 v[18:33], v[160:163], v[164:167], v[18:33]
	v_mfma_f32_32x32x16_bf16 v[2:17], v[160:163], v[168:171], v[2:17]
	s_waitcnt vmcnt(0) lgkmcnt(0)
	s_barrier
	v_mfma_f32_32x32x16_bf16 v[114:129], v[172:175], v[192:195], v[114:129]
	ds_read_b128 v[130:133], v177 offset:32768
	v_mfma_f32_32x32x16_bf16 v[98:113], v[172:175], v[200:203], v[98:113]
	ds_read_b128 v[164:167], v207 offset:32768
	v_mfma_f32_32x32x16_bf16 v[82:97], v[180:183], v[192:195], v[82:97]
	ds_read_b128 v[168:171], v207 offset:36864
	v_mfma_f32_32x32x16_bf16 v[66:81], v[180:183], v[200:203], v[66:81]
	ds_read_b128 v[134:137], v177 offset:36864
	v_mfma_f32_32x32x16_bf16 v[50:65], v[184:187], v[192:195], v[50:65]
	ds_read_b128 v[138:141], v177 offset:40960
	v_mfma_f32_32x32x16_bf16 v[34:49], v[184:187], v[200:203], v[34:49]
	ds_read_b128 v[160:163], v177 offset:45056
	v_mfma_f32_32x32x16_bf16 v[18:33], v[188:191], v[192:195], v[18:33]
	v_mfma_f32_32x32x16_bf16 v[2:17], v[188:191], v[200:203], v[2:17]
	s_waitcnt lgkmcnt(4)
	v_mfma_f32_32x32x16_bf16 v[114:129], v[130:133], v[164:167], v[114:129]
	ds_read_b128 v[172:175], v204 offset:32768
	s_waitcnt lgkmcnt(4)
	v_mfma_f32_32x32x16_bf16 v[98:113], v[130:133], v[168:171], v[98:113]
	ds_read_b128 v[192:195], v208 offset:32768
	s_waitcnt lgkmcnt(4)
	v_mfma_f32_32x32x16_bf16 v[82:97], v[134:137], v[164:167], v[82:97]
	ds_read_b128 v[200:203], v208 offset:36864
	v_mfma_f32_32x32x16_bf16 v[66:81], v[134:137], v[168:171], v[66:81]
	ds_read_b128 v[180:183], v204 offset:36864
	s_waitcnt lgkmcnt(5)
	v_mfma_f32_32x32x16_bf16 v[50:65], v[138:141], v[164:167], v[50:65]
	ds_read_b128 v[184:187], v204 offset:40960
	v_mfma_f32_32x32x16_bf16 v[34:49], v[138:141], v[168:171], v[34:49]
	ds_read_b128 v[188:191], v204 offset:45056
	s_waitcnt lgkmcnt(6)
	v_mfma_f32_32x32x16_bf16 v[18:33], v[160:163], v[164:167], v[18:33]
	v_mfma_f32_32x32x16_bf16 v[2:17], v[160:163], v[168:171], v[2:17]
	s_waitcnt lgkmcnt(4)
	v_mfma_f32_32x32x16_bf16 v[114:129], v[172:175], v[192:195], v[114:129]
	ds_read_b128 v[130:133], v205 offset:32768
	s_waitcnt lgkmcnt(4)
	v_mfma_f32_32x32x16_bf16 v[98:113], v[172:175], v[200:203], v[98:113]
	ds_read_b128 v[164:167], v209 offset:32768
	s_waitcnt lgkmcnt(4)
	v_mfma_f32_32x32x16_bf16 v[82:97], v[180:183], v[192:195], v[82:97]
	ds_read_b128 v[168:171], v209 offset:36864
	v_mfma_f32_32x32x16_bf16 v[66:81], v[180:183], v[200:203], v[66:81]
	ds_read_b128 v[134:137], v205 offset:36864
	s_waitcnt lgkmcnt(5)
	v_mfma_f32_32x32x16_bf16 v[50:65], v[184:187], v[192:195], v[50:65]
	ds_read_b128 v[138:141], v205 offset:40960
	v_mfma_f32_32x32x16_bf16 v[34:49], v[184:187], v[200:203], v[34:49]
	ds_read_b128 v[160:163], v205 offset:45056
	s_waitcnt lgkmcnt(6)
	v_mfma_f32_32x32x16_bf16 v[18:33], v[188:191], v[192:195], v[18:33]
	v_mfma_f32_32x32x16_bf16 v[2:17], v[188:191], v[200:203], v[2:17]
	s_waitcnt lgkmcnt(4)
	v_mfma_f32_32x32x16_bf16 v[114:129], v[130:133], v[164:167], v[114:129]
	ds_read_b128 v[172:175], v206 offset:32768
	ds_read_b128 v[192:195], v210 offset:32768
	s_waitcnt lgkmcnt(5)
	v_mfma_f32_32x32x16_bf16 v[98:113], v[130:133], v[168:171], v[98:113]
	ds_read_b128 v[200:203], v210 offset:36864
	ds_read_b128 v[180:183], v206 offset:36864
	s_waitcnt lgkmcnt(6)
	v_mfma_f32_32x32x16_bf16 v[82:97], v[134:137], v[164:167], v[82:97]
	ds_read_b128 v[184:187], v206 offset:40960
	ds_read_b128 v[188:191], v206 offset:45056
	v_mfma_f32_32x32x16_bf16 v[66:81], v[134:137], v[168:171], v[66:81]
	s_waitcnt lgkmcnt(7)
	v_mfma_f32_32x32x16_bf16 v[50:65], v[138:141], v[164:167], v[50:65]
	v_mfma_f32_32x32x16_bf16 v[34:49], v[138:141], v[168:171], v[34:49]
	s_waitcnt lgkmcnt(6)
	v_mfma_f32_32x32x16_bf16 v[18:33], v[160:163], v[164:167], v[18:33]
	v_mfma_f32_32x32x16_bf16 v[2:17], v[160:163], v[168:171], v[2:17]
	s_waitcnt vmcnt(0) lgkmcnt(0)
	s_barrier
	v_mfma_f32_32x32x16_bf16 v[114:129], v[172:175], v[192:195], v[114:129]
	v_mfma_f32_32x32x16_bf16 v[98:113], v[172:175], v[200:203], v[98:113]
	v_mfma_f32_32x32x16_bf16 v[82:97], v[180:183], v[192:195], v[82:97]
	v_mfma_f32_32x32x16_bf16 v[66:81], v[180:183], v[200:203], v[66:81]
	v_mfma_f32_32x32x16_bf16 v[50:65], v[184:187], v[192:195], v[50:65]
	v_mfma_f32_32x32x16_bf16 v[34:49], v[184:187], v[200:203], v[34:49]
	v_mfma_f32_32x32x16_bf16 v[18:33], v[188:191], v[192:195], v[18:33]
	v_mfma_f32_32x32x16_bf16 v[2:17], v[188:191], v[200:203], v[2:17]
	v_add_u32_e32 v159, s0, v153
	s_mov_b32 s0, 0x7e07e07f
	v_mul_hi_i32 v0, v159, s0
	v_lshrrev_b32_e32 v133, 31, v0
	v_ashrrev_i32_e32 v0, 13, v0
	v_add_u32_e32 v134, v0, v133
	v_mul_i32_i24_e32 v0, 0x4100, v134
	v_sub_u32_e32 v136, v159, v0
	s_movk_i32 s0, 0x100
	v_cmp_gt_i32_e64 s[56:57], s0, v136
	v_ashrrev_i32_e32 v137, 31, v136
	s_mov_b32 s0, 0xfff00000
	s_waitcnt vmcnt(0)
	v_ashrrev_i32_e32 v130, 7, v159
	v_lshlrev_b64 v[136:137], 12, v[136:137]
	s_mov_b32 s1, -1
	v_or_b32_e32 v132, s4, v154
	v_ashrrev_i32_e32 v131, 31, v130
	v_ashrrev_i32_e32 v135, 31, v134
	v_lshl_add_u64 v[136:137], v[136:137], 0, s[0:1]
	s_movk_i32 s0, 0x1840
	v_lshlrev_b64 v[130:131], 14, v[130:131]
	v_lshlrev_b64 v[134:135], 26, v[134:135]
	v_mov_b32_e32 v161, v179
	v_cmp_gt_i32_e64 s[54:55], s0, v132
	s_barrier
	s_and_saveexec_b64 s[2:3], s[54:55]
	s_cbranch_execz .LBB0_371
	s_movk_i32 s0, 0x7ff
	v_cmp_lt_i32_e32 vcc, s0, v132
	s_xor_b64 s[0:1], s[56:57], -1
	s_or_b64 s[0:1], vcc, s[0:1]
	s_and_b64 exec, exec, s[0:1]
	s_cbranch_execz .LBB0_371
	v_bfe_u32 v0, v161, 5, 1
	v_mul_u32_u24_e32 v0, 0x90, v0
	v_lshlrev_b32_e32 v133, 2, v161
	v_lshlrev_b32_e32 v0, 2, v0
	v_and_b32_e32 v133, 0x7c, v133
	v_add3_u32 v138, v155, v0, v133
	v_add3_u32 v0, v155, v133, v0
	ds_write_b32 v138, v114
	v_add_u32_e32 v114, 0x100, v0
	ds_write2_b32 v114, v117, v118 offset0:44 offset1:224
	v_add_u32_e32 v114, 0x400, v0
	ds_write2_b32 v114, v119, v120 offset0:68 offset1:104
	v_add_u32_e32 v114, 0x600, v0
	ds_write2_b32 v114, v121, v122 offset0:12 offset1:192
	v_add_u32_e32 v114, 0x800, v0
	ds_write2_b32 v114, v123, v124 offset0:100 offset1:136
	v_add_u32_e32 v114, 0xa00, v0
	ds_write2_b32 v114, v125, v126 offset0:44 offset1:224
	v_add_u32_e32 v114, 0xc00, v0
	ds_write2_b32 v0, v115, v116 offset0:36 offset1:72
	ds_write2_b32 v114, v127, v128 offset0:132 offset1:168
	ds_write_b32 v0, v129 offset:3888
	s_waitcnt lgkmcnt(0)
	v_and_b32_e32 v160, 63, v161
	s_and_saveexec_b64 s[0:1], vcc
	s_xor_b64 s[6:7], exec, s[0:1]
	s_cbranch_execz .LBB0_369
	s_cmpk_gt_u32 s4, 0x17ff
	s_mov_b64 s[0:1], -1
	s_cbranch_scc0 .LBB0_365
	v_readlane_b32 s16, v251, 2
	v_lshlrev_b32_e32 v116, 3, v161
	v_add_u32_e32 v0, 0xffffe800, v132
	v_readlane_b32 s17, v251, 3
	v_and_b32_e32 v116, 24, v116
	v_lshlrev_b32_e32 v140, 2, v116
	v_lshl_add_u64 v[114:115], v[0:1], 2, s[16:17]
	v_mov_b32_e32 v141, v1
	v_lshl_add_u64 v[138:139], v[114:115], 0, v[140:141]
	global_load_dwordx4 v[122:125], v[138:139], off
	global_load_dwordx4 v[114:117], v[138:139], off offset:16
	v_add_u32_e32 v162, v155, v140
	v_lshrrev_b32_e32 v133, 2, v160
	s_movk_i32 s0, 0x90
	v_mad_u32_u24 v118, v133, s0, v162
	ds_read_b128 v[126:129], v118
	ds_read_b128 v[118:121], v118 offset:16
	s_mov_b32 s0, 0xbfb8aa3b
	v_readlane_b32 s18, v251, 4
	v_readlane_b32 s19, v251, 5
	v_readlane_b32 s20, v251, 6
	v_readlane_b32 s21, v251, 7
	v_readlane_b32 s22, v251, 8
	v_readlane_b32 s23, v251, 9
	v_readlane_b32 s24, v251, 10
	v_readlane_b32 s25, v251, 11
	v_readlane_b32 s26, v251, 12
	v_readlane_b32 s27, v251, 13
	v_readlane_b32 s28, v251, 14
	v_readlane_b32 s29, v251, 15
	v_readlane_b32 s30, v251, 16
	v_readlane_b32 s31, v251, 17
	s_waitcnt vmcnt(1) lgkmcnt(1)
	v_add_f32_e32 v122, v126, v122
	v_mul_f32_e64 v126, |v122|, s0
	v_exp_f32_e32 v141, v126
	s_mov_b32 s0, 0x3c23d70a
	v_cmp_ngt_f32_e32 vcc, s0, v141
	s_and_saveexec_b64 s[0:1], vcc
	s_xor_b64 s[8:9], exec, s[0:1]
	s_cbranch_execz .LBB0_302
	v_add_f32_e32 v126, 1.0, v141
	s_mov_b32 s0, 0x800000
	v_cmp_gt_f32_e32 vcc, s0, v126
	s_mov_b32 s0, 0x3f317217
	s_nop 0
	v_cndmask_b32_e64 v141, 0, 32, vcc
	v_ldexp_f32 v126, v126, v141
	v_log_f32_e32 v126, v126
	s_nop 0
	v_mul_f32_e32 v141, 0x3f317217, v126
	v_fma_f32 v141, v126, s0, -v141
	v_fmac_f32_e32 v141, 0x3377d1cf, v126
	v_fmac_f32_e32 v141, 0x3f317217, v126
	v_cmp_lt_f32_e64 s[0:1], |v126|, s47
	s_nop 1
	v_cndmask_b32_e64 v126, v126, v141, s[0:1]
	v_cndmask_b32_e32 v141, 0, v238, vcc
	v_sub_f32_e32 v126, v126, v141

.LBB0_908:
	s_add_i32 s2, s7, s8
	s_cmpk_gt_i32 s2, 0x207
	s_mov_b64 s[0:1], -1
	s_cbranch_scc1 .LBB0_907
	s_ashr_i32 s0, s2, 31
	s_lshr_b32 s0, s0, 27
	s_add_i32 s0, s2, s0
	s_ashr_i32 s1, s0, 5
	s_lshl_b32 s1, s1, 3
	s_sub_i32 s3, 0x82, s1
	s_min_u32 s3, s3, 8
	v_cvt_f32_ubyte0_e32 v0, s3
	v_rcp_iflag_f32_e32 v0, v0
	s_sub_i32 s5, 0, s3
	s_andn2_b32 s0, s0, 31
	s_sub_i32 s0, s2, s0
	v_mul_f32_e32 v0, 0x4f7ffffe, v0
	v_cvt_u32_f32_e32 v0, v0
	s_abs_i32 s4, s0
	s_ashr_i32 s2, s0, 31
	s_waitcnt vmcnt(63) expcnt(7) lgkmcnt(15)
	v_readfirstlane_b32 s10, v0
	s_mul_i32 s5, s5, s10
	s_mul_hi_u32 s5, s10, s5
	s_add_i32 s10, s10, s5
	s_mul_hi_u32 s5, s4, s10
	s_mul_i32 s10, s5, s3
	s_sub_i32 s4, s4, s10
	s_add_i32 s10, s5, 1
	s_sub_i32 s11, s4, s3
	s_cmp_ge_u32 s4, s3
	s_cselect_b32 s5, s10, s5
	s_cselect_b32 s4, s11, s4
	s_add_i32 s10, s5, 1
	s_cmp_ge_u32 s4, s3
	s_cselect_b32 s4, s10, s5
	s_xor_b32 s4, s4, s2
	s_sub_i32 s2, s4, s2
	s_mul_i32 s3, s2, s3
	s_sub_i32 s0, s0, s3
	s_add_i32 s0, s0, s1
	s_lshl_b32 s0, s0, 8
	s_lshl_b32 s2, s2, 8
	s_ashr_i32 s1, s0, 31
	s_ashr_i32 s3, s2, 31
	s_lshl_b64 s[4:5], s[0:1], 11
	s_lshl_b64 s[10:11], s[2:3], 11
	s_add_u32 s12, s64, s4
	v_mov_b32_e32 v0, v132
	s_addc_u32 s13, s65, s5
	s_barrier
	v_readlane_b32 s14, v251, 50
	v_lshl_add_u64 v[2:3], v[0:1], 1, s[12:13]
	v_add_u32_e32 v0, 32, v133
	v_readlane_b32 s15, v251, 51
	v_readfirstlane_b32 s1, v0
	s_mov_b32 m0, s1
	v_mov_b32_e32 v0, v134
	global_load_lds_dwordx4 v[2:3], off
	s_add_u32 s14, s14, s10
	v_lshl_add_u64 v[2:3], v[0:1], 1, s[12:13]
	v_add_u32_e32 v0, 32, v135
	s_addc_u32 s15, s15, s11
	v_readfirstlane_b32 s1, v0
	s_mov_b32 m0, s1
	v_mov_b32_e32 v0, v136
	global_load_lds_dwordx4 v[2:3], off
	v_readlane_b32 s3, v254, 3
	v_lshl_add_u64 v[2:3], v[0:1], 1, s[12:13]
	v_add_u32_e32 v0, 32, v137
	s_mov_b32 s9, 0
	v_readfirstlane_b32 s1, v0
	s_mov_b32 m0, s1
	v_mov_b32_e32 v0, v138
	global_load_lds_dwordx4 v[2:3], off
	s_nop 0
	v_lshl_add_u64 v[2:3], v[0:1], 1, s[12:13]
	v_add_u32_e32 v0, 32, v139
	s_nop 0
	v_readfirstlane_b32 s1, v0
	s_mov_b32 m0, s1
	v_mov_b32_e32 v0, v132
	global_load_lds_dwordx4 v[2:3], off
	s_nop 0
	v_lshl_add_u64 v[2:3], v[0:1], 1, s[14:15]
	v_add_u32_e32 v0, s3, v133
	s_nop 0
	v_readfirstlane_b32 s1, v0
	s_mov_b32 m0, s1
	v_mov_b32_e32 v0, v134
	global_load_lds_dwordx4 v[2:3], off
	s_nop 0
	v_lshl_add_u64 v[2:3], v[0:1], 1, s[14:15]
	v_add_u32_e32 v0, s3, v135
	s_nop 0
	v_readfirstlane_b32 s1, v0
	s_mov_b32 m0, s1
	v_mov_b32_e32 v0, v136
	global_load_lds_dwordx4 v[2:3], off
	s_nop 0
	v_lshl_add_u64 v[2:3], v[0:1], 1, s[14:15]
	v_add_u32_e32 v0, s3, v137
	s_nop 0
	v_readfirstlane_b32 s1, v0
	s_mov_b32 m0, s1
	v_mov_b32_e32 v0, v138
	global_load_lds_dwordx4 v[2:3], off
	s_nop 0
	v_lshl_add_u64 v[2:3], v[0:1], 1, s[14:15]
	v_add_u32_e32 v0, s3, v139
	v_readlane_b32 s3, v253, 26
	v_readfirstlane_b32 s1, v0
	s_mov_b32 m0, s1
	v_readlane_b32 s1, v253, 25
	global_load_lds_dwordx4 v[2:3], off
	s_add_u32 s1, s1, s4
	s_waitcnt vmcnt(0)
	s_addc_u32 s3, s3, s5
	v_readlane_b32 s4, v253, 34
	s_add_u32 s10, s4, s10
	v_readlane_b32 s4, v253, 35
	v_mov_b32_e32 v2, 0
	s_addc_u32 s11, s4, s11
	s_mov_b64 s[4:5], 0
	v_mov_b32_e32 v3, v2
	v_mov_b32_e32 v4, v2
	v_mov_b32_e32 v5, v2
	v_mov_b32_e32 v6, v2
	v_mov_b32_e32 v7, v2
	v_mov_b32_e32 v8, v2
	v_mov_b32_e32 v9, v2
	v_mov_b32_e32 v10, v2
	v_mov_b32_e32 v11, v2
	v_mov_b32_e32 v12, v2
	v_mov_b32_e32 v13, v2
	s_waitcnt vmcnt(0)
	v_mov_b32_e32 v14, v2
	v_mov_b32_e32 v15, v2
	v_mov_b32_e32 v16, v2
	v_mov_b32_e32 v17, v2
	v_mov_b32_e32 v18, v2
	v_mov_b32_e32 v19, v2
	v_mov_b32_e32 v20, v2
	v_mov_b32_e32 v21, v2
	v_mov_b32_e32 v22, v2
	v_mov_b32_e32 v23, v2
	v_mov_b32_e32 v24, v2
	v_mov_b32_e32 v25, v2
	v_mov_b32_e32 v26, v2
	v_mov_b32_e32 v27, v2
	v_mov_b32_e32 v28, v2
	v_mov_b32_e32 v29, v2
	v_mov_b32_e32 v30, v2
	v_mov_b32_e32 v31, v2
	v_mov_b32_e32 v32, v2
	v_mov_b32_e32 v33, v2
	v_mov_b32_e32 v34, v2
	v_mov_b32_e32 v35, v2
	v_mov_b32_e32 v36, v2
	v_mov_b32_e32 v37, v2
	v_mov_b32_e32 v38, v2
	v_mov_b32_e32 v39, v2
	v_mov_b32_e32 v40, v2
	v_mov_b32_e32 v41, v2
	v_mov_b32_e32 v42, v2
	v_mov_b32_e32 v43, v2
	v_mov_b32_e32 v44, v2
	v_mov_b32_e32 v45, v2
	v_mov_b32_e32 v46, v2
	v_mov_b32_e32 v47, v2
	v_mov_b32_e32 v48, v2
	v_mov_b32_e32 v49, v2
	v_mov_b32_e32 v50, v2
	v_mov_b32_e32 v51, v2
	v_mov_b32_e32 v52, v2
	v_mov_b32_e32 v53, v2
	v_mov_b32_e32 v54, v2
	v_mov_b32_e32 v55, v2
	v_mov_b32_e32 v56, v2
	v_mov_b32_e32 v57, v2
	v_mov_b32_e32 v58, v2
	v_mov_b32_e32 v59, v2
	v_mov_b32_e32 v60, v2
	v_mov_b32_e32 v61, v2
	v_mov_b32_e32 v62, v2
	v_mov_b32_e32 v63, v2
	v_mov_b32_e32 v64, v2
	v_mov_b32_e32 v65, v2
	v_mov_b32_e32 v66, v2
	v_mov_b32_e32 v67, v2
	v_mov_b32_e32 v68, v2
	v_mov_b32_e32 v69, v2
	v_mov_b32_e32 v70, v2
	v_mov_b32_e32 v71, v2
	v_mov_b32_e32 v72, v2
	v_mov_b32_e32 v73, v2
	v_mov_b32_e32 v74, v2
	v_mov_b32_e32 v75, v2
	v_mov_b32_e32 v76, v2
	v_mov_b32_e32 v77, v2
	v_mov_b32_e32 v78, v2
	v_mov_b32_e32 v79, v2
	v_mov_b32_e32 v80, v2
	v_mov_b32_e32 v81, v2
	v_mov_b32_e32 v82, v2
	v_mov_b32_e32 v83, v2
	v_mov_b32_e32 v84, v2
	v_mov_b32_e32 v85, v2
	v_mov_b32_e32 v86, v2
	v_mov_b32_e32 v87, v2
	v_mov_b32_e32 v88, v2
	v_mov_b32_e32 v89, v2
	v_mov_b32_e32 v90, v2
	v_mov_b32_e32 v91, v2
	v_mov_b32_e32 v92, v2
	v_mov_b32_e32 v93, v2
	v_mov_b32_e32 v94, v2
	v_mov_b32_e32 v95, v2
	v_mov_b32_e32 v96, v2
	v_mov_b32_e32 v97, v2
	v_mov_b32_e32 v98, v2
	v_mov_b32_e32 v99, v2
	v_mov_b32_e32 v100, v2
	v_mov_b32_e32 v101, v2
	v_mov_b32_e32 v102, v2
	v_mov_b32_e32 v103, v2
	v_mov_b32_e32 v104, v2
	v_mov_b32_e32 v105, v2
	v_mov_b32_e32 v106, v2
	v_mov_b32_e32 v107, v2
	v_mov_b32_e32 v108, v2
	v_mov_b32_e32 v109, v2
	v_mov_b32_e32 v110, v2
	v_mov_b32_e32 v111, v2
	v_mov_b32_e32 v112, v2
	v_mov_b32_e32 v113, v2
	v_mov_b32_e32 v114, v2
	v_mov_b32_e32 v115, v2
	v_mov_b32_e32 v116, v2
	v_mov_b32_e32 v117, v2
	v_mov_b32_e32 v118, v2
	v_mov_b32_e32 v119, v2
	v_mov_b32_e32 v120, v2
	v_mov_b32_e32 v121, v2
	v_mov_b32_e32 v122, v2
	v_mov_b32_e32 v123, v2
	v_mov_b32_e32 v124, v2
	v_mov_b32_e32 v125, v2
	v_mov_b32_e32 v126, v2
	v_mov_b32_e32 v127, v2
	v_mov_b32_e32 v128, v2
	v_mov_b32_e32 v129, v2
	s_waitcnt lgkmcnt(0)
	s_barrier
	v_lshlrev_b32_e32 v149, 1, v132
	v_readfirstlane_b32 s14, v133
	v_add_u32_e32 v205, v140, v142
	v_add_u32_e32 v209, v141, v142
	v_add_u32_e32 v206, v140, v146
	v_add_u32_e32 v210, v141, v146
	v_add_u32_e32 v207, v140, v147
	v_add_u32_e32 v211, v141, v147
	v_add_u32_e32 v208, v140, v148
	v_add_u32_e32 v212, v141, v148
	s_mov_b32 s9, 7
	s_add_u32 m0, s14, 0x8020
	s_add_u32 s12, s1, s4
	s_addc_u32 s13, s3, s5
	global_load_lds_dwordx4 v149, s[12:13]
	s_add_u32 m0, s14, 0xa020
	s_add_u32 s12, s12, 0x20000
	s_addc_u32 s13, s13, 0
	global_load_lds_dwordx4 v149, s[12:13]
	s_add_u32 m0, s14, 0xc020
	s_add_u32 s12, s12, 0x20000
	s_addc_u32 s13, s13, 0
	global_load_lds_dwordx4 v149, s[12:13]
	s_add_u32 m0, s14, 0xe020
	s_add_u32 s12, s12, 0x20000
	s_addc_u32 s13, s13, 0
	global_load_lds_dwordx4 v149, s[12:13]
	s_add_u32 m0, s14, 0x18020
	s_add_u32 s12, s10, s4
	s_addc_u32 s13, s11, s5
	global_load_lds_dwordx4 v149, s[12:13]
	ds_read_b128 v[150:153], v205 offset:0
	ds_read_b128 v[166:169], v209 offset:0
	ds_read_b128 v[170:173], v209 offset:4096
	ds_read_b128 v[154:157], v205 offset:4096
	ds_read_b128 v[158:161], v205 offset:8192
	ds_read_b128 v[162:165], v205 offset:12288
.Lg910_loop:
	s_waitcnt lgkmcnt(4)
	v_mfma_f32_32x32x16_bf16 v[114:129], v[150:153], v[166:169], v[114:129]
	ds_read_b128 v[174:177], v206 offset:0
	s_waitcnt lgkmcnt(4)
	v_mfma_f32_32x32x16_bf16 v[98:113], v[150:153], v[170:173], v[98:113]
	ds_read_b128 v[192:195], v210 offset:0
	s_add_u32 m0, s14, 0x1a020
	s_add_u32 s12, s12, 0x20000
	s_addc_u32 s13, s13, 0
	global_load_lds_dwordx4 v149, s[12:13]
	s_waitcnt lgkmcnt(4)
	v_mfma_f32_32x32x16_bf16 v[82:97], v[154:157], v[166:169], v[82:97]
	ds_read_b128 v[200:203], v210 offset:4096
	v_mfma_f32_32x32x16_bf16 v[66:81], v[154:157], v[170:173], v[66:81]
	ds_read_b128 v[180:183], v206 offset:4096
	s_add_u32 m0, s14, 0x1c020
	s_add_u32 s12, s12, 0x20000
	s_addc_u32 s13, s13, 0
	global_load_lds_dwordx4 v149, s[12:13]
	s_waitcnt lgkmcnt(5)
	v_mfma_f32_32x32x16_bf16 v[50:65], v[158:161], v[166:169], v[50:65]
	ds_read_b128 v[184:187], v206 offset:8192
	v_mfma_f32_32x32x16_bf16 v[34:49], v[158:161], v[170:173], v[34:49]
	ds_read_b128 v[188:191], v206 offset:12288
	s_add_u32 m0, s14, 0x1e020
	s_add_u32 s12, s12, 0x20000
	s_addc_u32 s13, s13, 0
	global_load_lds_dwordx4 v149, s[12:13]
	s_add_u32 s4, s4, 0x80
	s_addc_u32 s5, s5, 0
	s_waitcnt lgkmcnt(6)
	v_mfma_f32_32x32x16_bf16 v[18:33], v[162:165], v[166:169], v[18:33]
	v_mfma_f32_32x32x16_bf16 v[2:17], v[162:165], v[170:173], v[2:17]
	s_waitcnt lgkmcnt(4)
	v_mfma_f32_32x32x16_bf16 v[114:129], v[174:177], v[192:195], v[114:129]
	ds_read_b128 v[150:153], v207 offset:0
	s_waitcnt lgkmcnt(4)
	v_mfma_f32_32x32x16_bf16 v[98:113], v[174:177], v[200:203], v[98:113]
	ds_read_b128 v[166:169], v211 offset:0
	s_waitcnt lgkmcnt(4)
	v_mfma_f32_32x32x16_bf16 v[82:97], v[180:183], v[192:195], v[82:97]
	ds_read_b128 v[170:173], v211 offset:4096
	v_mfma_f32_32x32x16_bf16 v[66:81], v[180:183], v[200:203], v[66:81]
	ds_read_b128 v[154:157], v207 offset:4096
	s_waitcnt lgkmcnt(5)
	v_mfma_f32_32x32x16_bf16 v[50:65], v[184:187], v[192:195], v[50:65]
	ds_read_b128 v[158:161], v207 offset:8192
	v_mfma_f32_32x32x16_bf16 v[34:49], v[184:187], v[200:203], v[34:49]
	ds_read_b128 v[162:165], v207 offset:12288
	s_waitcnt lgkmcnt(6)
	v_mfma_f32_32x32x16_bf16 v[18:33], v[188:191], v[192:195], v[18:33]
	v_mfma_f32_32x32x16_bf16 v[2:17], v[188:191], v[200:203], v[2:17]
	s_waitcnt lgkmcnt(4)
	v_mfma_f32_32x32x16_bf16 v[114:129], v[150:153], v[166:169], v[114:129]
	ds_read_b128 v[174:177], v208 offset:0
	ds_read_b128 v[192:195], v212 offset:0
	s_waitcnt lgkmcnt(5)
	v_mfma_f32_32x32x16_bf16 v[98:113], v[150:153], v[170:173], v[98:113]
	ds_read_b128 v[200:203], v212 offset:4096
	ds_read_b128 v[180:183], v208 offset:4096
	s_waitcnt lgkmcnt(6)
	v_mfma_f32_32x32x16_bf16 v[82:97], v[154:157], v[166:169], v[82:97]
	ds_read_b128 v[184:187], v208 offset:8192
	ds_read_b128 v[188:191], v208 offset:12288
	v_mfma_f32_32x32x16_bf16 v[66:81], v[154:157], v[170:173], v[66:81]
	s_waitcnt lgkmcnt(7)
	v_mfma_f32_32x32x16_bf16 v[50:65], v[158:161], v[166:169], v[50:65]
	v_mfma_f32_32x32x16_bf16 v[34:49], v[158:161], v[170:173], v[34:49]
	s_waitcnt lgkmcnt(6)
	v_mfma_f32_32x32x16_bf16 v[18:33], v[162:165], v[166:169], v[18:33]
	v_mfma_f32_32x32x16_bf16 v[2:17], v[162:165], v[170:173], v[2:17]
	s_waitcnt vmcnt(0) lgkmcnt(0)
	s_barrier
	v_mfma_f32_32x32x16_bf16 v[114:129], v[174:177], v[192:195], v[114:129]
	ds_read_b128 v[150:153], v205 offset:32768
	s_add_u32 m0, s14, 0x20
	s_add_u32 s12, s1, s4
	s_addc_u32 s13, s3, s5
	global_load_lds_dwordx4 v149, s[12:13]
	v_mfma_f32_32x32x16_bf16 v[98:113], v[174:177], v[200:203], v[98:113]
	ds_read_b128 v[166:169], v209 offset:32768
	s_add_u32 m0, s14, 0x2020
	s_add_u32 s12, s12, 0x20000
	s_addc_u32 s13, s13, 0
	global_load_lds_dwordx4 v149, s[12:13]
	v_mfma_f32_32x32x16_bf16 v[82:97], v[180:183], v[192:195], v[82:97]
	ds_read_b128 v[170:173], v209 offset:36864
	s_add_u32 m0, s14, 0x4020
	s_add_u32 s12, s12, 0x20000
	s_addc_u32 s13, s13, 0
	global_load_lds_dwordx4 v149, s[12:13]
	v_mfma_f32_32x32x16_bf16 v[66:81], v[180:183], v[200:203], v[66:81]
	ds_read_b128 v[154:157], v205 offset:36864
	s_add_u32 m0, s14, 0x6020
	s_add_u32 s12, s12, 0x20000
	s_addc_u32 s13, s13, 0
	global_load_lds_dwordx4 v149, s[12:13]
	v_mfma_f32_32x32x16_bf16 v[50:65], v[184:187], v[192:195], v[50:65]
	ds_read_b128 v[158:161], v205 offset:40960
	s_add_u32 m0, s14, 0x10020
	s_add_u32 s12, s10, s4
	s_addc_u32 s13, s11, s5
	global_load_lds_dwordx4 v149, s[12:13]
	v_mfma_f32_32x32x16_bf16 v[34:49], v[184:187], v[200:203], v[34:49]
	ds_read_b128 v[162:165], v205 offset:45056
	v_mfma_f32_32x32x16_bf16 v[18:33], v[188:191], v[192:195], v[18:33]
	v_mfma_f32_32x32x16_bf16 v[2:17], v[188:191], v[200:203], v[2:17]
	s_waitcnt lgkmcnt(4)
	v_mfma_f32_32x32x16_bf16 v[114:129], v[150:153], v[166:169], v[114:129]
	ds_read_b128 v[174:177], v206 offset:32768
	s_waitcnt lgkmcnt(4)
	v_mfma_f32_32x32x16_bf16 v[98:113], v[150:153], v[170:173], v[98:113]
	ds_read_b128 v[192:195], v210 offset:32768
	s_add_u32 m0, s14, 0x12020
	s_add_u32 s12, s12, 0x20000
	s_addc_u32 s13, s13, 0
	global_load_lds_dwordx4 v149, s[12:13]
	s_waitcnt lgkmcnt(4)
	v_mfma_f32_32x32x16_bf16 v[82:97], v[154:157], v[166:169], v[82:97]
	ds_read_b128 v[200:203], v210 offset:36864
	v_mfma_f32_32x32x16_bf16 v[66:81], v[154:157], v[170:173], v[66:81]
	ds_read_b128 v[180:183], v206 offset:36864
	s_add_u32 m0, s14, 0x14020
	s_add_u32 s12, s12, 0x20000
	s_addc_u32 s13, s13, 0
	global_load_lds_dwordx4 v149, s[12:13]
	s_waitcnt lgkmcnt(5)
	v_mfma_f32_32x32x16_bf16 v[50:65], v[158:161], v[166:169], v[50:65]
	ds_read_b128 v[184:187], v206 offset:40960
	v_mfma_f32_32x32x16_bf16 v[34:49], v[158:161], v[170:173], v[34:49]
	ds_read_b128 v[188:191], v206 offset:45056
	s_add_u32 m0, s14, 0x16020
	s_add_u32 s12, s12, 0x20000
	s_addc_u32 s13, s13, 0
	global_load_lds_dwordx4 v149, s[12:13]
	s_add_u32 s4, s4, 0x80
	s_addc_u32 s5, s5, 0
	s_waitcnt lgkmcnt(6)
	v_mfma_f32_32x32x16_bf16 v[18:33], v[162:165], v[166:169], v[18:33]
	v_mfma_f32_32x32x16_bf16 v[2:17], v[162:165], v[170:173], v[2:17]
	s_waitcnt lgkmcnt(4)
	v_mfma_f32_32x32x16_bf16 v[114:129], v[174:177], v[192:195], v[114:129]
	ds_read_b128 v[150:153], v207 offset:32768
	s_waitcnt lgkmcnt(4)
	v_mfma_f32_32x32x16_bf16 v[98:113], v[174:177], v[200:203], v[98:113]
	ds_read_b128 v[166:169], v211 offset:32768
	s_waitcnt lgkmcnt(4)
	v_mfma_f32_32x32x16_bf16 v[82:97], v[180:183], v[192:195], v[82:97]
	ds_read_b128 v[170:173], v211 offset:36864
	v_mfma_f32_32x32x16_bf16 v[66:81], v[180:183], v[200:203], v[66:81]
	ds_read_b128 v[154:157], v207 offset:36864
	s_waitcnt lgkmcnt(5)
	v_mfma_f32_32x32x16_bf16 v[50:65], v[184:187], v[192:195], v[50:65]
	ds_read_b128 v[158:161], v207 offset:40960
	v_mfma_f32_32x32x16_bf16 v[34:49], v[184:187], v[200:203], v[34:49]
	ds_read_b128 v[162:165], v207 offset:45056
	s_waitcnt lgkmcnt(6)
	v_mfma_f32_32x32x16_bf16 v[18:33], v[188:191], v[192:195], v[18:33]
	v_mfma_f32_32x32x16_bf16 v[2:17], v[188:191], v[200:203], v[2:17]
	s_waitcnt lgkmcnt(4)
	v_mfma_f32_32x32x16_bf16 v[114:129], v[150:153], v[166:169], v[114:129]
	ds_read_b128 v[174:177], v208 offset:32768
	ds_read_b128 v[192:195], v212 offset:32768
	s_waitcnt lgkmcnt(5)
	v_mfma_f32_32x32x16_bf16 v[98:113], v[150:153], v[170:173], v[98:113]
	ds_read_b128 v[200:203], v212 offset:36864
	ds_read_b128 v[180:183], v208 offset:36864
	s_waitcnt lgkmcnt(6)
	v_mfma_f32_32x32x16_bf16 v[82:97], v[154:157], v[166:169], v[82:97]
	ds_read_b128 v[184:187], v208 offset:40960
	ds_read_b128 v[188:191], v208 offset:45056
	v_mfma_f32_32x32x16_bf16 v[66:81], v[154:157], v[170:173], v[66:81]
	s_waitcnt lgkmcnt(7)
	v_mfma_f32_32x32x16_bf16 v[50:65], v[158:161], v[166:169], v[50:65]
	v_mfma_f32_32x32x16_bf16 v[34:49], v[158:161], v[170:173], v[34:49]
	s_waitcnt lgkmcnt(6)
	v_mfma_f32_32x32x16_bf16 v[18:33], v[162:165], v[166:169], v[18:33]
	v_mfma_f32_32x32x16_bf16 v[2:17], v[162:165], v[170:173], v[2:17]
	s_waitcnt vmcnt(0) lgkmcnt(0)
	s_barrier
	v_mfma_f32_32x32x16_bf16 v[114:129], v[174:177], v[192:195], v[114:129]
	ds_read_b128 v[150:153], v205 offset:0
	s_add_u32 m0, s14, 0x8020
	s_add_u32 s12, s1, s4
	s_addc_u32 s13, s3, s5
	global_load_lds_dwordx4 v149, s[12:13]
	v_mfma_f32_32x32x16_bf16 v[98:113], v[174:177], v[200:203], v[98:113]
	ds_read_b128 v[166:169], v209 offset:0
	s_add_u32 m0, s14, 0xa020
	s_add_u32 s12, s12, 0x20000
	s_addc_u32 s13, s13, 0
	global_load_lds_dwordx4 v149, s[12:13]
	v_mfma_f32_32x32x16_bf16 v[82:97], v[180:183], v[192:195], v[82:97]
	ds_read_b128 v[170:173], v209 offset:4096
	s_add_u32 m0, s14, 0xc020
	s_add_u32 s12, s12, 0x20000
	s_addc_u32 s13, s13, 0
	global_load_lds_dwordx4 v149, s[12:13]
	v_mfma_f32_32x32x16_bf16 v[66:81], v[180:183], v[200:203], v[66:81]
	ds_read_b128 v[154:157], v205 offset:4096
	s_add_u32 m0, s14, 0xe020
	s_add_u32 s12, s12, 0x20000
	s_addc_u32 s13, s13, 0
	global_load_lds_dwordx4 v149, s[12:13]
	v_mfma_f32_32x32x16_bf16 v[50:65], v[184:187], v[192:195], v[50:65]
	ds_read_b128 v[158:161], v205 offset:8192
	s_add_u32 m0, s14, 0x18020
	s_add_u32 s12, s10, s4
	s_addc_u32 s13, s11, s5
	global_load_lds_dwordx4 v149, s[12:13]
	v_mfma_f32_32x32x16_bf16 v[34:49], v[184:187], v[200:203], v[34:49]
	ds_read_b128 v[162:165], v205 offset:12288
	v_mfma_f32_32x32x16_bf16 v[18:33], v[188:191], v[192:195], v[18:33]
	v_mfma_f32_32x32x16_bf16 v[2:17], v[188:191], v[200:203], v[2:17]
	s_sub_u32 s9, s9, 1
	s_cmp_lg_u32 s9, 0
	s_cbranch_scc1 .Lg910_loop
	s_waitcnt lgkmcnt(4)
	v_mfma_f32_32x32x16_bf16 v[114:129], v[150:153], v[166:169], v[114:129]
	ds_read_b128 v[174:177], v206 offset:0
	s_waitcnt lgkmcnt(4)
	v_mfma_f32_32x32x16_bf16 v[98:113], v[150:153], v[170:173], v[98:113]
	ds_read_b128 v[192:195], v210 offset:0
	s_add_u32 m0, s14, 0x1a020
	s_add_u32 s12, s12, 0x20000
	s_addc_u32 s13, s13, 0
	global_load_lds_dwordx4 v149, s[12:13]
	s_waitcnt lgkmcnt(4)
	v_mfma_f32_32x32x16_bf16 v[82:97], v[154:157], v[166:169], v[82:97]
	ds_read_b128 v[200:203], v210 offset:4096
	v_mfma_f32_32x32x16_bf16 v[66:81], v[154:157], v[170:173], v[66:81]
	ds_read_b128 v[180:183], v206 offset:4096
	s_add_u32 m0, s14, 0x1c020
	s_add_u32 s12, s12, 0x20000
	s_addc_u32 s13, s13, 0
	global_load_lds_dwordx4 v149, s[12:13]
	s_waitcnt lgkmcnt(5)
	v_mfma_f32_32x32x16_bf16 v[50:65], v[158:161], v[166:169], v[50:65]
	ds_read_b128 v[184:187], v206 offset:8192
	v_mfma_f32_32x32x16_bf16 v[34:49], v[158:161], v[170:173], v[34:49]
	ds_read_b128 v[188:191], v206 offset:12288
	s_add_u32 m0, s14, 0x1e020
	s_add_u32 s12, s12, 0x20000
	s_addc_u32 s13, s13, 0
	global_load_lds_dwordx4 v149, s[12:13]
	s_add_u32 s4, s4, 0x80
	s_addc_u32 s5, s5, 0
	s_waitcnt lgkmcnt(6)
	v_mfma_f32_32x32x16_bf16 v[18:33], v[162:165], v[166:169], v[18:33]
	v_mfma_f32_32x32x16_bf16 v[2:17], v[162:165], v[170:173], v[2:17]
	s_waitcnt lgkmcnt(4)
	v_mfma_f32_32x32x16_bf16 v[114:129], v[174:177], v[192:195], v[114:129]
	ds_read_b128 v[150:153], v207 offset:0
	s_waitcnt lgkmcnt(4)
	v_mfma_f32_32x32x16_bf16 v[98:113], v[174:177], v[200:203], v[98:113]
	ds_read_b128 v[166:169], v211 offset:0
	s_waitcnt lgkmcnt(4)
	v_mfma_f32_32x32x16_bf16 v[82:97], v[180:183], v[192:195], v[82:97]
	ds_read_b128 v[170:173], v211 offset:4096
	v_mfma_f32_32x32x16_bf16 v[66:81], v[180:183], v[200:203], v[66:81]
	ds_read_b128 v[154:157], v207 offset:4096
	s_waitcnt lgkmcnt(5)
	v_mfma_f32_32x32x16_bf16 v[50:65], v[184:187], v[192:195], v[50:65]
	ds_read_b128 v[158:161], v207 offset:8192
	v_mfma_f32_32x32x16_bf16 v[34:49], v[184:187], v[200:203], v[34:49]
	ds_read_b128 v[162:165], v207 offset:12288
	s_waitcnt lgkmcnt(6)
	v_mfma_f32_32x32x16_bf16 v[18:33], v[188:191], v[192:195], v[18:33]
	v_mfma_f32_32x32x16_bf16 v[2:17], v[188:191], v[200:203], v[2:17]
	s_waitcnt lgkmcnt(4)
	v_mfma_f32_32x32x16_bf16 v[114:129], v[150:153], v[166:169], v[114:129]
	ds_read_b128 v[174:177], v208 offset:0
	ds_read_b128 v[192:195], v212 offset:0
	s_waitcnt lgkmcnt(5)
	v_mfma_f32_32x32x16_bf16 v[98:113], v[150:153], v[170:173], v[98:113]
	ds_read_b128 v[200:203], v212 offset:4096
	ds_read_b128 v[180:183], v208 offset:4096
	s_waitcnt lgkmcnt(6)
	v_mfma_f32_32x32x16_bf16 v[82:97], v[154:157], v[166:169], v[82:97]
	ds_read_b128 v[184:187], v208 offset:8192
	ds_read_b128 v[188:191], v208 offset:12288
	v_mfma_f32_32x32x16_bf16 v[66:81], v[154:157], v[170:173], v[66:81]
	s_waitcnt lgkmcnt(7)
	v_mfma_f32_32x32x16_bf16 v[50:65], v[158:161], v[166:169], v[50:65]
	v_mfma_f32_32x32x16_bf16 v[34:49], v[158:161], v[170:173], v[34:49]
	s_waitcnt lgkmcnt(6)
	v_mfma_f32_32x32x16_bf16 v[18:33], v[162:165], v[166:169], v[18:33]
	v_mfma_f32_32x32x16_bf16 v[2:17], v[162:165], v[170:173], v[2:17]
	s_waitcnt vmcnt(0) lgkmcnt(0)
	s_barrier
	v_mfma_f32_32x32x16_bf16 v[114:129], v[174:177], v[192:195], v[114:129]
	ds_read_b128 v[150:153], v205 offset:32768
	v_mfma_f32_32x32x16_bf16 v[98:113], v[174:177], v[200:203], v[98:113]
	ds_read_b128 v[166:169], v209 offset:32768
	v_mfma_f32_32x32x16_bf16 v[82:97], v[180:183], v[192:195], v[82:97]
	ds_read_b128 v[170:173], v209 offset:36864
	v_mfma_f32_32x32x16_bf16 v[66:81], v[180:183], v[200:203], v[66:81]
	ds_read_b128 v[154:157], v205 offset:36864
	v_mfma_f32_32x32x16_bf16 v[50:65], v[184:187], v[192:195], v[50:65]
	ds_read_b128 v[158:161], v205 offset:40960
	v_mfma_f32_32x32x16_bf16 v[34:49], v[184:187], v[200:203], v[34:49]
	ds_read_b128 v[162:165], v205 offset:45056
	v_mfma_f32_32x32x16_bf16 v[18:33], v[188:191], v[192:195], v[18:33]
	v_mfma_f32_32x32x16_bf16 v[2:17], v[188:191], v[200:203], v[2:17]
	s_waitcnt lgkmcnt(4)
	v_mfma_f32_32x32x16_bf16 v[114:129], v[150:153], v[166:169], v[114:129]
	ds_read_b128 v[174:177], v206 offset:32768
	s_waitcnt lgkmcnt(4)
	v_mfma_f32_32x32x16_bf16 v[98:113], v[150:153], v[170:173], v[98:113]
	ds_read_b128 v[192:195], v210 offset:32768
	s_waitcnt lgkmcnt(4)
	v_mfma_f32_32x32x16_bf16 v[82:97], v[154:157], v[166:169], v[82:97]
	ds_read_b128 v[200:203], v210 offset:36864
	v_mfma_f32_32x32x16_bf16 v[66:81], v[154:157], v[170:173], v[66:81]
	ds_read_b128 v[180:183], v206 offset:36864
	s_waitcnt lgkmcnt(5)
	v_mfma_f32_32x32x16_bf16 v[50:65], v[158:161], v[166:169], v[50:65]
	ds_read_b128 v[184:187], v206 offset:40960
	v_mfma_f32_32x32x16_bf16 v[34:49], v[158:161], v[170:173], v[34:49]
	ds_read_b128 v[188:191], v206 offset:45056
	s_waitcnt lgkmcnt(6)
	v_mfma_f32_32x32x16_bf16 v[18:33], v[162:165], v[166:169], v[18:33]
	v_mfma_f32_32x32x16_bf16 v[2:17], v[162:165], v[170:173], v[2:17]
	s_waitcnt lgkmcnt(4)
	v_mfma_f32_32x32x16_bf16 v[114:129], v[174:177], v[192:195], v[114:129]
	ds_read_b128 v[150:153], v207 offset:32768
	s_waitcnt lgkmcnt(4)
	v_mfma_f32_32x32x16_bf16 v[98:113], v[174:177], v[200:203], v[98:113]
	ds_read_b128 v[166:169], v211 offset:32768
	s_waitcnt lgkmcnt(4)
	v_mfma_f32_32x32x16_bf16 v[82:97], v[180:183], v[192:195], v[82:97]
	ds_read_b128 v[170:173], v211 offset:36864
	v_mfma_f32_32x32x16_bf16 v[66:81], v[180:183], v[200:203], v[66:81]
	ds_read_b128 v[154:157], v207 offset:36864
	s_waitcnt lgkmcnt(5)
	v_mfma_f32_32x32x16_bf16 v[50:65], v[184:187], v[192:195], v[50:65]
	ds_read_b128 v[158:161], v207 offset:40960
	v_mfma_f32_32x32x16_bf16 v[34:49], v[184:187], v[200:203], v[34:49]
	ds_read_b128 v[162:165], v207 offset:45056
	s_waitcnt lgkmcnt(6)
	v_mfma_f32_32x32x16_bf16 v[18:33], v[188:191], v[192:195], v[18:33]
	v_mfma_f32_32x32x16_bf16 v[2:17], v[188:191], v[200:203], v[2:17]
	s_waitcnt lgkmcnt(4)
	v_mfma_f32_32x32x16_bf16 v[114:129], v[150:153], v[166:169], v[114:129]
	ds_read_b128 v[174:177], v208 offset:32768
	ds_read_b128 v[192:195], v212 offset:32768
	s_waitcnt lgkmcnt(5)
	v_mfma_f32_32x32x16_bf16 v[98:113], v[150:153], v[170:173], v[98:113]
	ds_read_b128 v[200:203], v212 offset:36864
	ds_read_b128 v[180:183], v208 offset:36864
	s_waitcnt lgkmcnt(6)
	v_mfma_f32_32x32x16_bf16 v[82:97], v[154:157], v[166:169], v[82:97]
	ds_read_b128 v[184:187], v208 offset:40960
	ds_read_b128 v[188:191], v208 offset:45056
	v_mfma_f32_32x32x16_bf16 v[66:81], v[154:157], v[170:173], v[66:81]
	s_waitcnt lgkmcnt(7)
	v_mfma_f32_32x32x16_bf16 v[50:65], v[158:161], v[166:169], v[50:65]
	v_mfma_f32_32x32x16_bf16 v[34:49], v[158:161], v[170:173], v[34:49]
	s_waitcnt lgkmcnt(6)
	v_mfma_f32_32x32x16_bf16 v[18:33], v[162:165], v[166:169], v[18:33]
	v_mfma_f32_32x32x16_bf16 v[2:17], v[162:165], v[170:173], v[2:17]
	s_waitcnt vmcnt(0) lgkmcnt(0)
	s_barrier
	v_mfma_f32_32x32x16_bf16 v[114:129], v[174:177], v[192:195], v[114:129]
	v_mfma_f32_32x32x16_bf16 v[98:113], v[174:177], v[200:203], v[98:113]
	v_mfma_f32_32x32x16_bf16 v[82:97], v[180:183], v[192:195], v[82:97]
	v_mfma_f32_32x32x16_bf16 v[66:81], v[180:183], v[200:203], v[66:81]
	v_mfma_f32_32x32x16_bf16 v[50:65], v[184:187], v[192:195], v[50:65]
	v_mfma_f32_32x32x16_bf16 v[34:49], v[184:187], v[200:203], v[34:49]
	v_mfma_f32_32x32x16_bf16 v[18:33], v[188:191], v[192:195], v[18:33]
	v_mfma_f32_32x32x16_bf16 v[2:17], v[188:191], v[200:203], v[2:17]
	v_add_u32_e32 v149, s0, v143
	v_or_b32_e32 v130, s2, v144
	s_mov_b32 s2, 0x7e07e07f
	v_mul_hi_i32 v0, v149, s2
	v_lshrrev_b32_e32 v131, 31, v0
	v_ashrrev_i32_e32 v0, 13, v0
	v_add_u32_e32 v0, v0, v131
	v_mul_i32_i24_e32 v131, 0x4100, v0
	v_sub_u32_e32 v131, v149, v131
	s_movk_i32 s3, 0xff
	v_mul_i32_i24_e32 v0, 0xc00, v0
	v_cmp_lt_i32_e32 vcc, s3, v131
	v_mov_b32_e32 v162, 0x1800
	v_mov_b32_e32 v152, v179
	s_waitcnt vmcnt(0)
	s_barrier
	v_cndmask_b32_e32 v150, v162, v0, vcc
	v_readlane_b32 s12, v251, 2
	v_and_b32_e32 v0, 31, v152
	v_bfe_u32 v131, v152, 5, 1
	v_mul_u32_u24_e32 v131, 0x240, v131
	v_lshlrev_b32_e32 v0, 2, v0
	v_add3_u32 v0, v145, v131, v0
	ds_write2_b32 v0, v114, v115 offset1:36
	ds_write2_b32 v0, v116, v117 offset0:72 offset1:108
	v_add_u32_e32 v114, 0x400, v0
	v_ashrrev_i32_e32 v151, 31, v150
	ds_write2_b32 v114, v118, v119 offset0:32 offset1:68
	ds_write2_b32 v114, v120, v121 offset0:104 offset1:140
	v_add_u32_e32 v114, 0x800, v0
	v_add_u32_e32 v0, 0xc00, v0
	v_readlane_b32 s26, v251, 16
	v_readlane_b32 s27, v251, 17
	ds_write2_b32 v114, v122, v123 offset0:64 offset1:100
	ds_write2_b32 v114, v124, v125 offset0:136 offset1:172
	ds_write2_b32 v0, v126, v127 offset0:96 offset1:132
	ds_write2_b32 v0, v128, v129 offset0:168 offset1:204
	v_lshl_add_u64 v[114:115], v[150:151], 2, s[26:27]
	s_mov_b64 s[4:5], 0x1b02000
	v_ashrrev_i32_e32 v131, 31, v130
	v_readlane_b32 s0, v251, 26
	v_lshlrev_b32_e32 v0, 3, v152
	v_lshl_add_u64 v[118:119], v[114:115], 0, s[4:5]
	v_lshlrev_b64 v[116:117], 2, v[130:131]
	v_readlane_b32 s1, v251, 27
	v_and_b32_e32 v122, 24, v0
	v_lshl_add_u64 v[120:121], v[118:119], 0, v[116:117]
	v_lshl_add_u64 v[114:115], v[130:131], 1, s[0:1]
	v_lshlrev_b32_e32 v0, 2, v122
	v_bfe_u32 v131, v152, 2, 4
	v_lshl_add_u64 v[158:159], v[120:121], 0, v[0:1]
	v_lshlrev_b32_e32 v120, 1, v122
	v_mul_u32_u24_e32 v122, 0x90, v131
	s_waitcnt lgkmcnt(0)
	v_add3_u32 v0, v145, v0, v122
	ds_read_b128 v[122:125], v0
	ds_read_b128 v[126:129], v0 offset:16
	global_load_dwordx4 v[150:153], v[158:159], off offset:16
	global_load_dwordx4 v[154:157], v[158:159], off
	v_or_b32_e32 v160, v131, v149
	v_mov_b32_e32 v121, v1
	v_ashrrev_i32_e32 v161, 31, v160
	v_lshl_add_u64 v[120:121], v[114:115], 0, v[120:121]
	v_readlane_b32 s13, v251, 3
	v_readlane_b32 s14, v251, 4
	v_readlane_b32 s15, v251, 5
	v_readlane_b32 s16, v251, 6
	v_readlane_b32 s17, v251, 7
	v_readlane_b32 s18, v251, 8
	v_readlane_b32 s19, v251, 9
	v_readlane_b32 s20, v251, 10
	v_readlane_b32 s21, v251, 11
	v_readlane_b32 s22, v251, 12
	v_readlane_b32 s23, v251, 13
	v_readlane_b32 s24, v251, 14
	v_readlane_b32 s25, v251, 15
	s_waitcnt vmcnt(1) lgkmcnt(0)
	v_pk_mul_f32 v[126:127], v[126:127], v[150:151]
	s_waitcnt vmcnt(0)
	v_pk_mul_f32 v[122:123], v[122:123], v[154:155]
	v_pk_mul_f32 v[124:125], v[124:125], v[156:157]
	v_pk_mul_f32 v[128:129], v[128:129], v[152:153]
	v_cvt_pk_bf16_f32 v122, v122, v123
	v_cvt_pk_bf16_f32 v123, v124, v125
	v_cvt_pk_bf16_f32 v124, v126, v127
	v_lshlrev_b64 v[126:127], 11, v[160:161]
	v_cvt_pk_bf16_f32 v125, v128, v129
	v_lshl_add_u64 v[126:127], v[120:121], 0, v[126:127]
	global_store_dwordx4 v[126:127], v[122:125], off
	ds_read_b128 v[122:125], v0 offset:2304
	ds_read_b128 v[126:129], v0 offset:2320
	global_load_dwordx4 v[150:153], v[158:159], off offset:16
	global_load_dwordx4 v[154:157], v[158:159], off
	s_waitcnt vmcnt(1) lgkmcnt(0)
	v_pk_mul_f32 v[126:127], v[126:127], v[150:151]
	s_waitcnt vmcnt(0)
	v_pk_mul_f32 v[122:123], v[122:123], v[154:155]
	v_pk_mul_f32 v[124:125], v[124:125], v[156:157]
	v_cvt_pk_bf16_f32 v122, v122, v123
	v_cvt_pk_bf16_f32 v123, v124, v125
	v_cvt_pk_bf16_f32 v124, v126, v127
	v_or_b32_e32 v126, 16, v160
	v_ashrrev_i32_e32 v127, 31, v126
	v_pk_mul_f32 v[128:129], v[128:129], v[152:153]
	v_lshlrev_b64 v[126:127], 11, v[126:127]
	v_cvt_pk_bf16_f32 v125, v128, v129
	v_lshl_add_u64 v[120:121], v[120:121], 0, v[126:127]
	global_store_dwordx4 v[120:121], v[122:125], off
	v_mov_b32_e32 v120, v179
	v_or_b32_e32 v126, 32, v130
	v_and_b32_e32 v0, 31, v120
	v_bfe_u32 v121, v120, 5, 1
	v_mul_u32_u24_e32 v121, 0x240, v121
	v_lshlrev_b32_e32 v0, 2, v0
	v_add3_u32 v0, v145, v121, v0
	ds_write2_b32 v0, v98, v99 offset1:36
	ds_write2_b32 v0, v100, v101 offset0:72 offset1:108
	v_add_u32_e32 v98, 0x400, v0
	ds_write2_b32 v98, v102, v103 offset0:32 offset1:68
	ds_write2_b32 v98, v104, v105 offset0:104 offset1:140
	v_add_u32_e32 v98, 0x800, v0
	v_add_u32_e32 v0, 0xc00, v0
	ds_write2_b32 v98, v106, v107 offset0:64 offset1:100
	ds_write2_b32 v98, v108, v109 offset0:136 offset1:172
	ds_write2_b32 v0, v110, v111 offset0:96 offset1:132
	ds_write2_b32 v0, v112, v113 offset0:168 offset1:204
	v_lshlrev_b32_e32 v0, 3, v120
	v_and_b32_e32 v102, 24, v0
	v_ashrrev_i32_e32 v127, 31, v126
	v_lshlrev_b32_e32 v0, 2, v102
	v_lshl_add_u64 v[98:99], v[118:119], 0, v[0:1]
	v_lshlrev_b64 v[100:101], 2, v[126:127]
	v_lshl_add_u64 v[112:113], v[98:99], 0, v[100:101]
	v_lshlrev_b32_e32 v98, 1, v102
	v_mov_b32_e32 v99, v1
	v_bfe_u32 v128, v120, 2, 4
	v_lshl_add_u64 v[102:103], s[0:1], 0, v[98:99]
	v_mul_u32_u24_e32 v98, 0x90, v128
	s_waitcnt lgkmcnt(0)
	v_add3_u32 v0, v145, v0, v98
	ds_read_b128 v[104:107], v0
	ds_read_b128 v[108:111], v0 offset:16
	global_load_dwordx4 v[118:121], v[112:113], off offset:16
	global_load_dwordx4 v[122:125], v[112:113], off
	v_or_b32_e32 v128, v128, v149
	v_ashrrev_i32_e32 v129, 31, v128
	s_waitcnt vmcnt(1) lgkmcnt(0)
	v_pk_mul_f32 v[108:109], v[108:109], v[118:119]
	s_waitcnt vmcnt(0)
	v_pk_mul_f32 v[98:99], v[104:105], v[122:123]
	v_pk_mul_f32 v[106:107], v[106:107], v[124:125]
	v_cvt_pk_bf16_f32 v104, v98, v99
	v_lshlrev_b64 v[98:99], 11, v[128:129]
	v_pk_mul_f32 v[110:111], v[110:111], v[120:121]
	v_cvt_pk_bf16_f32 v105, v106, v107
	v_cvt_pk_bf16_f32 v106, v108, v109
	v_lshl_add_u64 v[108:109], v[102:103], 0, v[98:99]
	v_lshlrev_b64 v[98:99], 1, v[126:127]
	v_cvt_pk_bf16_f32 v107, v110, v111
	v_lshl_add_u64 v[108:109], v[108:109], 0, v[98:99]
	global_store_dwordx4 v[108:109], v[104:107], off
	ds_read_b128 v[104:107], v0 offset:2304
	ds_read_b128 v[108:111], v0 offset:2320
	global_load_dwordx4 v[118:121], v[112:113], off offset:16
	global_load_dwordx4 v[122:125], v[112:113], off
	s_waitcnt vmcnt(1) lgkmcnt(0)
	v_pk_mul_f32 v[108:109], v[108:109], v[118:119]
	s_waitcnt vmcnt(0)
	v_pk_mul_f32 v[104:105], v[104:105], v[122:123]
	v_pk_mul_f32 v[106:107], v[106:107], v[124:125]
	v_cvt_pk_bf16_f32 v104, v104, v105
	v_cvt_pk_bf16_f32 v105, v106, v107
	v_cvt_pk_bf16_f32 v106, v108, v109
	v_or_b32_e32 v108, 16, v128
	v_ashrrev_i32_e32 v109, 31, v108
	v_lshlrev_b64 v[108:109], 11, v[108:109]
	v_pk_mul_f32 v[110:111], v[110:111], v[120:121]
	v_lshl_add_u64 v[102:103], v[102:103], 0, v[108:109]
	v_cvt_pk_bf16_f32 v107, v110, v111
	v_lshl_add_u64 v[102:103], v[102:103], 0, v[98:99]
	global_store_dwordx4 v[102:103], v[104:107], off
	v_or_b32_e32 v110, 32, v149
	v_mul_hi_i32 v0, v110, s2
	v_lshrrev_b32_e32 v102, 31, v0
	v_ashrrev_i32_e32 v0, 13, v0
	v_add_u32_e32 v0, v0, v102
	v_mul_i32_i24_e32 v102, 0x4100, v0
	v_sub_u32_e32 v102, v110, v102
	v_mul_i32_i24_e32 v0, 0xc00, v0
	v_cmp_lt_i32_e32 vcc, s3, v102
	v_mov_b32_e32 v104, v179
	s_nop 0
	v_cndmask_b32_e32 v102, v162, v0, vcc
	v_and_b32_e32 v0, 31, v104
	v_bfe_u32 v105, v104, 5, 1
	v_mul_u32_u24_e32 v105, 0x240, v105
	v_lshlrev_b32_e32 v0, 2, v0
	v_add3_u32 v0, v145, v105, v0
	ds_write2_b32 v0, v82, v83 offset1:36
	ds_write2_b32 v0, v84, v85 offset0:72 offset1:108
	v_add_u32_e32 v82, 0x400, v0
	v_ashrrev_i32_e32 v103, 31, v102
	ds_write2_b32 v82, v86, v87 offset0:32 offset1:68
	ds_write2_b32 v82, v88, v89 offset0:104 offset1:140
	v_add_u32_e32 v82, 0x800, v0
	v_add_u32_e32 v0, 0xc00, v0
	ds_write2_b32 v82, v90, v91 offset0:64 offset1:100
	ds_write2_b32 v82, v92, v93 offset0:136 offset1:172
	ds_write2_b32 v0, v94, v95 offset0:96 offset1:132
	ds_write2_b32 v0, v96, v97 offset0:168 offset1:204
	v_lshl_add_u64 v[82:83], v[102:103], 2, s[26:27]
	v_lshlrev_b32_e32 v0, 3, v104
	v_lshl_add_u64 v[82:83], v[82:83], 0, s[4:5]
	v_and_b32_e32 v86, 24, v0
	v_lshl_add_u64 v[84:85], v[82:83], 0, v[116:117]
	v_lshlrev_b32_e32 v0, 2, v86
	v_bfe_u32 v108, v104, 2, 4
	v_lshl_add_u64 v[106:107], v[84:85], 0, v[0:1]
	v_lshlrev_b32_e32 v84, 1, v86
	v_mul_u32_u24_e32 v86, 0x90, v108
	s_waitcnt lgkmcnt(0)
	v_add3_u32 v0, v145, v0, v86
	ds_read_b128 v[86:89], v0
	ds_read_b128 v[90:93], v0 offset:16
	global_load_dwordx4 v[94:97], v[106:107], off offset:16
	global_load_dwordx4 v[102:105], v[106:107], off
	v_or_b32_e32 v108, v108, v110
	v_mov_b32_e32 v85, v1
	v_ashrrev_i32_e32 v109, 31, v108
	v_lshl_add_u64 v[84:85], v[114:115], 0, v[84:85]
	s_waitcnt vmcnt(1) lgkmcnt(0)
	v_pk_mul_f32 v[90:91], v[90:91], v[94:95]
	s_waitcnt vmcnt(0)
	v_pk_mul_f32 v[86:87], v[86:87], v[102:103]
	v_pk_mul_f32 v[88:89], v[88:89], v[104:105]
	v_pk_mul_f32 v[92:93], v[92:93], v[96:97]
	v_cvt_pk_bf16_f32 v86, v86, v87
	v_cvt_pk_bf16_f32 v87, v88, v89
	v_cvt_pk_bf16_f32 v88, v90, v91
	v_lshlrev_b64 v[90:91], 11, v[108:109]
	v_cvt_pk_bf16_f32 v89, v92, v93
	v_lshl_add_u64 v[90:91], v[84:85], 0, v[90:91]
	global_store_dwordx4 v[90:91], v[86:89], off
	ds_read_b128 v[86:89], v0 offset:2304
	ds_read_b128 v[90:93], v0 offset:2320
	global_load_dwordx4 v[94:97], v[106:107], off offset:16
	global_load_dwordx4 v[102:105], v[106:107], off
	s_waitcnt vmcnt(1) lgkmcnt(0)
	v_pk_mul_f32 v[90:91], v[90:91], v[94:95]
	s_waitcnt vmcnt(0)
	v_pk_mul_f32 v[86:87], v[86:87], v[102:103]
	v_pk_mul_f32 v[88:89], v[88:89], v[104:105]
	v_cvt_pk_bf16_f32 v86, v86, v87
	v_cvt_pk_bf16_f32 v87, v88, v89
	v_cvt_pk_bf16_f32 v88, v90, v91
	v_or_b32_e32 v90, 16, v108
	v_ashrrev_i32_e32 v91, 31, v90
	v_pk_mul_f32 v[92:93], v[92:93], v[96:97]
	v_lshlrev_b64 v[90:91], 11, v[90:91]
	v_cvt_pk_bf16_f32 v89, v92, v93
	v_lshl_add_u64 v[84:85], v[84:85], 0, v[90:91]
	global_store_dwordx4 v[84:85], v[86:89], off
	s_nop 1
	v_mov_b32_e32 v86, v179
	s_nop 0
	v_and_b32_e32 v0, 31, v86
	v_bfe_u32 v84, v86, 5, 1
	v_mul_u32_u24_e32 v84, 0x240, v84
	v_lshlrev_b32_e32 v0, 2, v0
	v_add3_u32 v0, v145, v84, v0
	ds_write2_b32 v0, v66, v67 offset1:36
	ds_write2_b32 v0, v68, v69 offset0:72 offset1:108
	v_add_u32_e32 v66, 0x400, v0
	ds_write2_b32 v66, v70, v71 offset0:32 offset1:68
	ds_write2_b32 v66, v72, v73 offset0:104 offset1:140
	v_add_u32_e32 v66, 0x800, v0
	v_add_u32_e32 v0, 0xc00, v0
	ds_write2_b32 v66, v74, v75 offset0:64 offset1:100
	ds_write2_b32 v66, v76, v77 offset0:136 offset1:172
	ds_write2_b32 v0, v78, v79 offset0:96 offset1:132
	ds_write2_b32 v0, v80, v81 offset0:168 offset1:204
	v_lshlrev_b32_e32 v0, 3, v86
	v_and_b32_e32 v68, 24, v0
	v_lshlrev_b32_e32 v0, 2, v68
	v_lshl_add_u64 v[66:67], v[82:83], 0, v[0:1]
	v_bfe_u32 v86, v86, 2, 4
	v_lshl_add_u64 v[84:85], v[66:67], 0, v[100:101]
	v_lshlrev_b32_e32 v66, 1, v68
	v_mul_u32_u24_e32 v68, 0x90, v86
	s_waitcnt lgkmcnt(0)
	v_add3_u32 v0, v145, v0, v68
	ds_read_b128 v[68:71], v0
	ds_read_b128 v[72:75], v0 offset:16
	global_load_dwordx4 v[76:79], v[84:85], off offset:16
	global_load_dwordx4 v[80:83], v[84:85], off
	v_or_b32_e32 v86, v86, v110
	v_mov_b32_e32 v67, v1
	v_ashrrev_i32_e32 v87, 31, v86
	v_lshl_add_u64 v[66:67], s[0:1], 0, v[66:67]
	s_waitcnt vmcnt(1) lgkmcnt(0)
	v_pk_mul_f32 v[72:73], v[72:73], v[76:77]
	s_waitcnt vmcnt(0)
	v_pk_mul_f32 v[68:69], v[68:69], v[80:81]
	v_pk_mul_f32 v[70:71], v[70:71], v[82:83]
	v_cvt_pk_bf16_f32 v68, v68, v69
	v_cvt_pk_bf16_f32 v69, v70, v71
	v_cvt_pk_bf16_f32 v70, v72, v73
	v_lshlrev_b64 v[72:73], 11, v[86:87]
	v_pk_mul_f32 v[74:75], v[74:75], v[78:79]
	v_lshl_add_u64 v[72:73], v[66:67], 0, v[72:73]
	v_cvt_pk_bf16_f32 v71, v74, v75
	v_lshl_add_u64 v[72:73], v[72:73], 0, v[98:99]
	global_store_dwordx4 v[72:73], v[68:71], off
	ds_read_b128 v[68:71], v0 offset:2304
	ds_read_b128 v[72:75], v0 offset:2320
	global_load_dwordx4 v[76:79], v[84:85], off offset:16
	global_load_dwordx4 v[80:83], v[84:85], off
	s_waitcnt vmcnt(1) lgkmcnt(0)
	v_pk_mul_f32 v[72:73], v[72:73], v[76:77]
	s_waitcnt vmcnt(0)
	v_pk_mul_f32 v[68:69], v[68:69], v[80:81]
	v_pk_mul_f32 v[70:71], v[70:71], v[82:83]
	v_cvt_pk_bf16_f32 v68, v68, v69
	v_cvt_pk_bf16_f32 v69, v70, v71
	v_cvt_pk_bf16_f32 v70, v72, v73
	v_or_b32_e32 v72, 16, v86
	v_ashrrev_i32_e32 v73, 31, v72
	v_lshlrev_b64 v[72:73], 11, v[72:73]
	v_pk_mul_f32 v[74:75], v[74:75], v[78:79]
	v_lshl_add_u64 v[66:67], v[66:67], 0, v[72:73]
	v_cvt_pk_bf16_f32 v71, v74, v75
	v_lshl_add_u64 v[66:67], v[66:67], 0, v[98:99]
	global_store_dwordx4 v[66:67], v[68:71], off
	v_or_b32_e32 v74, 64, v149
	v_mul_hi_i32 v0, v74, s2
	v_lshrrev_b32_e32 v66, 31, v0
	v_ashrrev_i32_e32 v0, 13, v0
	v_add_u32_e32 v0, v0, v66
	v_mul_i32_i24_e32 v66, 0x4100, v0
	v_sub_u32_e32 v66, v74, v66
	v_mul_i32_i24_e32 v0, 0xc00, v0
	v_cmp_lt_i32_e32 vcc, s3, v66
	v_mov_b32_e32 v68, v179
	s_nop 0
	v_cndmask_b32_e32 v66, v162, v0, vcc
	v_and_b32_e32 v0, 31, v68
	v_bfe_u32 v69, v68, 5, 1
	v_mul_u32_u24_e32 v69, 0x240, v69
	v_lshlrev_b32_e32 v0, 2, v0
	v_add3_u32 v0, v145, v69, v0
	ds_write2_b32 v0, v50, v51 offset1:36
	ds_write2_b32 v0, v52, v53 offset0:72 offset1:108
	v_add_u32_e32 v50, 0x400, v0
	v_ashrrev_i32_e32 v67, 31, v66
	ds_write2_b32 v50, v54, v55 offset0:32 offset1:68
	ds_write2_b32 v50, v56, v57 offset0:104 offset1:140
	v_add_u32_e32 v50, 0x800, v0
	v_add_u32_e32 v0, 0xc00, v0
	ds_write2_b32 v50, v58, v59 offset0:64 offset1:100
	ds_write2_b32 v50, v60, v61 offset0:136 offset1:172
	ds_write2_b32 v0, v62, v63 offset0:96 offset1:132
	ds_write2_b32 v0, v64, v65 offset0:168 offset1:204
	v_lshl_add_u64 v[50:51], v[66:67], 2, s[26:27]
	v_lshlrev_b32_e32 v0, 3, v68
	v_lshl_add_u64 v[50:51], v[50:51], 0, s[4:5]
	v_and_b32_e32 v54, 24, v0
	v_lshl_add_u64 v[52:53], v[50:51], 0, v[116:117]
	v_lshlrev_b32_e32 v0, 2, v54
	v_bfe_u32 v72, v68, 2, 4
	v_lshl_add_u64 v[70:71], v[52:53], 0, v[0:1]
	v_lshlrev_b32_e32 v52, 1, v54
	v_mul_u32_u24_e32 v54, 0x90, v72
	s_waitcnt lgkmcnt(0)
	v_add3_u32 v0, v145, v0, v54
	ds_read_b128 v[54:57], v0
	ds_read_b128 v[58:61], v0 offset:16
	global_load_dwordx4 v[62:65], v[70:71], off offset:16
	global_load_dwordx4 v[66:69], v[70:71], off
	v_or_b32_e32 v72, v72, v74
	v_mov_b32_e32 v53, v1
	v_ashrrev_i32_e32 v73, 31, v72
	v_lshl_add_u64 v[52:53], v[114:115], 0, v[52:53]
	s_waitcnt vmcnt(1) lgkmcnt(0)
	v_pk_mul_f32 v[58:59], v[58:59], v[62:63]
	s_waitcnt vmcnt(0)
	v_pk_mul_f32 v[54:55], v[54:55], v[66:67]
	v_pk_mul_f32 v[56:57], v[56:57], v[68:69]
	v_pk_mul_f32 v[60:61], v[60:61], v[64:65]
	v_cvt_pk_bf16_f32 v54, v54, v55
	v_cvt_pk_bf16_f32 v55, v56, v57
	v_cvt_pk_bf16_f32 v56, v58, v59
	v_lshlrev_b64 v[58:59], 11, v[72:73]
	v_cvt_pk_bf16_f32 v57, v60, v61
	v_lshl_add_u64 v[58:59], v[52:53], 0, v[58:59]
	global_store_dwordx4 v[58:59], v[54:57], off
	ds_read_b128 v[54:57], v0 offset:2304
	ds_read_b128 v[58:61], v0 offset:2320
	global_load_dwordx4 v[62:65], v[70:71], off offset:16
	global_load_dwordx4 v[66:69], v[70:71], off
	s_waitcnt vmcnt(1) lgkmcnt(0)
	v_pk_mul_f32 v[58:59], v[58:59], v[62:63]
	s_waitcnt vmcnt(0)
	v_pk_mul_f32 v[54:55], v[54:55], v[66:67]
	v_pk_mul_f32 v[56:57], v[56:57], v[68:69]
	v_cvt_pk_bf16_f32 v54, v54, v55
	v_cvt_pk_bf16_f32 v55, v56, v57
	v_cvt_pk_bf16_f32 v56, v58, v59
	v_or_b32_e32 v58, 16, v72
	v_ashrrev_i32_e32 v59, 31, v58
	v_pk_mul_f32 v[60:61], v[60:61], v[64:65]
	v_lshlrev_b64 v[58:59], 11, v[58:59]
	v_cvt_pk_bf16_f32 v57, v60, v61
	v_lshl_add_u64 v[52:53], v[52:53], 0, v[58:59]
	global_store_dwordx4 v[52:53], v[54:57], off
	s_nop 1
	v_mov_b32_e32 v54, v179
	s_nop 0
	v_and_b32_e32 v0, 31, v54
	v_bfe_u32 v52, v54, 5, 1
	v_mul_u32_u24_e32 v52, 0x240, v52
	v_lshlrev_b32_e32 v0, 2, v0
	v_add3_u32 v0, v145, v52, v0
	ds_write2_b32 v0, v34, v35 offset1:36
	ds_write2_b32 v0, v36, v37 offset0:72 offset1:108
	v_add_u32_e32 v34, 0x400, v0
	ds_write2_b32 v34, v38, v39 offset0:32 offset1:68
	ds_write2_b32 v34, v40, v41 offset0:104 offset1:140
	v_add_u32_e32 v34, 0x800, v0
	v_add_u32_e32 v0, 0xc00, v0
	ds_write2_b32 v34, v42, v43 offset0:64 offset1:100
	ds_write2_b32 v34, v44, v45 offset0:136 offset1:172
	ds_write2_b32 v0, v46, v47 offset0:96 offset1:132
	ds_write2_b32 v0, v48, v49 offset0:168 offset1:204
	v_lshlrev_b32_e32 v0, 3, v54
	v_and_b32_e32 v36, 24, v0
	v_lshlrev_b32_e32 v0, 2, v36
	v_lshl_add_u64 v[34:35], v[50:51], 0, v[0:1]
	v_bfe_u32 v54, v54, 2, 4
	v_lshl_add_u64 v[52:53], v[34:35], 0, v[100:101]
	v_lshlrev_b32_e32 v34, 1, v36
	v_mul_u32_u24_e32 v36, 0x90, v54
	s_waitcnt lgkmcnt(0)
	v_add3_u32 v0, v145, v0, v36
	ds_read_b128 v[36:39], v0
	ds_read_b128 v[40:43], v0 offset:16
	global_load_dwordx4 v[44:47], v[52:53], off offset:16
	global_load_dwordx4 v[48:51], v[52:53], off
	v_or_b32_e32 v54, v54, v74
	v_mov_b32_e32 v35, v1
	v_ashrrev_i32_e32 v55, 31, v54
	v_lshl_add_u64 v[34:35], s[0:1], 0, v[34:35]
	s_waitcnt vmcnt(1) lgkmcnt(0)
	v_pk_mul_f32 v[40:41], v[40:41], v[44:45]
	s_waitcnt vmcnt(0)
	v_pk_mul_f32 v[36:37], v[36:37], v[48:49]
	v_pk_mul_f32 v[38:39], v[38:39], v[50:51]
	v_cvt_pk_bf16_f32 v36, v36, v37
	v_cvt_pk_bf16_f32 v37, v38, v39
	v_cvt_pk_bf16_f32 v38, v40, v41
	v_lshlrev_b64 v[40:41], 11, v[54:55]
	v_pk_mul_f32 v[42:43], v[42:43], v[46:47]
	v_lshl_add_u64 v[40:41], v[34:35], 0, v[40:41]
	v_cvt_pk_bf16_f32 v39, v42, v43
	v_lshl_add_u64 v[40:41], v[40:41], 0, v[98:99]
	global_store_dwordx4 v[40:41], v[36:39], off
	ds_read_b128 v[36:39], v0 offset:2304
	ds_read_b128 v[40:43], v0 offset:2320
	global_load_dwordx4 v[44:47], v[52:53], off offset:16
	global_load_dwordx4 v[48:51], v[52:53], off
	s_waitcnt vmcnt(1) lgkmcnt(0)
	v_pk_mul_f32 v[40:41], v[40:41], v[44:45]
	s_waitcnt vmcnt(0)
	v_pk_mul_f32 v[36:37], v[36:37], v[48:49]
	v_pk_mul_f32 v[38:39], v[38:39], v[50:51]
	v_cvt_pk_bf16_f32 v36, v36, v37
	v_cvt_pk_bf16_f32 v37, v38, v39
	v_cvt_pk_bf16_f32 v38, v40, v41
	v_or_b32_e32 v40, 16, v54
	v_ashrrev_i32_e32 v41, 31, v40
	v_lshlrev_b64 v[40:41], 11, v[40:41]
	v_pk_mul_f32 v[42:43], v[42:43], v[46:47]
	v_lshl_add_u64 v[34:35], v[34:35], 0, v[40:41]
	v_cvt_pk_bf16_f32 v39, v42, v43
	v_lshl_add_u64 v[34:35], v[34:35], 0, v[98:99]
	global_store_dwordx4 v[34:35], v[36:39], off
	v_or_b32_e32 v42, 0x60, v149
	v_mul_hi_i32 v0, v42, s2
	v_lshrrev_b32_e32 v34, 31, v0
	v_ashrrev_i32_e32 v0, 13, v0
	v_add_u32_e32 v0, v0, v34
	v_mul_i32_i24_e32 v34, 0x4100, v0
	v_sub_u32_e32 v34, v42, v34
	v_mul_i32_i24_e32 v0, 0xc00, v0
	v_cmp_lt_i32_e32 vcc, s3, v34
	v_mov_b32_e32 v36, v179
	s_nop 0
	v_cndmask_b32_e32 v34, v162, v0, vcc
	v_and_b32_e32 v0, 31, v36
	v_bfe_u32 v37, v36, 5, 1
	v_mul_u32_u24_e32 v37, 0x240, v37
	v_lshlrev_b32_e32 v0, 2, v0
	v_add3_u32 v0, v145, v37, v0
	ds_write2_b32 v0, v18, v19 offset1:36
	ds_write2_b32 v0, v20, v21 offset0:72 offset1:108
	v_add_u32_e32 v18, 0x400, v0
	v_ashrrev_i32_e32 v35, 31, v34
	ds_write2_b32 v18, v22, v23 offset0:32 offset1:68
	ds_write2_b32 v18, v24, v25 offset0:104 offset1:140
	v_add_u32_e32 v18, 0x800, v0
	v_add_u32_e32 v0, 0xc00, v0
	ds_write2_b32 v18, v26, v27 offset0:64 offset1:100
	ds_write2_b32 v18, v28, v29 offset0:136 offset1:172
	ds_write2_b32 v0, v30, v31 offset0:96 offset1:132
	ds_write2_b32 v0, v32, v33 offset0:168 offset1:204
	v_lshl_add_u64 v[18:19], v[34:35], 2, s[26:27]
	v_lshlrev_b32_e32 v0, 3, v36
	v_lshl_add_u64 v[18:19], v[18:19], 0, s[4:5]
	v_and_b32_e32 v22, 24, v0
	v_lshl_add_u64 v[20:21], v[18:19], 0, v[116:117]
	v_lshlrev_b32_e32 v0, 2, v22
	v_bfe_u32 v40, v36, 2, 4
	v_lshl_add_u64 v[38:39], v[20:21], 0, v[0:1]
	v_lshlrev_b32_e32 v20, 1, v22
	v_mul_u32_u24_e32 v22, 0x90, v40
	s_waitcnt lgkmcnt(0)
	v_add3_u32 v0, v145, v0, v22
	ds_read_b128 v[22:25], v0
	ds_read_b128 v[26:29], v0 offset:16
	global_load_dwordx4 v[30:33], v[38:39], off offset:16
	global_load_dwordx4 v[34:37], v[38:39], off
	v_or_b32_e32 v40, v40, v42
	v_mov_b32_e32 v21, v1
	v_ashrrev_i32_e32 v41, 31, v40
	v_lshl_add_u64 v[20:21], v[114:115], 0, v[20:21]
	s_waitcnt vmcnt(1) lgkmcnt(0)
	v_pk_mul_f32 v[26:27], v[26:27], v[30:31]
	s_waitcnt vmcnt(0)
	v_pk_mul_f32 v[22:23], v[22:23], v[34:35]
	v_pk_mul_f32 v[24:25], v[24:25], v[36:37]
	v_pk_mul_f32 v[28:29], v[28:29], v[32:33]
	v_cvt_pk_bf16_f32 v22, v22, v23
	v_cvt_pk_bf16_f32 v23, v24, v25
	v_cvt_pk_bf16_f32 v24, v26, v27
	v_lshlrev_b64 v[26:27], 11, v[40:41]
	v_cvt_pk_bf16_f32 v25, v28, v29
	v_lshl_add_u64 v[26:27], v[20:21], 0, v[26:27]
	global_store_dwordx4 v[26:27], v[22:25], off
	ds_read_b128 v[22:25], v0 offset:2304
	ds_read_b128 v[26:29], v0 offset:2320
	global_load_dwordx4 v[30:33], v[38:39], off offset:16
	global_load_dwordx4 v[34:37], v[38:39], off
	s_waitcnt vmcnt(1) lgkmcnt(0)
	v_pk_mul_f32 v[26:27], v[26:27], v[30:31]
	s_waitcnt vmcnt(0)
	v_pk_mul_f32 v[22:23], v[22:23], v[34:35]
	v_pk_mul_f32 v[24:25], v[24:25], v[36:37]
	v_cvt_pk_bf16_f32 v22, v22, v23
	v_cvt_pk_bf16_f32 v23, v24, v25
	v_cvt_pk_bf16_f32 v24, v26, v27
	v_or_b32_e32 v26, 16, v40
	v_ashrrev_i32_e32 v27, 31, v26
	v_pk_mul_f32 v[28:29], v[28:29], v[32:33]
	v_lshlrev_b64 v[26:27], 11, v[26:27]
	v_cvt_pk_bf16_f32 v25, v28, v29
	v_lshl_add_u64 v[20:21], v[20:21], 0, v[26:27]
	global_store_dwordx4 v[20:21], v[22:25], off
	s_nop 1
	v_mov_b32_e32 v22, v179
	s_nop 0
	v_and_b32_e32 v0, 31, v22
	v_bfe_u32 v20, v22, 5, 1
	v_mul_u32_u24_e32 v20, 0x240, v20
	v_lshlrev_b32_e32 v0, 2, v0
	v_add3_u32 v0, v145, v20, v0
	ds_write2_b32 v0, v2, v3 offset1:36
	ds_write2_b32 v0, v4, v5 offset0:72 offset1:108
	v_add_u32_e32 v2, 0x400, v0
	ds_write2_b32 v2, v6, v7 offset0:32 offset1:68
	ds_write2_b32 v2, v8, v9 offset0:104 offset1:140
	v_add_u32_e32 v2, 0x800, v0
	v_add_u32_e32 v0, 0xc00, v0
	ds_write2_b32 v2, v10, v11 offset0:64 offset1:100
	ds_write2_b32 v2, v12, v13 offset0:136 offset1:172
	ds_write2_b32 v0, v14, v15 offset0:96 offset1:132
	ds_write2_b32 v0, v16, v17 offset0:168 offset1:204
	v_lshlrev_b32_e32 v0, 3, v22
	v_and_b32_e32 v4, 24, v0
	v_lshlrev_b32_e32 v0, 2, v4
	v_lshl_add_u64 v[2:3], v[18:19], 0, v[0:1]
	v_bfe_u32 v22, v22, 2, 4
	v_lshl_add_u64 v[20:21], v[2:3], 0, v[100:101]
	v_lshlrev_b32_e32 v2, 1, v4
	v_mul_u32_u24_e32 v4, 0x90, v22
	s_waitcnt lgkmcnt(0)
	v_add3_u32 v0, v145, v0, v4
	ds_read_b128 v[4:7], v0
	ds_read_b128 v[8:11], v0 offset:16
	global_load_dwordx4 v[12:15], v[20:21], off offset:16
	global_load_dwordx4 v[16:19], v[20:21], off
	v_or_b32_e32 v22, v22, v42
	v_mov_b32_e32 v3, v1
	v_ashrrev_i32_e32 v23, 31, v22
	v_lshl_add_u64 v[2:3], s[0:1], 0, v[2:3]
	s_waitcnt vmcnt(1) lgkmcnt(0)
	v_pk_mul_f32 v[8:9], v[8:9], v[12:13]
	s_waitcnt vmcnt(0)
	v_pk_mul_f32 v[4:5], v[4:5], v[16:17]
	v_pk_mul_f32 v[6:7], v[6:7], v[18:19]
	v_cvt_pk_bf16_f32 v4, v4, v5
	v_cvt_pk_bf16_f32 v5, v6, v7
	v_cvt_pk_bf16_f32 v6, v8, v9
	v_lshlrev_b64 v[8:9], 11, v[22:23]
	v_pk_mul_f32 v[10:11], v[10:11], v[14:15]
	v_lshl_add_u64 v[8:9], v[2:3], 0, v[8:9]
	v_cvt_pk_bf16_f32 v7, v10, v11
	v_lshl_add_u64 v[8:9], v[8:9], 0, v[98:99]
	global_store_dwordx4 v[8:9], v[4:7], off
	ds_read_b128 v[4:7], v0 offset:2304
	ds_read_b128 v[8:11], v0 offset:2320
	global_load_dwordx4 v[12:15], v[20:21], off offset:16
	global_load_dwordx4 v[16:19], v[20:21], off
	s_waitcnt vmcnt(1) lgkmcnt(0)
	v_pk_mul_f32 v[8:9], v[8:9], v[12:13]
	s_waitcnt vmcnt(0)
	v_pk_mul_f32 v[4:5], v[4:5], v[16:17]
	v_pk_mul_f32 v[6:7], v[6:7], v[18:19]
	v_cvt_pk_bf16_f32 v4, v4, v5
	v_cvt_pk_bf16_f32 v5, v6, v7
	v_cvt_pk_bf16_f32 v6, v8, v9
	v_or_b32_e32 v8, 16, v22
	v_ashrrev_i32_e32 v9, 31, v8
	v_lshlrev_b64 v[8:9], 11, v[8:9]
	v_pk_mul_f32 v[10:11], v[10:11], v[14:15]
	v_lshl_add_u64 v[2:3], v[2:3], 0, v[8:9]
	v_cvt_pk_bf16_f32 v7, v10, v11
	v_lshl_add_u64 v[2:3], v[2:3], 0, v[98:99]
	global_store_dwordx4 v[2:3], v[4:7], off
	s_add_i32 s7, s7, s6
	s_cmpk_gt_i32 s7, 0x207
	s_cselect_b64 s[0:1], -1, 0
	s_branch .LBB0_907

.LBB0_1120:
	s_add_i32 s2, s13, s14
	s_cmpk_gt_i32 s2, 0x81f
	s_mov_b64 s[0:1], -1
	s_cbranch_scc1 .LBB0_1119
	s_ashr_i32 s0, s2, 31
	s_lshr_b32 s0, s0, 25
	s_add_i32 s0, s2, s0
	s_ashr_i32 s1, s0, 7
	s_lshl_b32 s1, s1, 3
	s_sub_i32 s3, 0x82, s1
	s_min_u32 s3, s3, 8
	v_cvt_f32_ubyte0_e32 v0, s3
	v_rcp_iflag_f32_e32 v0, v0
	s_sub_i32 s6, 0, s3
	s_and_b32 s0, s0, 0xffffff80
	s_sub_i32 s0, s2, s0
	v_mul_f32_e32 v0, 0x4f7ffffe, v0
	v_cvt_u32_f32_e32 v0, v0
	s_abs_i32 s4, s0
	s_ashr_i32 s2, s0, 31
	s_waitcnt vmcnt(63) expcnt(7) lgkmcnt(15)
	v_readfirstlane_b32 s7, v0
	s_mul_i32 s6, s6, s7
	s_mul_hi_u32 s6, s7, s6
	s_add_i32 s7, s7, s6
	s_mul_hi_u32 s6, s4, s7
	s_mul_i32 s7, s6, s3
	s_sub_i32 s4, s4, s7
	s_add_i32 s7, s6, 1
	s_sub_i32 s8, s4, s3
	s_cmp_ge_u32 s4, s3
	s_cselect_b32 s6, s7, s6
	s_cselect_b32 s4, s8, s4
	s_add_i32 s7, s6, 1
	s_cmp_ge_u32 s4, s3
	s_cselect_b32 s4, s7, s6
	s_xor_b32 s4, s4, s2
	s_sub_i32 s4, s4, s2
	s_mul_i32 s2, s4, s3
	s_sub_i32 s0, s0, s2
	s_add_i32 s0, s0, s1
	s_lshl_b32 s0, s0, 8
	s_lshl_b32 s6, s4, 8
	s_ashr_i32 s1, s0, 31
	s_ashr_i32 s7, s6, 31
	s_lshl_b64 s[2:3], s[0:1], 11
	s_lshl_b64 s[8:9], s[6:7], 11
	s_add_u32 s10, s64, s2
	v_mov_b32_e32 v0, v143
	s_addc_u32 s11, s65, s3
	s_barrier
	v_readlane_b32 s16, v251, 2
	v_lshl_add_u64 v[2:3], v[0:1], 1, s[10:11]
	v_add_u32_e32 v0, 32, v158
	v_readlane_b32 s30, v251, 16
	v_readfirstlane_b32 s1, v0
	s_mov_b32 m0, s1
	v_mov_b32_e32 v0, v159
	global_load_lds_dwordx4 v[2:3], off
	v_readlane_b32 s17, v251, 3
	v_lshl_add_u64 v[2:3], v[0:1], 1, s[10:11]
	v_add_u32_e32 v0, 32, v160
	v_readlane_b32 s31, v251, 17
	v_readfirstlane_b32 s1, v0
	s_mov_b32 m0, s1
	v_mov_b32_e32 v0, v161
	global_load_lds_dwordx4 v[2:3], off
	s_add_u32 s16, s30, s8
	v_lshl_add_u64 v[2:3], v[0:1], 1, s[10:11]
	v_add_u32_e32 v0, 32, v162
	s_addc_u32 s17, s31, s9
	v_readfirstlane_b32 s1, v0
	s_mov_b32 m0, s1
	v_mov_b32_e32 v0, v163
	global_load_lds_dwordx4 v[2:3], off
	v_readlane_b32 s7, v254, 3
	v_lshl_add_u64 v[2:3], v[0:1], 1, s[10:11]
	v_add_u32_e32 v0, 32, v164
	s_mov_b32 s5, 0
	v_readfirstlane_b32 s1, v0
	s_mov_b32 m0, s1
	v_mov_b32_e32 v0, v143
	global_load_lds_dwordx4 v[2:3], off
	v_readlane_b32 s18, v251, 4
	v_lshl_add_u64 v[2:3], v[0:1], 1, s[16:17]
	v_add_u32_e32 v0, s7, v158
	v_readlane_b32 s19, v251, 5
	v_readfirstlane_b32 s1, v0
	s_mov_b32 m0, s1
	v_mov_b32_e32 v0, v159
	global_load_lds_dwordx4 v[2:3], off
	v_readlane_b32 s20, v251, 6
	v_lshl_add_u64 v[2:3], v[0:1], 1, s[16:17]
	v_add_u32_e32 v0, s7, v160
	v_readlane_b32 s21, v251, 7
	v_readfirstlane_b32 s1, v0
	s_mov_b32 m0, s1
	v_mov_b32_e32 v0, v161
	global_load_lds_dwordx4 v[2:3], off
	v_readlane_b32 s22, v251, 8
	v_lshl_add_u64 v[2:3], v[0:1], 1, s[16:17]
	v_add_u32_e32 v0, s7, v162
	v_readlane_b32 s23, v251, 9
	v_readfirstlane_b32 s1, v0
	s_mov_b32 m0, s1
	v_mov_b32_e32 v0, v163
	global_load_lds_dwordx4 v[2:3], off
	v_readlane_b32 s24, v251, 10
	v_lshl_add_u64 v[2:3], v[0:1], 1, s[16:17]
	v_add_u32_e32 v0, s7, v164
	v_readlane_b32 s25, v251, 11
	v_readfirstlane_b32 s1, v0
	s_mov_b32 m0, s1
	v_readlane_b32 s1, v253, 25
	global_load_lds_dwordx4 v[2:3], off
	s_add_u32 s1, s1, s2
	v_readlane_b32 s2, v253, 26
	s_waitcnt vmcnt(0)
	s_addc_u32 s7, s2, s3
	v_readlane_b32 s2, v253, 45
	s_add_u32 s8, s2, s8
	v_readlane_b32 s2, v253, 46
	v_mov_b32_e32 v2, 0
	s_addc_u32 s9, s2, s9
	s_mov_b64 s[2:3], 0
	v_mov_b32_e32 v3, v2
	v_mov_b32_e32 v4, v2
	v_mov_b32_e32 v5, v2
	v_mov_b32_e32 v6, v2
	v_mov_b32_e32 v7, v2
	v_mov_b32_e32 v8, v2
	v_mov_b32_e32 v9, v2
	v_mov_b32_e32 v10, v2
	v_mov_b32_e32 v11, v2
	v_mov_b32_e32 v12, v2
	v_mov_b32_e32 v13, v2
	s_waitcnt vmcnt(0)
	v_mov_b32_e32 v14, v2
	v_mov_b32_e32 v15, v2
	v_mov_b32_e32 v16, v2
	v_mov_b32_e32 v17, v2
	v_mov_b32_e32 v18, v2
	v_mov_b32_e32 v19, v2
	v_mov_b32_e32 v20, v2
	v_mov_b32_e32 v21, v2
	v_mov_b32_e32 v22, v2
	v_mov_b32_e32 v23, v2
	v_mov_b32_e32 v24, v2
	v_mov_b32_e32 v25, v2
	v_mov_b32_e32 v26, v2
	v_mov_b32_e32 v27, v2
	v_mov_b32_e32 v28, v2
	v_mov_b32_e32 v29, v2
	v_mov_b32_e32 v30, v2
	v_mov_b32_e32 v31, v2
	v_mov_b32_e32 v32, v2
	v_mov_b32_e32 v33, v2
	v_mov_b32_e32 v34, v2
	v_mov_b32_e32 v35, v2
	v_mov_b32_e32 v36, v2
	v_mov_b32_e32 v37, v2
	v_mov_b32_e32 v38, v2
	v_mov_b32_e32 v39, v2
	v_mov_b32_e32 v40, v2
	v_mov_b32_e32 v41, v2
	v_mov_b32_e32 v42, v2
	v_mov_b32_e32 v43, v2
	v_mov_b32_e32 v44, v2
	v_mov_b32_e32 v45, v2
	v_mov_b32_e32 v46, v2
	v_mov_b32_e32 v47, v2
	v_mov_b32_e32 v48, v2
	v_mov_b32_e32 v49, v2
	v_mov_b32_e32 v50, v2
	v_mov_b32_e32 v51, v2
	v_mov_b32_e32 v52, v2
	v_mov_b32_e32 v53, v2
	v_mov_b32_e32 v54, v2
	v_mov_b32_e32 v55, v2
	v_mov_b32_e32 v56, v2
	v_mov_b32_e32 v57, v2
	v_mov_b32_e32 v58, v2
	v_mov_b32_e32 v59, v2
	v_mov_b32_e32 v60, v2
	v_mov_b32_e32 v61, v2
	v_mov_b32_e32 v62, v2
	v_mov_b32_e32 v63, v2
	v_mov_b32_e32 v64, v2
	v_mov_b32_e32 v65, v2
	v_mov_b32_e32 v66, v2
	v_mov_b32_e32 v67, v2
	v_mov_b32_e32 v68, v2
	v_mov_b32_e32 v69, v2
	v_mov_b32_e32 v70, v2
	v_mov_b32_e32 v71, v2
	v_mov_b32_e32 v72, v2
	v_mov_b32_e32 v73, v2
	v_mov_b32_e32 v74, v2
	v_mov_b32_e32 v75, v2
	v_mov_b32_e32 v76, v2
	v_mov_b32_e32 v77, v2
	v_mov_b32_e32 v78, v2
	v_mov_b32_e32 v79, v2
	v_mov_b32_e32 v80, v2
	v_mov_b32_e32 v81, v2
	v_mov_b32_e32 v82, v2
	v_mov_b32_e32 v83, v2
	v_mov_b32_e32 v84, v2
	v_mov_b32_e32 v85, v2
	v_mov_b32_e32 v86, v2
	v_mov_b32_e32 v87, v2
	v_mov_b32_e32 v88, v2
	v_mov_b32_e32 v89, v2
	v_mov_b32_e32 v90, v2
	v_mov_b32_e32 v91, v2
	v_mov_b32_e32 v92, v2
	v_mov_b32_e32 v93, v2
	v_mov_b32_e32 v94, v2
	v_mov_b32_e32 v95, v2
	v_mov_b32_e32 v96, v2
	v_mov_b32_e32 v97, v2
	v_mov_b32_e32 v98, v2
	v_mov_b32_e32 v99, v2
	v_mov_b32_e32 v100, v2
	v_mov_b32_e32 v101, v2
	v_mov_b32_e32 v102, v2
	v_mov_b32_e32 v103, v2
	v_mov_b32_e32 v104, v2
	v_mov_b32_e32 v105, v2
	v_mov_b32_e32 v106, v2
	v_mov_b32_e32 v107, v2
	v_mov_b32_e32 v108, v2
	v_mov_b32_e32 v109, v2
	v_mov_b32_e32 v110, v2
	v_mov_b32_e32 v111, v2
	v_mov_b32_e32 v112, v2
	v_mov_b32_e32 v113, v2
	v_mov_b32_e32 v114, v2
	v_mov_b32_e32 v115, v2
	v_mov_b32_e32 v116, v2
	v_mov_b32_e32 v117, v2
	v_mov_b32_e32 v118, v2
	v_mov_b32_e32 v119, v2
	v_mov_b32_e32 v120, v2
	v_mov_b32_e32 v121, v2
	v_mov_b32_e32 v122, v2
	v_mov_b32_e32 v123, v2
	v_mov_b32_e32 v124, v2
	v_mov_b32_e32 v125, v2
	v_mov_b32_e32 v126, v2
	v_mov_b32_e32 v127, v2
	v_mov_b32_e32 v128, v2
	v_mov_b32_e32 v129, v2
	v_readlane_b32 s26, v251, 12
	v_readlane_b32 s27, v251, 13
	v_readlane_b32 s28, v251, 14
	v_readlane_b32 s29, v251, 15
	s_waitcnt lgkmcnt(0)
	s_barrier
	v_lshlrev_b32_e32 v142, 1, v143
	v_readfirstlane_b32 s15, v158
	v_add_u32_e32 v156, v165, v167
	v_add_u32_e32 v195, v166, v167
	v_add_u32_e32 v157, v165, v172
	v_add_u32_e32 v200, v166, v172
	v_add_u32_e32 v193, v165, v173
	v_add_u32_e32 v201, v166, v173
	v_add_u32_e32 v194, v165, v174
	v_add_u32_e32 v202, v166, v174
	s_mov_b32 s5, 7
	s_add_u32 m0, s15, 0x8020
	s_add_u32 s10, s1, s2
	s_addc_u32 s11, s7, s3
	global_load_lds_dwordx4 v142, s[10:11]
	s_add_u32 m0, s15, 0xa020
	s_add_u32 s10, s10, 0x20000
	s_addc_u32 s11, s11, 0
	global_load_lds_dwordx4 v142, s[10:11]
	s_add_u32 m0, s15, 0xc020
	s_add_u32 s10, s10, 0x20000
	s_addc_u32 s11, s11, 0
	global_load_lds_dwordx4 v142, s[10:11]
	s_add_u32 m0, s15, 0xe020
	s_add_u32 s10, s10, 0x20000
	s_addc_u32 s11, s11, 0
	global_load_lds_dwordx4 v142, s[10:11]
	s_add_u32 m0, s15, 0x18020
	s_add_u32 s10, s8, s2
	s_addc_u32 s11, s9, s3
	global_load_lds_dwordx4 v142, s[10:11]
	ds_read_b128 v[130:133], v156 offset:0
	ds_read_b128 v[148:151], v195 offset:0
	ds_read_b128 v[152:155], v195 offset:4096
	ds_read_b128 v[134:137], v156 offset:4096
	ds_read_b128 v[138:141], v156 offset:8192
	ds_read_b128 v[144:147], v156 offset:12288
.Lg1122_loop:
	s_waitcnt lgkmcnt(4)
	v_mfma_f32_32x32x16_bf16 v[114:129], v[130:133], v[148:151], v[114:129]
	ds_read_b128 v[180:183], v157 offset:0
	s_waitcnt lgkmcnt(4)
	v_mfma_f32_32x32x16_bf16 v[98:113], v[130:133], v[152:155], v[98:113]
	ds_read_b128 v[226:229], v200 offset:0
	s_add_u32 m0, s15, 0x1a020
	s_add_u32 s10, s10, 0x20000
	s_addc_u32 s11, s11, 0
	global_load_lds_dwordx4 v142, s[10:11]
	s_waitcnt lgkmcnt(4)
	v_mfma_f32_32x32x16_bf16 v[82:97], v[134:137], v[148:151], v[82:97]
	ds_read_b128 v[230:233], v200 offset:4096
	v_mfma_f32_32x32x16_bf16 v[66:81], v[134:137], v[152:155], v[66:81]
	ds_read_b128 v[184:187], v157 offset:4096
	s_add_u32 m0, s15, 0x1c020
	s_add_u32 s10, s10, 0x20000
	s_addc_u32 s11, s11, 0
	global_load_lds_dwordx4 v142, s[10:11]
	s_waitcnt lgkmcnt(5)
	v_mfma_f32_32x32x16_bf16 v[50:65], v[138:141], v[148:151], v[50:65]
	ds_read_b128 v[188:191], v157 offset:8192
	v_mfma_f32_32x32x16_bf16 v[34:49], v[138:141], v[152:155], v[34:49]
	ds_read_b128 v[222:225], v157 offset:12288
	s_add_u32 m0, s15, 0x1e020
	s_add_u32 s10, s10, 0x20000
	s_addc_u32 s11, s11, 0
	global_load_lds_dwordx4 v142, s[10:11]
	s_add_u32 s2, s2, 0x80
	s_addc_u32 s3, s3, 0
	s_waitcnt lgkmcnt(6)
	v_mfma_f32_32x32x16_bf16 v[18:33], v[144:147], v[148:151], v[18:33]
	v_mfma_f32_32x32x16_bf16 v[2:17], v[144:147], v[152:155], v[2:17]
	s_waitcnt lgkmcnt(4)
	v_mfma_f32_32x32x16_bf16 v[114:129], v[180:183], v[226:229], v[114:129]
	ds_read_b128 v[130:133], v193 offset:0
	s_waitcnt lgkmcnt(4)
	v_mfma_f32_32x32x16_bf16 v[98:113], v[180:183], v[230:233], v[98:113]
	ds_read_b128 v[148:151], v201 offset:0
	s_waitcnt lgkmcnt(4)
	v_mfma_f32_32x32x16_bf16 v[82:97], v[184:187], v[226:229], v[82:97]
	ds_read_b128 v[152:155], v201 offset:4096
	v_mfma_f32_32x32x16_bf16 v[66:81], v[184:187], v[230:233], v[66:81]
	ds_read_b128 v[134:137], v193 offset:4096
	s_waitcnt lgkmcnt(5)
	v_mfma_f32_32x32x16_bf16 v[50:65], v[188:191], v[226:229], v[50:65]
	ds_read_b128 v[138:141], v193 offset:8192
	v_mfma_f32_32x32x16_bf16 v[34:49], v[188:191], v[230:233], v[34:49]
	ds_read_b128 v[144:147], v193 offset:12288
	s_waitcnt lgkmcnt(6)
	v_mfma_f32_32x32x16_bf16 v[18:33], v[222:225], v[226:229], v[18:33]
	v_mfma_f32_32x32x16_bf16 v[2:17], v[222:225], v[230:233], v[2:17]
	s_waitcnt lgkmcnt(4)
	v_mfma_f32_32x32x16_bf16 v[114:129], v[130:133], v[148:151], v[114:129]
	ds_read_b128 v[180:183], v194 offset:0
	ds_read_b128 v[226:229], v202 offset:0
	s_waitcnt lgkmcnt(5)
	v_mfma_f32_32x32x16_bf16 v[98:113], v[130:133], v[152:155], v[98:113]
	ds_read_b128 v[230:233], v202 offset:4096
	ds_read_b128 v[184:187], v194 offset:4096
	s_waitcnt lgkmcnt(6)
	v_mfma_f32_32x32x16_bf16 v[82:97], v[134:137], v[148:151], v[82:97]
	ds_read_b128 v[188:191], v194 offset:8192
	ds_read_b128 v[222:225], v194 offset:12288
	v_mfma_f32_32x32x16_bf16 v[66:81], v[134:137], v[152:155], v[66:81]
	s_waitcnt lgkmcnt(7)
	v_mfma_f32_32x32x16_bf16 v[50:65], v[138:141], v[148:151], v[50:65]
	v_mfma_f32_32x32x16_bf16 v[34:49], v[138:141], v[152:155], v[34:49]
	s_waitcnt lgkmcnt(6)
	v_mfma_f32_32x32x16_bf16 v[18:33], v[144:147], v[148:151], v[18:33]
	v_mfma_f32_32x32x16_bf16 v[2:17], v[144:147], v[152:155], v[2:17]
	s_waitcnt vmcnt(0) lgkmcnt(0)
	s_barrier
	v_mfma_f32_32x32x16_bf16 v[114:129], v[180:183], v[226:229], v[114:129]
	ds_read_b128 v[130:133], v156 offset:32768
	s_add_u32 m0, s15, 0x20
	s_add_u32 s10, s1, s2
	s_addc_u32 s11, s7, s3
	global_load_lds_dwordx4 v142, s[10:11]
	v_mfma_f32_32x32x16_bf16 v[98:113], v[180:183], v[230:233], v[98:113]
	ds_read_b128 v[148:151], v195 offset:32768
	s_add_u32 m0, s15, 0x2020
	s_add_u32 s10, s10, 0x20000
	s_addc_u32 s11, s11, 0
	global_load_lds_dwordx4 v142, s[10:11]
	v_mfma_f32_32x32x16_bf16 v[82:97], v[184:187], v[226:229], v[82:97]
	ds_read_b128 v[152:155], v195 offset:36864
	s_add_u32 m0, s15, 0x4020
	s_add_u32 s10, s10, 0x20000
	s_addc_u32 s11, s11, 0
	global_load_lds_dwordx4 v142, s[10:11]
	v_mfma_f32_32x32x16_bf16 v[66:81], v[184:187], v[230:233], v[66:81]
	ds_read_b128 v[134:137], v156 offset:36864
	s_add_u32 m0, s15, 0x6020
	s_add_u32 s10, s10, 0x20000
	s_addc_u32 s11, s11, 0
	global_load_lds_dwordx4 v142, s[10:11]
	v_mfma_f32_32x32x16_bf16 v[50:65], v[188:191], v[226:229], v[50:65]
	ds_read_b128 v[138:141], v156 offset:40960
	s_add_u32 m0, s15, 0x10020
	s_add_u32 s10, s8, s2
	s_addc_u32 s11, s9, s3
	global_load_lds_dwordx4 v142, s[10:11]
	v_mfma_f32_32x32x16_bf16 v[34:49], v[188:191], v[230:233], v[34:49]
	ds_read_b128 v[144:147], v156 offset:45056
	v_mfma_f32_32x32x16_bf16 v[18:33], v[222:225], v[226:229], v[18:33]
	v_mfma_f32_32x32x16_bf16 v[2:17], v[222:225], v[230:233], v[2:17]
	s_waitcnt lgkmcnt(4)
	v_mfma_f32_32x32x16_bf16 v[114:129], v[130:133], v[148:151], v[114:129]
	ds_read_b128 v[180:183], v157 offset:32768
	s_waitcnt lgkmcnt(4)
	v_mfma_f32_32x32x16_bf16 v[98:113], v[130:133], v[152:155], v[98:113]
	ds_read_b128 v[226:229], v200 offset:32768
	s_add_u32 m0, s15, 0x12020
	s_add_u32 s10, s10, 0x20000
	s_addc_u32 s11, s11, 0
	global_load_lds_dwordx4 v142, s[10:11]
	s_waitcnt lgkmcnt(4)
	v_mfma_f32_32x32x16_bf16 v[82:97], v[134:137], v[148:151], v[82:97]
	ds_read_b128 v[230:233], v200 offset:36864
	v_mfma_f32_32x32x16_bf16 v[66:81], v[134:137], v[152:155], v[66:81]
	ds_read_b128 v[184:187], v157 offset:36864
	s_add_u32 m0, s15, 0x14020
	s_add_u32 s10, s10, 0x20000
	s_addc_u32 s11, s11, 0
	global_load_lds_dwordx4 v142, s[10:11]
	s_waitcnt lgkmcnt(5)
	v_mfma_f32_32x32x16_bf16 v[50:65], v[138:141], v[148:151], v[50:65]
	ds_read_b128 v[188:191], v157 offset:40960
	v_mfma_f32_32x32x16_bf16 v[34:49], v[138:141], v[152:155], v[34:49]
	ds_read_b128 v[222:225], v157 offset:45056
	s_add_u32 m0, s15, 0x16020
	s_add_u32 s10, s10, 0x20000
	s_addc_u32 s11, s11, 0
	global_load_lds_dwordx4 v142, s[10:11]
	s_add_u32 s2, s2, 0x80
	s_addc_u32 s3, s3, 0
	s_waitcnt lgkmcnt(6)
	v_mfma_f32_32x32x16_bf16 v[18:33], v[144:147], v[148:151], v[18:33]
	v_mfma_f32_32x32x16_bf16 v[2:17], v[144:147], v[152:155], v[2:17]
	s_waitcnt lgkmcnt(4)
	v_mfma_f32_32x32x16_bf16 v[114:129], v[180:183], v[226:229], v[114:129]
	ds_read_b128 v[130:133], v193 offset:32768
	s_waitcnt lgkmcnt(4)
	v_mfma_f32_32x32x16_bf16 v[98:113], v[180:183], v[230:233], v[98:113]
	ds_read_b128 v[148:151], v201 offset:32768
	s_waitcnt lgkmcnt(4)
	v_mfma_f32_32x32x16_bf16 v[82:97], v[184:187], v[226:229], v[82:97]
	ds_read_b128 v[152:155], v201 offset:36864
	v_mfma_f32_32x32x16_bf16 v[66:81], v[184:187], v[230:233], v[66:81]
	ds_read_b128 v[134:137], v193 offset:36864
	s_waitcnt lgkmcnt(5)
	v_mfma_f32_32x32x16_bf16 v[50:65], v[188:191], v[226:229], v[50:65]
	ds_read_b128 v[138:141], v193 offset:40960
	v_mfma_f32_32x32x16_bf16 v[34:49], v[188:191], v[230:233], v[34:49]
	ds_read_b128 v[144:147], v193 offset:45056
	s_waitcnt lgkmcnt(6)
	v_mfma_f32_32x32x16_bf16 v[18:33], v[222:225], v[226:229], v[18:33]
	v_mfma_f32_32x32x16_bf16 v[2:17], v[222:225], v[230:233], v[2:17]
	s_waitcnt lgkmcnt(4)
	v_mfma_f32_32x32x16_bf16 v[114:129], v[130:133], v[148:151], v[114:129]
	ds_read_b128 v[180:183], v194 offset:32768
	ds_read_b128 v[226:229], v202 offset:32768
	s_waitcnt lgkmcnt(5)
	v_mfma_f32_32x32x16_bf16 v[98:113], v[130:133], v[152:155], v[98:113]
	ds_read_b128 v[230:233], v202 offset:36864
	ds_read_b128 v[184:187], v194 offset:36864
	s_waitcnt lgkmcnt(6)
	v_mfma_f32_32x32x16_bf16 v[82:97], v[134:137], v[148:151], v[82:97]
	ds_read_b128 v[188:191], v194 offset:40960
	ds_read_b128 v[222:225], v194 offset:45056
	v_mfma_f32_32x32x16_bf16 v[66:81], v[134:137], v[152:155], v[66:81]
	s_waitcnt lgkmcnt(7)
	v_mfma_f32_32x32x16_bf16 v[50:65], v[138:141], v[148:151], v[50:65]
	v_mfma_f32_32x32x16_bf16 v[34:49], v[138:141], v[152:155], v[34:49]
	s_waitcnt lgkmcnt(6)
	v_mfma_f32_32x32x16_bf16 v[18:33], v[144:147], v[148:151], v[18:33]
	v_mfma_f32_32x32x16_bf16 v[2:17], v[144:147], v[152:155], v[2:17]
	s_waitcnt vmcnt(0) lgkmcnt(0)
	s_barrier
	v_mfma_f32_32x32x16_bf16 v[114:129], v[180:183], v[226:229], v[114:129]
	ds_read_b128 v[130:133], v156 offset:0
	s_add_u32 m0, s15, 0x8020
	s_add_u32 s10, s1, s2
	s_addc_u32 s11, s7, s3
	global_load_lds_dwordx4 v142, s[10:11]
	v_mfma_f32_32x32x16_bf16 v[98:113], v[180:183], v[230:233], v[98:113]
	ds_read_b128 v[148:151], v195 offset:0
	s_add_u32 m0, s15, 0xa020
	s_add_u32 s10, s10, 0x20000
	s_addc_u32 s11, s11, 0
	global_load_lds_dwordx4 v142, s[10:11]
	v_mfma_f32_32x32x16_bf16 v[82:97], v[184:187], v[226:229], v[82:97]
	ds_read_b128 v[152:155], v195 offset:4096
	s_add_u32 m0, s15, 0xc020
	s_add_u32 s10, s10, 0x20000
	s_addc_u32 s11, s11, 0
	global_load_lds_dwordx4 v142, s[10:11]
	v_mfma_f32_32x32x16_bf16 v[66:81], v[184:187], v[230:233], v[66:81]
	ds_read_b128 v[134:137], v156 offset:4096
	s_add_u32 m0, s15, 0xe020
	s_add_u32 s10, s10, 0x20000
	s_addc_u32 s11, s11, 0
	global_load_lds_dwordx4 v142, s[10:11]
	v_mfma_f32_32x32x16_bf16 v[50:65], v[188:191], v[226:229], v[50:65]
	ds_read_b128 v[138:141], v156 offset:8192
	s_add_u32 m0, s15, 0x18020
	s_add_u32 s10, s8, s2
	s_addc_u32 s11, s9, s3
	global_load_lds_dwordx4 v142, s[10:11]
	v_mfma_f32_32x32x16_bf16 v[34:49], v[188:191], v[230:233], v[34:49]
	ds_read_b128 v[144:147], v156 offset:12288
	v_mfma_f32_32x32x16_bf16 v[18:33], v[222:225], v[226:229], v[18:33]
	v_mfma_f32_32x32x16_bf16 v[2:17], v[222:225], v[230:233], v[2:17]
	s_sub_u32 s5, s5, 1
	s_cmp_lg_u32 s5, 0
	s_cbranch_scc1 .Lg1122_loop
	s_waitcnt lgkmcnt(4)
	v_mfma_f32_32x32x16_bf16 v[114:129], v[130:133], v[148:151], v[114:129]
	ds_read_b128 v[180:183], v157 offset:0
	s_waitcnt lgkmcnt(4)
	v_mfma_f32_32x32x16_bf16 v[98:113], v[130:133], v[152:155], v[98:113]
	ds_read_b128 v[226:229], v200 offset:0
	s_add_u32 m0, s15, 0x1a020
	s_add_u32 s10, s10, 0x20000
	s_addc_u32 s11, s11, 0
	global_load_lds_dwordx4 v142, s[10:11]
	s_waitcnt lgkmcnt(4)
	v_mfma_f32_32x32x16_bf16 v[82:97], v[134:137], v[148:151], v[82:97]
	ds_read_b128 v[230:233], v200 offset:4096
	v_mfma_f32_32x32x16_bf16 v[66:81], v[134:137], v[152:155], v[66:81]
	ds_read_b128 v[184:187], v157 offset:4096
	s_add_u32 m0, s15, 0x1c020
	s_add_u32 s10, s10, 0x20000
	s_addc_u32 s11, s11, 0
	global_load_lds_dwordx4 v142, s[10:11]
	s_waitcnt lgkmcnt(5)
	v_mfma_f32_32x32x16_bf16 v[50:65], v[138:141], v[148:151], v[50:65]
	ds_read_b128 v[188:191], v157 offset:8192
	v_mfma_f32_32x32x16_bf16 v[34:49], v[138:141], v[152:155], v[34:49]
	ds_read_b128 v[222:225], v157 offset:12288
	s_add_u32 m0, s15, 0x1e020
	s_add_u32 s10, s10, 0x20000
	s_addc_u32 s11, s11, 0
	global_load_lds_dwordx4 v142, s[10:11]
	s_add_u32 s2, s2, 0x80
	s_addc_u32 s3, s3, 0
	s_waitcnt lgkmcnt(6)
	v_mfma_f32_32x32x16_bf16 v[18:33], v[144:147], v[148:151], v[18:33]
	v_mfma_f32_32x32x16_bf16 v[2:17], v[144:147], v[152:155], v[2:17]
	s_waitcnt lgkmcnt(4)
	v_mfma_f32_32x32x16_bf16 v[114:129], v[180:183], v[226:229], v[114:129]
	ds_read_b128 v[130:133], v193 offset:0
	s_waitcnt lgkmcnt(4)
	v_mfma_f32_32x32x16_bf16 v[98:113], v[180:183], v[230:233], v[98:113]
	ds_read_b128 v[148:151], v201 offset:0
	s_waitcnt lgkmcnt(4)
	v_mfma_f32_32x32x16_bf16 v[82:97], v[184:187], v[226:229], v[82:97]
	ds_read_b128 v[152:155], v201 offset:4096
	v_mfma_f32_32x32x16_bf16 v[66:81], v[184:187], v[230:233], v[66:81]
	ds_read_b128 v[134:137], v193 offset:4096
	s_waitcnt lgkmcnt(5)
	v_mfma_f32_32x32x16_bf16 v[50:65], v[188:191], v[226:229], v[50:65]
	ds_read_b128 v[138:141], v193 offset:8192
	v_mfma_f32_32x32x16_bf16 v[34:49], v[188:191], v[230:233], v[34:49]
	ds_read_b128 v[144:147], v193 offset:12288
	s_waitcnt lgkmcnt(6)
	v_mfma_f32_32x32x16_bf16 v[18:33], v[222:225], v[226:229], v[18:33]
	v_mfma_f32_32x32x16_bf16 v[2:17], v[222:225], v[230:233], v[2:17]
	s_waitcnt lgkmcnt(4)
	v_mfma_f32_32x32x16_bf16 v[114:129], v[130:133], v[148:151], v[114:129]
	ds_read_b128 v[180:183], v194 offset:0
	ds_read_b128 v[226:229], v202 offset:0
	s_waitcnt lgkmcnt(5)
	v_mfma_f32_32x32x16_bf16 v[98:113], v[130:133], v[152:155], v[98:113]
	ds_read_b128 v[230:233], v202 offset:4096
	ds_read_b128 v[184:187], v194 offset:4096
	s_waitcnt lgkmcnt(6)
	v_mfma_f32_32x32x16_bf16 v[82:97], v[134:137], v[148:151], v[82:97]
	ds_read_b128 v[188:191], v194 offset:8192
	ds_read_b128 v[222:225], v194 offset:12288
	v_mfma_f32_32x32x16_bf16 v[66:81], v[134:137], v[152:155], v[66:81]
	s_waitcnt lgkmcnt(7)
	v_mfma_f32_32x32x16_bf16 v[50:65], v[138:141], v[148:151], v[50:65]
	v_mfma_f32_32x32x16_bf16 v[34:49], v[138:141], v[152:155], v[34:49]
	s_waitcnt lgkmcnt(6)
	v_mfma_f32_32x32x16_bf16 v[18:33], v[144:147], v[148:151], v[18:33]
	v_mfma_f32_32x32x16_bf16 v[2:17], v[144:147], v[152:155], v[2:17]
	s_waitcnt vmcnt(0) lgkmcnt(0)
	s_barrier
	v_mfma_f32_32x32x16_bf16 v[114:129], v[180:183], v[226:229], v[114:129]
	ds_read_b128 v[130:133], v156 offset:32768
	v_mfma_f32_32x32x16_bf16 v[98:113], v[180:183], v[230:233], v[98:113]
	ds_read_b128 v[148:151], v195 offset:32768
	v_mfma_f32_32x32x16_bf16 v[82:97], v[184:187], v[226:229], v[82:97]
	ds_read_b128 v[152:155], v195 offset:36864
	v_mfma_f32_32x32x16_bf16 v[66:81], v[184:187], v[230:233], v[66:81]
	ds_read_b128 v[134:137], v156 offset:36864
	v_mfma_f32_32x32x16_bf16 v[50:65], v[188:191], v[226:229], v[50:65]
	ds_read_b128 v[138:141], v156 offset:40960
	v_mfma_f32_32x32x16_bf16 v[34:49], v[188:191], v[230:233], v[34:49]
	ds_read_b128 v[144:147], v156 offset:45056
	v_mfma_f32_32x32x16_bf16 v[18:33], v[222:225], v[226:229], v[18:33]
	v_mfma_f32_32x32x16_bf16 v[2:17], v[222:225], v[230:233], v[2:17]
	s_waitcnt lgkmcnt(4)
	v_mfma_f32_32x32x16_bf16 v[114:129], v[130:133], v[148:151], v[114:129]
	ds_read_b128 v[180:183], v157 offset:32768
	s_waitcnt lgkmcnt(4)
	v_mfma_f32_32x32x16_bf16 v[98:113], v[130:133], v[152:155], v[98:113]
	ds_read_b128 v[226:229], v200 offset:32768
	s_waitcnt lgkmcnt(4)
	v_mfma_f32_32x32x16_bf16 v[82:97], v[134:137], v[148:151], v[82:97]
	ds_read_b128 v[230:233], v200 offset:36864
	v_mfma_f32_32x32x16_bf16 v[66:81], v[134:137], v[152:155], v[66:81]
	ds_read_b128 v[184:187], v157 offset:36864
	s_waitcnt lgkmcnt(5)
	v_mfma_f32_32x32x16_bf16 v[50:65], v[138:141], v[148:151], v[50:65]
	ds_read_b128 v[188:191], v157 offset:40960
	v_mfma_f32_32x32x16_bf16 v[34:49], v[138:141], v[152:155], v[34:49]
	ds_read_b128 v[222:225], v157 offset:45056
	s_waitcnt lgkmcnt(6)
	v_mfma_f32_32x32x16_bf16 v[18:33], v[144:147], v[148:151], v[18:33]
	v_mfma_f32_32x32x16_bf16 v[2:17], v[144:147], v[152:155], v[2:17]
	s_waitcnt lgkmcnt(4)
	v_mfma_f32_32x32x16_bf16 v[114:129], v[180:183], v[226:229], v[114:129]
	ds_read_b128 v[130:133], v193 offset:32768
	s_waitcnt lgkmcnt(4)
	v_mfma_f32_32x32x16_bf16 v[98:113], v[180:183], v[230:233], v[98:113]
	ds_read_b128 v[148:151], v201 offset:32768
	s_waitcnt lgkmcnt(4)
	v_mfma_f32_32x32x16_bf16 v[82:97], v[184:187], v[226:229], v[82:97]
	ds_read_b128 v[152:155], v201 offset:36864
	v_mfma_f32_32x32x16_bf16 v[66:81], v[184:187], v[230:233], v[66:81]
	ds_read_b128 v[134:137], v193 offset:36864
	s_waitcnt lgkmcnt(5)
	v_mfma_f32_32x32x16_bf16 v[50:65], v[188:191], v[226:229], v[50:65]
	ds_read_b128 v[138:141], v193 offset:40960
	v_mfma_f32_32x32x16_bf16 v[34:49], v[188:191], v[230:233], v[34:49]
	ds_read_b128 v[144:147], v193 offset:45056
	s_waitcnt lgkmcnt(6)
	v_mfma_f32_32x32x16_bf16 v[18:33], v[222:225], v[226:229], v[18:33]
	v_mfma_f32_32x32x16_bf16 v[2:17], v[222:225], v[230:233], v[2:17]
	s_waitcnt lgkmcnt(4)
	v_mfma_f32_32x32x16_bf16 v[114:129], v[130:133], v[148:151], v[114:129]
	ds_read_b128 v[180:183], v194 offset:32768
	ds_read_b128 v[226:229], v202 offset:32768
	s_waitcnt lgkmcnt(5)
	v_mfma_f32_32x32x16_bf16 v[98:113], v[130:133], v[152:155], v[98:113]
	ds_read_b128 v[230:233], v202 offset:36864
	ds_read_b128 v[184:187], v194 offset:36864
	s_waitcnt lgkmcnt(6)
	v_mfma_f32_32x32x16_bf16 v[82:97], v[134:137], v[148:151], v[82:97]
	ds_read_b128 v[188:191], v194 offset:40960
	ds_read_b128 v[222:225], v194 offset:45056
	v_mfma_f32_32x32x16_bf16 v[66:81], v[134:137], v[152:155], v[66:81]
	s_waitcnt lgkmcnt(7)
	v_mfma_f32_32x32x16_bf16 v[50:65], v[138:141], v[148:151], v[50:65]
	v_mfma_f32_32x32x16_bf16 v[34:49], v[138:141], v[152:155], v[34:49]
	s_waitcnt lgkmcnt(6)
	v_mfma_f32_32x32x16_bf16 v[18:33], v[144:147], v[148:151], v[18:33]
	v_mfma_f32_32x32x16_bf16 v[2:17], v[144:147], v[152:155], v[2:17]
	s_waitcnt vmcnt(0) lgkmcnt(0)
	s_barrier
	v_mfma_f32_32x32x16_bf16 v[114:129], v[180:183], v[226:229], v[114:129]
	v_mfma_f32_32x32x16_bf16 v[98:113], v[180:183], v[230:233], v[98:113]
	v_mfma_f32_32x32x16_bf16 v[82:97], v[184:187], v[226:229], v[82:97]
	v_mfma_f32_32x32x16_bf16 v[66:81], v[184:187], v[230:233], v[66:81]
	v_mfma_f32_32x32x16_bf16 v[50:65], v[188:191], v[226:229], v[50:65]
	v_mfma_f32_32x32x16_bf16 v[34:49], v[188:191], v[230:233], v[34:49]
	v_mfma_f32_32x32x16_bf16 v[18:33], v[222:225], v[226:229], v[18:33]
	v_mfma_f32_32x32x16_bf16 v[2:17], v[222:225], v[230:233], v[2:17]
	v_add_u32_e32 v180, s0, v168
	s_and_b32 s0, s4, 0x7ffffe
	s_mov_b32 s4, 0x7e07e07f
	v_mul_hi_i32 v0, v180, s4
	v_lshrrev_b32_e32 v130, 31, v0
	v_ashrrev_i32_e32 v0, 13, v0
	s_cmp_eq_u32 s0, 12
	v_add_u32_e32 v182, v0, v130
	s_waitcnt vmcnt(0)
	s_cselect_b64 s[2:3], -1, 0
	s_cmp_lg_u32 s0, 12
	v_mul_i32_i24_e32 v0, 0x4100, v182
	v_or_b32_e32 v138, s6, v169
	s_movk_i32 s4, 0x5ff
	s_cselect_b64 s[0:1], -1, 0
	v_sub_u32_e32 v140, v180, v0
	v_mov_b32_e32 v184, v179
	v_cmp_lt_i32_e64 s[52:53], s4, v138
	s_barrier
	v_lshl_or_b32 v181, v182, 3, v171
	v_ashrrev_i32_e32 v141, 31, v140
	s_and_b64 s[10:11], s[0:1], s[52:53]
	v_and_b32_e32 v183, 63, v184
	v_and_b32_e32 v0, 31, v184
	v_bfe_u32 v133, v184, 5, 1
	s_and_saveexec_b64 s[0:1], s[10:11]
	s_xor_b64 s[8:9], exec, s[0:1]
	s_cbranch_execz .LBB0_1136
	s_add_i32 s4, s6, 0xfffff200
	v_mul_u32_u24_e32 v130, 0x90, v133
	s_mov_b64 s[0:1], -1
	s_cmp_gt_u32 s4, 0xfffff9ff
	v_lshlrev_b32_e32 v139, 2, v0
	v_lshlrev_b32_e32 v185, 2, v130
	s_cbranch_scc0 .LBB0_1134
	v_add3_u32 v0, v170, v185, v139
	ds_write_b32 v0, v114
	v_add3_u32 v0, v170, v139, v185
	v_add_u32_e32 v130, 0x100, v0
	ds_write2_b32 v130, v117, v118 offset0:44 offset1:224
	v_add_u32_e32 v130, 0x400, v0
	ds_write2_b32 v130, v119, v120 offset0:68 offset1:104
	v_add_u32_e32 v130, 0x600, v0
	ds_write2_b32 v130, v121, v122 offset0:12 offset1:192
	v_add_u32_e32 v130, 0x800, v0
	ds_write2_b32 v130, v123, v124 offset0:100 offset1:136
	v_add_u32_e32 v130, 0xa00, v0
	ds_write2_b32 v130, v125, v126 offset0:44 offset1:224
	v_add_u32_e32 v130, 0xc00, v0
	s_cmpk_lt_u32 s6, 0xa00
	ds_write2_b32 v0, v115, v116 offset0:36 offset1:72
	ds_write2_b32 v130, v127, v128 offset0:132 offset1:168
	ds_write_b32 v0, v129 offset:3888
	s_cselect_b64 s[0:1], -1, 0
	v_mov_b32_e32 v0, 0x3e38aa3b
	v_cndmask_b32_e64 v142, 1.0, v0, s[0:1]
	v_lshlrev_b32_e32 v0, 3, v184
	v_lshrrev_b32_e32 v188, 2, v183
	s_movk_i32 s4, 0x90
	v_and_b32_e32 v187, 24, v0
	v_mad_u32_u24 v147, v188, s4, v170
	s_waitcnt lgkmcnt(0)
	v_lshl_add_u32 v130, v187, 2, v147
	ds_read_b128 v[134:137], v130
	ds_read_b128 v[130:133], v130 offset:16
	v_and_b32_e32 v144, 2, v184
	v_or_b32_e32 v150, v188, v140
	s_movk_i32 s4, 0x100
	v_cmp_eq_u32_e32 vcc, 0, v144
	v_cmp_gt_i32_e64 s[4:5], s4, v150
	s_and_saveexec_b64 s[16:17], s[4:5]
	s_xor_b64 s[4:5], exec, s[16:17]
	s_cbranch_execz .LBB0_1127
	s_waitcnt lgkmcnt(1)
	v_pk_mul_f32 v[152:153], v[142:143], v[134:135] op_sel_hi:[0,1]
	v_pk_mul_f32 v[154:155], v[142:143], v[136:137] op_sel_hi:[0,1]
	s_waitcnt lgkmcnt(0)
	v_pk_mul_f32 v[156:157], v[142:143], v[130:131] op_sel_hi:[0,1]
	v_mul_f32_e32 v145, v142, v132
